# v16 + in the 8-read load segments the ds_reads are issued before the scalar m0/descriptor setup
# baseline (speedup 1.0000x reference)
.LBB0_642:
	ds_read_b128 v[148:151], v139
	ds_read_b128 v[152:155], v139 offset:1024
	ds_read_b128 v[156:159], v139 offset:2048
	ds_read_b128 v[160:163], v139 offset:3072
	ds_read_b128 v[164:167], v140
	ds_read_b128 v[168:171], v140 offset:1024
	ds_read_b128 v[172:175], v140 offset:2048
	ds_read_b128 v[176:179], v140 offset:3072
	s_add_i32 s18, s71, 0xffe80080
	s_cmp_eq_u32 s58, s73
	s_cselect_b32 s74, s69, s18
	s_cselect_b32 s76, s70, s72
	s_or_b32 s75, s74, 0x80
	s_add_i32 s18, s71, 0xfff80000
	s_mov_b32 m0, s59
	ds_read_b128 v[180:183], v141
	ds_read_b128 v[184:187], v141 offset:1024
	ds_read_b128 v[188:191], v141 offset:2048
	ds_read_b128 v[192:195], v141 offset:3072
	ds_read_b128 v[196:199], v141 offset:4096
	ds_read_b128 v[200:203], v141 offset:5120
	ds_read_b128 v[204:207], v141 offset:6144
	ds_read_b128 v[208:211], v141 offset:7168
	buffer_load_dwordx4 v137, s[12:15], s18 offen lds
	s_mov_b32 m0, s60
	s_nop 0
	buffer_load_dwordx4 v137, s[12:15], s71 offen lds
	s_waitcnt vmcnt(8) lgkmcnt(0)
	s_setprio 1
	v_mfma_f32_16x16x32_bf16 v[118:121], v[148:151], v[180:183], v[118:121]
	s_barrier
	v_mfma_f32_16x16x32_bf16 v[118:121], v[152:155], v[184:187], v[118:121]
	v_mfma_f32_16x16x32_bf16 v[114:117], v[156:159], v[180:183], v[114:117]
	v_mfma_f32_16x16x32_bf16 v[114:117], v[160:163], v[184:187], v[114:117]
	v_mfma_f32_16x16x32_bf16 v[126:129], v[164:167], v[180:183], v[126:129]
	v_mfma_f32_16x16x32_bf16 v[126:129], v[168:171], v[184:187], v[126:129]
	v_mfma_f32_16x16x32_bf16 v[122:125], v[172:175], v[180:183], v[122:125]
	v_mfma_f32_16x16x32_bf16 v[122:125], v[176:179], v[184:187], v[122:125]
	v_mfma_f32_16x16x32_bf16 v[98:101], v[172:175], v[188:191], v[98:101]
	v_mfma_f32_16x16x32_bf16 v[98:101], v[176:179], v[192:195], v[98:101]
	v_mfma_f32_16x16x32_bf16 v[106:109], v[164:167], v[188:191], v[106:109]
	v_mfma_f32_16x16x32_bf16 v[106:109], v[168:171], v[192:195], v[106:109]
	v_mfma_f32_16x16x32_bf16 v[102:105], v[156:159], v[188:191], v[102:105]
	v_mfma_f32_16x16x32_bf16 v[102:105], v[160:163], v[192:195], v[102:105]
	v_mfma_f32_16x16x32_bf16 v[110:113], v[148:151], v[188:191], v[110:113]
	v_mfma_f32_16x16x32_bf16 v[110:113], v[152:155], v[192:195], v[110:113]
	v_mfma_f32_16x16x32_bf16 v[94:97], v[148:151], v[196:199], v[94:97]
	v_mfma_f32_16x16x32_bf16 v[94:97], v[152:155], v[200:203], v[94:97]
	v_mfma_f32_16x16x32_bf16 v[86:89], v[156:159], v[196:199], v[86:89]
	v_mfma_f32_16x16x32_bf16 v[86:89], v[160:163], v[200:203], v[86:89]
	v_mfma_f32_16x16x32_bf16 v[90:93], v[164:167], v[196:199], v[90:93]
	v_mfma_f32_16x16x32_bf16 v[90:93], v[168:171], v[200:203], v[90:93]
	v_mfma_f32_16x16x32_bf16 v[82:85], v[172:175], v[196:199], v[82:85]
	v_mfma_f32_16x16x32_bf16 v[82:85], v[176:179], v[200:203], v[82:85]
	v_mfma_f32_16x16x32_bf16 v[70:73], v[172:175], v[204:207], v[70:73]
	v_mfma_f32_16x16x32_bf16 v[70:73], v[176:179], v[208:211], v[70:73]
	v_mfma_f32_16x16x32_bf16 v[74:77], v[164:167], v[204:207], v[74:77]
	v_mfma_f32_16x16x32_bf16 v[74:77], v[168:171], v[208:211], v[74:77]
	v_mfma_f32_16x16x32_bf16 v[66:69], v[156:159], v[204:207], v[66:69]
	v_mfma_f32_16x16x32_bf16 v[66:69], v[160:163], v[208:211], v[66:69]
	v_mfma_f32_16x16x32_bf16 v[78:81], v[148:151], v[204:207], v[78:81]
	v_mfma_f32_16x16x32_bf16 v[78:81], v[152:155], v[208:211], v[78:81]
	s_setprio 0
	s_barrier
	ds_read_b128 v[180:183], v141 offset:16384
	ds_read_b128 v[184:187], v141 offset:17408
	ds_read_b128 v[188:191], v141 offset:18432
	ds_read_b128 v[192:195], v141 offset:19456
	ds_read_b128 v[196:199], v141 offset:20480
	ds_read_b128 v[200:203], v141 offset:21504
	ds_read_b128 v[204:207], v141 offset:22528
	ds_read_b128 v[208:211], v141 offset:23552
	s_mov_b32 m0, s30
	s_mov_b32 s18, s14
	s_mov_b32 s19, s15
	buffer_load_dwordx4 v138, s[16:19], s76 offen lds
	s_mov_b32 m0, s31
	s_add_i32 s77, s76, 0x80000
	buffer_load_dwordx4 v138, s[16:19], s77 offen lds
	s_mov_b32 m0, s44
	s_add_i32 s77, s76, 0x100000
	buffer_load_dwordx4 v138, s[16:19], s77 offen lds
	s_mov_b32 m0, s45
	s_add_i32 s77, s76, 0x180000
	buffer_load_dwordx4 v138, s[16:19], s77 offen lds
	s_mov_b32 m0, s27
	s_add_i32 s77, s74, 0x80000
	buffer_load_dwordx4 v137, s[12:15], s74 offen lds
	s_mov_b32 m0, s46
	s_nop 0
	buffer_load_dwordx4 v137, s[12:15], s77 offen lds
	s_waitcnt vmcnt(8) lgkmcnt(0)
	s_setprio 1
	v_mfma_f32_16x16x32_bf16 v[62:65], v[148:151], v[180:183], v[62:65]
	s_barrier
	v_mfma_f32_16x16x32_bf16 v[62:65], v[152:155], v[184:187], v[62:65]
	v_mfma_f32_16x16x32_bf16 v[54:57], v[156:159], v[180:183], v[54:57]
	v_mfma_f32_16x16x32_bf16 v[54:57], v[160:163], v[184:187], v[54:57]
	v_mfma_f32_16x16x32_bf16 v[58:61], v[164:167], v[180:183], v[58:61]
	v_mfma_f32_16x16x32_bf16 v[58:61], v[168:171], v[184:187], v[58:61]
	v_mfma_f32_16x16x32_bf16 v[50:53], v[172:175], v[180:183], v[50:53]
	v_mfma_f32_16x16x32_bf16 v[50:53], v[176:179], v[184:187], v[50:53]
	v_mfma_f32_16x16x32_bf16 v[34:37], v[172:175], v[188:191], v[34:37]
	v_mfma_f32_16x16x32_bf16 v[34:37], v[176:179], v[192:195], v[34:37]
	v_mfma_f32_16x16x32_bf16 v[42:45], v[164:167], v[188:191], v[42:45]
	v_mfma_f32_16x16x32_bf16 v[42:45], v[168:171], v[192:195], v[42:45]
	v_mfma_f32_16x16x32_bf16 v[38:41], v[156:159], v[188:191], v[38:41]
	v_mfma_f32_16x16x32_bf16 v[38:41], v[160:163], v[192:195], v[38:41]
	v_mfma_f32_16x16x32_bf16 v[46:49], v[148:151], v[188:191], v[46:49]
	v_mfma_f32_16x16x32_bf16 v[46:49], v[152:155], v[192:195], v[46:49]
	v_mfma_f32_16x16x32_bf16 v[30:33], v[148:151], v[196:199], v[30:33]
	v_mfma_f32_16x16x32_bf16 v[30:33], v[152:155], v[200:203], v[30:33]
	v_mfma_f32_16x16x32_bf16 v[22:25], v[156:159], v[196:199], v[22:25]
	v_mfma_f32_16x16x32_bf16 v[22:25], v[160:163], v[200:203], v[22:25]
	v_mfma_f32_16x16x32_bf16 v[26:29], v[164:167], v[196:199], v[26:29]
	v_mfma_f32_16x16x32_bf16 v[26:29], v[168:171], v[200:203], v[26:29]
	v_mfma_f32_16x16x32_bf16 v[18:21], v[172:175], v[196:199], v[18:21]
	v_mfma_f32_16x16x32_bf16 v[18:21], v[176:179], v[200:203], v[18:21]
	v_mfma_f32_16x16x32_bf16 v[2:5], v[172:175], v[204:207], v[2:5]
	v_mfma_f32_16x16x32_bf16 v[2:5], v[176:179], v[208:211], v[2:5]
	v_mfma_f32_16x16x32_bf16 v[10:13], v[164:167], v[204:207], v[10:13]
	v_mfma_f32_16x16x32_bf16 v[10:13], v[168:171], v[208:211], v[10:13]
	v_mfma_f32_16x16x32_bf16 v[6:9], v[156:159], v[204:207], v[6:9]
	v_mfma_f32_16x16x32_bf16 v[6:9], v[160:163], v[208:211], v[6:9]
	v_mfma_f32_16x16x32_bf16 v[14:17], v[148:151], v[204:207], v[14:17]
	v_mfma_f32_16x16x32_bf16 v[14:17], v[152:155], v[208:211], v[14:17]
	s_setprio 0
	s_barrier
	ds_read_b128 v[148:151], v142
	ds_read_b128 v[152:155], v142 offset:1024
	ds_read_b128 v[156:159], v142 offset:2048
	ds_read_b128 v[160:163], v142 offset:3072
	ds_read_b128 v[164:167], v143
	ds_read_b128 v[168:171], v143 offset:1024
	ds_read_b128 v[172:175], v143 offset:2048
	ds_read_b128 v[176:179], v143 offset:3072
	s_mov_b32 m0, s47
	s_add_i32 s77, s74, 0x100000
	ds_read_b128 v[180:183], v141 offset:32768
	ds_read_b128 v[184:187], v141 offset:33792
	ds_read_b128 v[188:191], v141 offset:34816
	ds_read_b128 v[192:195], v141 offset:35840
	ds_read_b128 v[196:199], v141 offset:36864
	ds_read_b128 v[200:203], v141 offset:37888
	ds_read_b128 v[204:207], v141 offset:38912
	ds_read_b128 v[208:211], v141 offset:39936
	buffer_load_dwordx4 v137, s[12:15], s77 offen lds
	s_mov_b32 m0, s48
	s_add_i32 s77, s74, 0x180000
	buffer_load_dwordx4 v137, s[12:15], s77 offen lds
	s_waitcnt vmcnt(8) lgkmcnt(0)
	s_setprio 1
	v_mfma_f32_16x16x32_bf16 v[118:121], v[148:151], v[180:183], v[118:121]
	s_barrier
	v_mfma_f32_16x16x32_bf16 v[118:121], v[152:155], v[184:187], v[118:121]
	v_mfma_f32_16x16x32_bf16 v[114:117], v[156:159], v[180:183], v[114:117]
	v_mfma_f32_16x16x32_bf16 v[114:117], v[160:163], v[184:187], v[114:117]
	v_mfma_f32_16x16x32_bf16 v[126:129], v[164:167], v[180:183], v[126:129]
	v_mfma_f32_16x16x32_bf16 v[126:129], v[168:171], v[184:187], v[126:129]
	v_mfma_f32_16x16x32_bf16 v[122:125], v[172:175], v[180:183], v[122:125]
	v_mfma_f32_16x16x32_bf16 v[122:125], v[176:179], v[184:187], v[122:125]
	v_mfma_f32_16x16x32_bf16 v[98:101], v[172:175], v[188:191], v[98:101]
	v_mfma_f32_16x16x32_bf16 v[98:101], v[176:179], v[192:195], v[98:101]
	v_mfma_f32_16x16x32_bf16 v[106:109], v[164:167], v[188:191], v[106:109]
	v_mfma_f32_16x16x32_bf16 v[106:109], v[168:171], v[192:195], v[106:109]
	v_mfma_f32_16x16x32_bf16 v[102:105], v[156:159], v[188:191], v[102:105]
	v_mfma_f32_16x16x32_bf16 v[102:105], v[160:163], v[192:195], v[102:105]
	v_mfma_f32_16x16x32_bf16 v[110:113], v[148:151], v[188:191], v[110:113]
	v_mfma_f32_16x16x32_bf16 v[110:113], v[152:155], v[192:195], v[110:113]
	v_mfma_f32_16x16x32_bf16 v[94:97], v[148:151], v[196:199], v[94:97]
	v_mfma_f32_16x16x32_bf16 v[94:97], v[152:155], v[200:203], v[94:97]
	v_mfma_f32_16x16x32_bf16 v[86:89], v[156:159], v[196:199], v[86:89]
	v_mfma_f32_16x16x32_bf16 v[86:89], v[160:163], v[200:203], v[86:89]
	v_mfma_f32_16x16x32_bf16 v[90:93], v[164:167], v[196:199], v[90:93]
	v_mfma_f32_16x16x32_bf16 v[90:93], v[168:171], v[200:203], v[90:93]
	v_mfma_f32_16x16x32_bf16 v[82:85], v[172:175], v[196:199], v[82:85]
	v_mfma_f32_16x16x32_bf16 v[82:85], v[176:179], v[200:203], v[82:85]
	v_mfma_f32_16x16x32_bf16 v[70:73], v[172:175], v[204:207], v[70:73]
	v_mfma_f32_16x16x32_bf16 v[70:73], v[176:179], v[208:211], v[70:73]
	v_mfma_f32_16x16x32_bf16 v[74:77], v[164:167], v[204:207], v[74:77]
	v_mfma_f32_16x16x32_bf16 v[74:77], v[168:171], v[208:211], v[74:77]
	v_mfma_f32_16x16x32_bf16 v[66:69], v[156:159], v[204:207], v[66:69]
	v_mfma_f32_16x16x32_bf16 v[66:69], v[160:163], v[208:211], v[66:69]
	v_mfma_f32_16x16x32_bf16 v[78:81], v[148:151], v[204:207], v[78:81]
	v_mfma_f32_16x16x32_bf16 v[78:81], v[152:155], v[208:211], v[78:81]
	s_setprio 0
	s_barrier
	ds_read_b128 v[180:183], v141 offset:49152
	ds_read_b128 v[184:187], v141 offset:50176
	ds_read_b128 v[188:191], v141 offset:51200
	ds_read_b128 v[192:195], v141 offset:52224
	ds_read_b128 v[196:199], v141 offset:53248
	ds_read_b128 v[200:203], v141 offset:54272
	ds_read_b128 v[204:207], v141 offset:55296
	ds_read_b128 v[208:211], v141 offset:56320
	s_mov_b32 m0, s50
	s_or_b32 s77, s76, 0x80
	buffer_load_dwordx4 v138, s[16:19], s77 offen lds
	s_add_i32 s77, s76, 0x80080
	s_mov_b32 m0, s51
	s_add_i32 s74, s74, 0x80080
	buffer_load_dwordx4 v138, s[16:19], s77 offen lds
	s_add_i32 s77, s76, 0x100080
	s_mov_b32 m0, s54
	s_add_i32 s76, s76, 0x180080
	buffer_load_dwordx4 v138, s[16:19], s77 offen lds
	s_mov_b32 m0, s55
	s_nop 0
	buffer_load_dwordx4 v138, s[16:19], s76 offen lds
	s_mov_b32 m0, s52
	s_nop 0
	buffer_load_dwordx4 v137, s[12:15], s75 offen lds
	s_mov_b32 m0, s53
	s_nop 0
	buffer_load_dwordx4 v137, s[12:15], s74 offen lds
	s_waitcnt vmcnt(8) lgkmcnt(0)
	s_setprio 1
	v_mfma_f32_16x16x32_bf16 v[62:65], v[148:151], v[180:183], v[62:65]
	s_barrier
	v_mfma_f32_16x16x32_bf16 v[62:65], v[152:155], v[184:187], v[62:65]
	v_mfma_f32_16x16x32_bf16 v[54:57], v[156:159], v[180:183], v[54:57]
	v_mfma_f32_16x16x32_bf16 v[54:57], v[160:163], v[184:187], v[54:57]
	v_mfma_f32_16x16x32_bf16 v[58:61], v[164:167], v[180:183], v[58:61]
	v_mfma_f32_16x16x32_bf16 v[58:61], v[168:171], v[184:187], v[58:61]
	v_mfma_f32_16x16x32_bf16 v[50:53], v[172:175], v[180:183], v[50:53]
	v_mfma_f32_16x16x32_bf16 v[50:53], v[176:179], v[184:187], v[50:53]
	v_mfma_f32_16x16x32_bf16 v[34:37], v[172:175], v[188:191], v[34:37]
	v_mfma_f32_16x16x32_bf16 v[34:37], v[176:179], v[192:195], v[34:37]
	v_mfma_f32_16x16x32_bf16 v[42:45], v[164:167], v[188:191], v[42:45]
	v_mfma_f32_16x16x32_bf16 v[42:45], v[168:171], v[192:195], v[42:45]
	v_mfma_f32_16x16x32_bf16 v[38:41], v[156:159], v[188:191], v[38:41]
	v_mfma_f32_16x16x32_bf16 v[38:41], v[160:163], v[192:195], v[38:41]
	v_mfma_f32_16x16x32_bf16 v[46:49], v[148:151], v[188:191], v[46:49]
	v_mfma_f32_16x16x32_bf16 v[46:49], v[152:155], v[192:195], v[46:49]
	v_mfma_f32_16x16x32_bf16 v[30:33], v[148:151], v[196:199], v[30:33]
	v_mfma_f32_16x16x32_bf16 v[30:33], v[152:155], v[200:203], v[30:33]
	v_mfma_f32_16x16x32_bf16 v[22:25], v[156:159], v[196:199], v[22:25]
	v_mfma_f32_16x16x32_bf16 v[22:25], v[160:163], v[200:203], v[22:25]
	v_mfma_f32_16x16x32_bf16 v[26:29], v[164:167], v[196:199], v[26:29]
	v_mfma_f32_16x16x32_bf16 v[26:29], v[168:171], v[200:203], v[26:29]
	v_mfma_f32_16x16x32_bf16 v[18:21], v[172:175], v[196:199], v[18:21]
	v_mfma_f32_16x16x32_bf16 v[18:21], v[176:179], v[200:203], v[18:21]
	v_mfma_f32_16x16x32_bf16 v[2:5], v[172:175], v[204:207], v[2:5]
	v_mfma_f32_16x16x32_bf16 v[2:5], v[176:179], v[208:211], v[2:5]
	v_mfma_f32_16x16x32_bf16 v[10:13], v[164:167], v[204:207], v[10:13]
	v_mfma_f32_16x16x32_bf16 v[10:13], v[168:171], v[208:211], v[10:13]
	v_mfma_f32_16x16x32_bf16 v[6:9], v[156:159], v[204:207], v[6:9]
	v_mfma_f32_16x16x32_bf16 v[6:9], v[160:163], v[208:211], v[6:9]
	v_mfma_f32_16x16x32_bf16 v[14:17], v[148:151], v[204:207], v[14:17]
	v_mfma_f32_16x16x32_bf16 v[14:17], v[152:155], v[208:211], v[14:17]
	s_setprio 0
	s_barrier
	s_add_i32 s73, s73, 2
	s_addk_i32 s71, 0x100
	s_addk_i32 s72, 0x100
	s_cmp_ge_i32 s73, s3
	s_cbranch_scc0 .LBB0_642
	s_and_b64 vcc, exec, s[42:43]
	s_cbranch_vccz .LBB0_645

.LBB0_799:
	ds_read_b128 v[134:137], v210
	ds_read_b128 v[138:141], v210 offset:1024
	ds_read_b128 v[142:145], v210 offset:2048
	ds_read_b128 v[148:151], v210 offset:3072
	ds_read_b128 v[152:155], v211
	ds_read_b128 v[156:159], v211 offset:1024
	ds_read_b128 v[160:163], v211 offset:2048
	ds_read_b128 v[164:167], v211 offset:3072
	s_add_i32 s18, s77, 0xffbf8080
	s_cmp_eq_u32 s62, s79
	s_cselect_b32 s80, s6, s18
	s_cselect_b32 s82, s7, s78
	s_or_b32 s81, s80, 0x80
	s_add_i32 s18, s77, 0xffea8000
	s_mov_b32 m0, s63
	ds_read_b128 v[168:171], v212
	ds_read_b128 v[172:175], v212 offset:1024
	ds_read_b128 v[176:179], v212 offset:2048
	ds_read_b128 v[180:183], v212 offset:3072
	ds_read_b128 v[184:187], v212 offset:4096
	ds_read_b128 v[188:191], v212 offset:5120
	ds_read_b128 v[192:195], v212 offset:6144
	ds_read_b128 v[196:199], v212 offset:7168
	buffer_load_dwordx4 v208, s[12:15], s18 offen lds
	s_mov_b32 m0, s66
	s_nop 0
	buffer_load_dwordx4 v208, s[12:15], s77 offen lds
	s_waitcnt vmcnt(8) lgkmcnt(0)
	s_setprio 1
	v_mfma_f32_16x16x32_bf16 v[126:129], v[134:137], v[168:171], v[126:129]
	s_barrier
	v_mfma_f32_16x16x32_bf16 v[126:129], v[138:141], v[172:175], v[126:129]
	v_mfma_f32_16x16x32_bf16 v[122:125], v[142:145], v[168:171], v[122:125]
	v_mfma_f32_16x16x32_bf16 v[122:125], v[148:151], v[172:175], v[122:125]
	v_mfma_f32_16x16x32_bf16 v[110:113], v[152:155], v[168:171], v[110:113]
	v_mfma_f32_16x16x32_bf16 v[110:113], v[156:159], v[172:175], v[110:113]
	v_mfma_f32_16x16x32_bf16 v[102:105], v[160:163], v[168:171], v[102:105]
	v_mfma_f32_16x16x32_bf16 v[102:105], v[164:167], v[172:175], v[102:105]
	v_mfma_f32_16x16x32_bf16 v[86:89], v[160:163], v[176:179], v[86:89]
	v_mfma_f32_16x16x32_bf16 v[86:89], v[164:167], v[180:183], v[86:89]
	v_mfma_f32_16x16x32_bf16 v[94:97], v[152:155], v[176:179], v[94:97]
	v_mfma_f32_16x16x32_bf16 v[94:97], v[156:159], v[180:183], v[94:97]
	v_mfma_f32_16x16x32_bf16 v[114:117], v[142:145], v[176:179], v[114:117]
	v_mfma_f32_16x16x32_bf16 v[114:117], v[148:151], v[180:183], v[114:117]
	v_mfma_f32_16x16x32_bf16 v[118:121], v[134:137], v[176:179], v[118:121]
	v_mfma_f32_16x16x32_bf16 v[118:121], v[138:141], v[180:183], v[118:121]
	v_mfma_f32_16x16x32_bf16 v[106:109], v[134:137], v[184:187], v[106:109]
	v_mfma_f32_16x16x32_bf16 v[106:109], v[138:141], v[188:191], v[106:109]
	v_mfma_f32_16x16x32_bf16 v[98:101], v[142:145], v[184:187], v[98:101]
	v_mfma_f32_16x16x32_bf16 v[98:101], v[148:151], v[188:191], v[98:101]
	v_mfma_f32_16x16x32_bf16 v[78:81], v[152:155], v[184:187], v[78:81]
	v_mfma_f32_16x16x32_bf16 v[78:81], v[156:159], v[188:191], v[78:81]
	v_mfma_f32_16x16x32_bf16 v[74:77], v[160:163], v[184:187], v[74:77]
	v_mfma_f32_16x16x32_bf16 v[74:77], v[164:167], v[188:191], v[74:77]
	v_mfma_f32_16x16x32_bf16 v[66:69], v[160:163], v[192:195], v[66:69]
	v_mfma_f32_16x16x32_bf16 v[66:69], v[164:167], v[196:199], v[66:69]
	v_mfma_f32_16x16x32_bf16 v[70:73], v[152:155], v[192:195], v[70:73]
	v_mfma_f32_16x16x32_bf16 v[70:73], v[156:159], v[196:199], v[70:73]
	v_mfma_f32_16x16x32_bf16 v[82:85], v[142:145], v[192:195], v[82:85]
	v_mfma_f32_16x16x32_bf16 v[82:85], v[148:151], v[196:199], v[82:85]
	v_mfma_f32_16x16x32_bf16 v[90:93], v[134:137], v[192:195], v[90:93]
	v_mfma_f32_16x16x32_bf16 v[90:93], v[138:141], v[196:199], v[90:93]
	s_setprio 0
	s_barrier
	ds_read_b128 v[168:171], v212 offset:16384
	ds_read_b128 v[172:175], v212 offset:17408
	ds_read_b128 v[176:179], v212 offset:18432
	ds_read_b128 v[180:183], v212 offset:19456
	ds_read_b128 v[184:187], v212 offset:20480
	ds_read_b128 v[188:191], v212 offset:21504
	ds_read_b128 v[192:195], v212 offset:22528
	ds_read_b128 v[196:199], v212 offset:23552
	s_mov_b32 m0, s25
	s_mov_b32 s18, s14
	s_mov_b32 s19, s15
	buffer_load_dwordx4 v209, s[16:19], s82 offen lds
	s_mov_b32 m0, s27
	s_add_i32 s83, s82, 0x158000
	buffer_load_dwordx4 v209, s[16:19], s83 offen lds
	s_mov_b32 m0, s30
	s_add_i32 s83, s82, 0x2b0000
	buffer_load_dwordx4 v209, s[16:19], s83 offen lds
	s_mov_b32 m0, s31
	s_add_i32 s83, s82, 0x408000
	buffer_load_dwordx4 v209, s[16:19], s83 offen lds
	s_mov_b32 m0, s21
	s_add_i32 s83, s80, 0x158000
	buffer_load_dwordx4 v208, s[12:15], s80 offen lds
	s_mov_b32 m0, s48
	s_nop 0
	buffer_load_dwordx4 v208, s[12:15], s83 offen lds
	s_waitcnt vmcnt(8) lgkmcnt(0)
	s_setprio 1
	v_mfma_f32_16x16x32_bf16 v[62:65], v[134:137], v[168:171], v[62:65]
	s_barrier
	v_mfma_f32_16x16x32_bf16 v[62:65], v[138:141], v[172:175], v[62:65]
	v_mfma_f32_16x16x32_bf16 v[58:61], v[142:145], v[168:171], v[58:61]
	v_mfma_f32_16x16x32_bf16 v[58:61], v[148:151], v[172:175], v[58:61]
	v_mfma_f32_16x16x32_bf16 v[46:49], v[152:155], v[168:171], v[46:49]
	v_mfma_f32_16x16x32_bf16 v[46:49], v[156:159], v[172:175], v[46:49]
	v_mfma_f32_16x16x32_bf16 v[38:41], v[160:163], v[168:171], v[38:41]
	v_mfma_f32_16x16x32_bf16 v[38:41], v[164:167], v[172:175], v[38:41]
	v_mfma_f32_16x16x32_bf16 v[22:25], v[160:163], v[176:179], v[22:25]
	v_mfma_f32_16x16x32_bf16 v[22:25], v[164:167], v[180:183], v[22:25]
	v_mfma_f32_16x16x32_bf16 v[30:33], v[152:155], v[176:179], v[30:33]
	v_mfma_f32_16x16x32_bf16 v[30:33], v[156:159], v[180:183], v[30:33]
	v_mfma_f32_16x16x32_bf16 v[50:53], v[142:145], v[176:179], v[50:53]
	v_mfma_f32_16x16x32_bf16 v[50:53], v[148:151], v[180:183], v[50:53]
	v_mfma_f32_16x16x32_bf16 v[54:57], v[134:137], v[176:179], v[54:57]
	v_mfma_f32_16x16x32_bf16 v[54:57], v[138:141], v[180:183], v[54:57]
	v_mfma_f32_16x16x32_bf16 v[42:45], v[134:137], v[184:187], v[42:45]
	v_mfma_f32_16x16x32_bf16 v[42:45], v[138:141], v[188:191], v[42:45]
	v_mfma_f32_16x16x32_bf16 v[34:37], v[142:145], v[184:187], v[34:37]
	v_mfma_f32_16x16x32_bf16 v[34:37], v[148:151], v[188:191], v[34:37]
	v_mfma_f32_16x16x32_bf16 v[14:17], v[152:155], v[184:187], v[14:17]
	v_mfma_f32_16x16x32_bf16 v[14:17], v[156:159], v[188:191], v[14:17]
	v_mfma_f32_16x16x32_bf16 v[10:13], v[160:163], v[184:187], v[10:13]
	v_mfma_f32_16x16x32_bf16 v[10:13], v[164:167], v[188:191], v[10:13]
	v_mfma_f32_16x16x32_bf16 v[2:5], v[160:163], v[192:195], v[2:5]
	v_mfma_f32_16x16x32_bf16 v[2:5], v[164:167], v[196:199], v[2:5]
	v_mfma_f32_16x16x32_bf16 v[6:9], v[152:155], v[192:195], v[6:9]
	v_mfma_f32_16x16x32_bf16 v[6:9], v[156:159], v[196:199], v[6:9]
	v_mfma_f32_16x16x32_bf16 v[18:21], v[142:145], v[192:195], v[18:21]
	v_mfma_f32_16x16x32_bf16 v[18:21], v[148:151], v[196:199], v[18:21]
	v_mfma_f32_16x16x32_bf16 v[26:29], v[134:137], v[192:195], v[26:29]
	v_mfma_f32_16x16x32_bf16 v[26:29], v[138:141], v[196:199], v[26:29]
	s_setprio 0
	s_barrier
	ds_read_b128 v[134:137], v213
	ds_read_b128 v[138:141], v213 offset:1024
	ds_read_b128 v[142:145], v213 offset:2048
	ds_read_b128 v[148:151], v213 offset:3072
	ds_read_b128 v[152:155], v214
	ds_read_b128 v[156:159], v214 offset:1024
	ds_read_b128 v[160:163], v214 offset:2048
	ds_read_b128 v[164:167], v214 offset:3072
	s_mov_b32 m0, s49
	s_add_i32 s83, s80, 0x2b0000
	ds_read_b128 v[168:171], v212 offset:32768
	ds_read_b128 v[172:175], v212 offset:33792
	ds_read_b128 v[176:179], v212 offset:34816
	ds_read_b128 v[180:183], v212 offset:35840
	ds_read_b128 v[184:187], v212 offset:36864
	ds_read_b128 v[188:191], v212 offset:37888
	ds_read_b128 v[192:195], v212 offset:38912
	ds_read_b128 v[196:199], v212 offset:39936
	buffer_load_dwordx4 v208, s[12:15], s83 offen lds
	s_mov_b32 m0, s50
	s_add_i32 s83, s80, 0x408000
	buffer_load_dwordx4 v208, s[12:15], s83 offen lds
	s_waitcnt vmcnt(8) lgkmcnt(0)
	s_setprio 1
	v_mfma_f32_16x16x32_bf16 v[126:129], v[134:137], v[168:171], v[126:129]
	s_barrier
	v_mfma_f32_16x16x32_bf16 v[126:129], v[138:141], v[172:175], v[126:129]
	v_mfma_f32_16x16x32_bf16 v[122:125], v[142:145], v[168:171], v[122:125]
	v_mfma_f32_16x16x32_bf16 v[122:125], v[148:151], v[172:175], v[122:125]
	v_mfma_f32_16x16x32_bf16 v[110:113], v[152:155], v[168:171], v[110:113]
	v_mfma_f32_16x16x32_bf16 v[110:113], v[156:159], v[172:175], v[110:113]
	v_mfma_f32_16x16x32_bf16 v[102:105], v[160:163], v[168:171], v[102:105]
	v_mfma_f32_16x16x32_bf16 v[102:105], v[164:167], v[172:175], v[102:105]
	v_mfma_f32_16x16x32_bf16 v[86:89], v[160:163], v[176:179], v[86:89]
	v_mfma_f32_16x16x32_bf16 v[86:89], v[164:167], v[180:183], v[86:89]
	v_mfma_f32_16x16x32_bf16 v[94:97], v[152:155], v[176:179], v[94:97]
	v_mfma_f32_16x16x32_bf16 v[94:97], v[156:159], v[180:183], v[94:97]
	v_mfma_f32_16x16x32_bf16 v[114:117], v[142:145], v[176:179], v[114:117]
	v_mfma_f32_16x16x32_bf16 v[114:117], v[148:151], v[180:183], v[114:117]
	v_mfma_f32_16x16x32_bf16 v[118:121], v[134:137], v[176:179], v[118:121]
	v_mfma_f32_16x16x32_bf16 v[118:121], v[138:141], v[180:183], v[118:121]
	v_mfma_f32_16x16x32_bf16 v[106:109], v[134:137], v[184:187], v[106:109]
	v_mfma_f32_16x16x32_bf16 v[106:109], v[138:141], v[188:191], v[106:109]
	v_mfma_f32_16x16x32_bf16 v[98:101], v[142:145], v[184:187], v[98:101]
	v_mfma_f32_16x16x32_bf16 v[98:101], v[148:151], v[188:191], v[98:101]
	v_mfma_f32_16x16x32_bf16 v[78:81], v[152:155], v[184:187], v[78:81]
	v_mfma_f32_16x16x32_bf16 v[78:81], v[156:159], v[188:191], v[78:81]
	v_mfma_f32_16x16x32_bf16 v[74:77], v[160:163], v[184:187], v[74:77]
	v_mfma_f32_16x16x32_bf16 v[74:77], v[164:167], v[188:191], v[74:77]
	v_mfma_f32_16x16x32_bf16 v[66:69], v[160:163], v[192:195], v[66:69]
	v_mfma_f32_16x16x32_bf16 v[66:69], v[164:167], v[196:199], v[66:69]
	v_mfma_f32_16x16x32_bf16 v[70:73], v[152:155], v[192:195], v[70:73]
	v_mfma_f32_16x16x32_bf16 v[70:73], v[156:159], v[196:199], v[70:73]
	v_mfma_f32_16x16x32_bf16 v[82:85], v[142:145], v[192:195], v[82:85]
	v_mfma_f32_16x16x32_bf16 v[82:85], v[148:151], v[196:199], v[82:85]
	v_mfma_f32_16x16x32_bf16 v[90:93], v[134:137], v[192:195], v[90:93]
	v_mfma_f32_16x16x32_bf16 v[90:93], v[138:141], v[196:199], v[90:93]
	s_setprio 0
	s_barrier
	ds_read_b128 v[168:171], v212 offset:49152
	ds_read_b128 v[172:175], v212 offset:50176
	ds_read_b128 v[176:179], v212 offset:51200
	ds_read_b128 v[180:183], v212 offset:52224
	ds_read_b128 v[184:187], v212 offset:53248
	ds_read_b128 v[188:191], v212 offset:54272
	ds_read_b128 v[192:195], v212 offset:55296
	ds_read_b128 v[196:199], v212 offset:56320
	s_mov_b32 m0, s54
	s_or_b32 s83, s82, 0x80
	buffer_load_dwordx4 v209, s[16:19], s83 offen lds
	s_add_i32 s83, s82, 0x158080
	s_mov_b32 m0, s55
	s_add_i32 s80, s80, 0x158080
	buffer_load_dwordx4 v209, s[16:19], s83 offen lds
	s_add_i32 s83, s82, 0x2b0080
	s_mov_b32 m0, s58
	s_add_i32 s82, s82, 0x408080
	buffer_load_dwordx4 v209, s[16:19], s83 offen lds
	s_mov_b32 m0, s59
	s_nop 0
	buffer_load_dwordx4 v209, s[16:19], s82 offen lds
	s_mov_b32 m0, s56
	s_nop 0
	buffer_load_dwordx4 v208, s[12:15], s81 offen lds
	s_mov_b32 m0, s57
	s_nop 0
	buffer_load_dwordx4 v208, s[12:15], s80 offen lds
	s_waitcnt vmcnt(8) lgkmcnt(0)
	s_setprio 1
	v_mfma_f32_16x16x32_bf16 v[62:65], v[134:137], v[168:171], v[62:65]
	s_barrier
	v_mfma_f32_16x16x32_bf16 v[62:65], v[138:141], v[172:175], v[62:65]
	v_mfma_f32_16x16x32_bf16 v[58:61], v[142:145], v[168:171], v[58:61]
	v_mfma_f32_16x16x32_bf16 v[58:61], v[148:151], v[172:175], v[58:61]
	v_mfma_f32_16x16x32_bf16 v[46:49], v[152:155], v[168:171], v[46:49]
	v_mfma_f32_16x16x32_bf16 v[46:49], v[156:159], v[172:175], v[46:49]
	v_mfma_f32_16x16x32_bf16 v[38:41], v[160:163], v[168:171], v[38:41]
	v_mfma_f32_16x16x32_bf16 v[38:41], v[164:167], v[172:175], v[38:41]
	v_mfma_f32_16x16x32_bf16 v[22:25], v[160:163], v[176:179], v[22:25]
	v_mfma_f32_16x16x32_bf16 v[22:25], v[164:167], v[180:183], v[22:25]
	v_mfma_f32_16x16x32_bf16 v[30:33], v[152:155], v[176:179], v[30:33]
	v_mfma_f32_16x16x32_bf16 v[30:33], v[156:159], v[180:183], v[30:33]
	v_mfma_f32_16x16x32_bf16 v[50:53], v[142:145], v[176:179], v[50:53]
	v_mfma_f32_16x16x32_bf16 v[50:53], v[148:151], v[180:183], v[50:53]
	v_mfma_f32_16x16x32_bf16 v[54:57], v[134:137], v[176:179], v[54:57]
	v_mfma_f32_16x16x32_bf16 v[54:57], v[138:141], v[180:183], v[54:57]
	v_mfma_f32_16x16x32_bf16 v[42:45], v[134:137], v[184:187], v[42:45]
	v_mfma_f32_16x16x32_bf16 v[42:45], v[138:141], v[188:191], v[42:45]
	v_mfma_f32_16x16x32_bf16 v[34:37], v[142:145], v[184:187], v[34:37]
	v_mfma_f32_16x16x32_bf16 v[34:37], v[148:151], v[188:191], v[34:37]
	v_mfma_f32_16x16x32_bf16 v[14:17], v[152:155], v[184:187], v[14:17]
	v_mfma_f32_16x16x32_bf16 v[14:17], v[156:159], v[188:191], v[14:17]
	v_mfma_f32_16x16x32_bf16 v[10:13], v[160:163], v[184:187], v[10:13]
	v_mfma_f32_16x16x32_bf16 v[10:13], v[164:167], v[188:191], v[10:13]
	v_mfma_f32_16x16x32_bf16 v[2:5], v[160:163], v[192:195], v[2:5]
	v_mfma_f32_16x16x32_bf16 v[2:5], v[164:167], v[196:199], v[2:5]
	v_mfma_f32_16x16x32_bf16 v[6:9], v[152:155], v[192:195], v[6:9]
	v_mfma_f32_16x16x32_bf16 v[6:9], v[156:159], v[196:199], v[6:9]
	v_mfma_f32_16x16x32_bf16 v[18:21], v[142:145], v[192:195], v[18:21]
	v_mfma_f32_16x16x32_bf16 v[18:21], v[148:151], v[196:199], v[18:21]
	v_mfma_f32_16x16x32_bf16 v[26:29], v[134:137], v[192:195], v[26:29]
	v_mfma_f32_16x16x32_bf16 v[26:29], v[138:141], v[196:199], v[26:29]
	s_setprio 0
	s_barrier
	s_add_i32 s79, s79, 2
	s_addk_i32 s77, 0x100
	s_addk_i32 s78, 0x100
	s_cmp_ge_i32 s79, s3
	s_cbranch_scc0 .LBB0_799
	v_pk_mul_f32 v[184:185], v[128:129], 0.5 op_sel_hi:[1,0]
	v_pk_mul_f32 v[186:187], v[126:127], 0.5 op_sel_hi:[1,0]
	v_pk_mul_f32 v[188:189], v[124:125], 0.5 op_sel_hi:[1,0]
	v_pk_mul_f32 v[190:191], v[122:123], 0.5 op_sel_hi:[1,0]
	v_pk_mul_f32 v[198:199], v[112:113], 0.5 op_sel_hi:[1,0]
	v_pk_mul_f32 v[196:197], v[110:111], 0.5 op_sel_hi:[1,0]
	v_pk_mul_f32 v[194:195], v[104:105], 0.5 op_sel_hi:[1,0]
	v_pk_mul_f32 v[192:193], v[102:103], 0.5 op_sel_hi:[1,0]
	v_pk_mul_f32 v[182:183], v[120:121], 0.5 op_sel_hi:[1,0]
	v_pk_mul_f32 v[180:181], v[118:119], 0.5 op_sel_hi:[1,0]
	v_pk_mul_f32 v[178:179], v[116:117], 0.5 op_sel_hi:[1,0]
	v_pk_mul_f32 v[176:177], v[114:115], 0.5 op_sel_hi:[1,0]
	v_pk_mul_f32 v[172:173], v[96:97], 0.5 op_sel_hi:[1,0]
	v_pk_mul_f32 v[170:171], v[94:95], 0.5 op_sel_hi:[1,0]
	v_pk_mul_f32 v[168:169], v[88:89], 0.5 op_sel_hi:[1,0]
	v_pk_mul_f32 v[166:167], v[86:87], 0.5 op_sel_hi:[1,0]
	v_pk_mul_f32 v[164:165], v[108:109], 0.5 op_sel_hi:[1,0]
	v_pk_mul_f32 v[162:163], v[106:107], 0.5 op_sel_hi:[1,0]
	v_pk_mul_f32 v[160:161], v[100:101], 0.5 op_sel_hi:[1,0]
	v_pk_mul_f32 v[158:159], v[98:99], 0.5 op_sel_hi:[1,0]
	v_pk_mul_f32 v[156:157], v[80:81], 0.5 op_sel_hi:[1,0]
	v_pk_mul_f32 v[154:155], v[78:79], 0.5 op_sel_hi:[1,0]
	v_pk_mul_f32 v[152:153], v[76:77], 0.5 op_sel_hi:[1,0]
	v_pk_mul_f32 v[150:151], v[74:75], 0.5 op_sel_hi:[1,0]
	v_pk_mul_f32 v[144:145], v[92:93], 0.5 op_sel_hi:[1,0]
	v_pk_mul_f32 v[142:143], v[90:91], 0.5 op_sel_hi:[1,0]
	v_pk_mul_f32 v[140:141], v[84:85], 0.5 op_sel_hi:[1,0]
	v_pk_mul_f32 v[138:139], v[82:83], 0.5 op_sel_hi:[1,0]
	v_pk_mul_f32 v[136:137], v[72:73], 0.5 op_sel_hi:[1,0]
	v_pk_mul_f32 v[134:135], v[70:71], 0.5 op_sel_hi:[1,0]
	v_pk_mul_f32 v[128:129], v[68:69], 0.5 op_sel_hi:[1,0]
	v_pk_mul_f32 v[126:127], v[66:67], 0.5 op_sel_hi:[1,0]
	v_pk_mul_f32 v[122:123], v[64:65], 0.5 op_sel_hi:[1,0]
	v_pk_mul_f32 v[120:121], v[62:63], 0.5 op_sel_hi:[1,0]
	v_pk_mul_f32 v[118:119], v[60:61], 0.5 op_sel_hi:[1,0]
	v_pk_mul_f32 v[116:117], v[58:59], 0.5 op_sel_hi:[1,0]
	v_pk_mul_f32 v[112:113], v[48:49], 0.5 op_sel_hi:[1,0]
	v_pk_mul_f32 v[110:111], v[46:47], 0.5 op_sel_hi:[1,0]
	v_pk_mul_f32 v[108:109], v[40:41], 0.5 op_sel_hi:[1,0]
	v_pk_mul_f32 v[106:107], v[38:39], 0.5 op_sel_hi:[1,0]
	v_pk_mul_f32 v[104:105], v[56:57], 0.5 op_sel_hi:[1,0]
	v_pk_mul_f32 v[102:103], v[54:55], 0.5 op_sel_hi:[1,0]
	v_pk_mul_f32 v[100:101], v[52:53], 0.5 op_sel_hi:[1,0]
	v_pk_mul_f32 v[98:99], v[50:51], 0.5 op_sel_hi:[1,0]
	v_pk_mul_f32 v[96:97], v[32:33], 0.5 op_sel_hi:[1,0]
	v_pk_mul_f32 v[94:95], v[30:31], 0.5 op_sel_hi:[1,0]
	v_pk_mul_f32 v[92:93], v[24:25], 0.5 op_sel_hi:[1,0]
	v_pk_mul_f32 v[90:91], v[22:23], 0.5 op_sel_hi:[1,0]
	v_pk_mul_f32 v[88:89], v[44:45], 0.5 op_sel_hi:[1,0]
	v_pk_mul_f32 v[86:87], v[42:43], 0.5 op_sel_hi:[1,0]
	v_pk_mul_f32 v[84:85], v[36:37], 0.5 op_sel_hi:[1,0]
	v_pk_mul_f32 v[82:83], v[34:35], 0.5 op_sel_hi:[1,0]
	v_pk_mul_f32 v[80:81], v[16:17], 0.5 op_sel_hi:[1,0]
	v_pk_mul_f32 v[78:79], v[14:15], 0.5 op_sel_hi:[1,0]
	v_pk_mul_f32 v[76:77], v[12:13], 0.5 op_sel_hi:[1,0]
	v_pk_mul_f32 v[74:75], v[10:11], 0.5 op_sel_hi:[1,0]
	v_pk_mul_f32 v[72:73], v[28:29], 0.5 op_sel_hi:[1,0]
	v_pk_mul_f32 v[70:71], v[26:27], 0.5 op_sel_hi:[1,0]
	v_pk_mul_f32 v[68:69], v[20:21], 0.5 op_sel_hi:[1,0]
	v_pk_mul_f32 v[66:67], v[18:19], 0.5 op_sel_hi:[1,0]
	v_pk_mul_f32 v[64:65], v[8:9], 0.5 op_sel_hi:[1,0]
	v_pk_mul_f32 v[62:63], v[6:7], 0.5 op_sel_hi:[1,0]
	v_pk_mul_f32 v[60:61], v[4:5], 0.5 op_sel_hi:[1,0]
	v_pk_mul_f32 v[58:59], v[2:3], 0.5 op_sel_hi:[1,0]
	s_and_b64 vcc, exec, s[38:39]
	s_cbranch_vccz .LBB0_802

.LBB0_892:
	ds_read_b128 v[130:133], v172
	ds_read_b128 v[134:137], v172 offset:1024
	ds_read_b128 v[148:151], v172 offset:2048
	ds_read_b128 v[152:155], v172 offset:3072
	ds_read_b128 v[156:159], v173
	ds_read_b128 v[160:163], v173 offset:1024
	ds_read_b128 v[164:167], v173 offset:2048
	ds_read_b128 v[180:183], v173 offset:3072
	s_add_i32 s18, s8, 0xffe80080
	s_cmp_eq_u32 s77, s52
	s_cselect_b32 s53, s6, s18
	s_cselect_b32 s58, s7, s9
	s_or_b32 s57, s53, 0x80
	s_add_i32 s18, s8, 0xfff80000
	s_mov_b32 m0, s78
	ds_read_b128 v[184:187], v174
	ds_read_b128 v[188:191], v174 offset:1024
	ds_read_b128 v[192:195], v174 offset:2048
	ds_read_b128 v[196:199], v174 offset:3072
	ds_read_b128 v[200:203], v174 offset:4096
	ds_read_b128 v[204:207], v174 offset:5120
	ds_read_b128 v[208:211], v174 offset:6144
	ds_read_b128 v[212:215], v174 offset:7168
	buffer_load_dwordx4 v170, s[12:15], s18 offen lds
	s_mov_b32 m0, s79
	s_nop 0
	buffer_load_dwordx4 v170, s[12:15], s8 offen lds
	s_waitcnt vmcnt(8) lgkmcnt(0)
	s_setprio 1
	v_mfma_f32_16x16x32_bf16 v[126:129], v[130:133], v[184:187], v[126:129]
	s_barrier
	v_mfma_f32_16x16x32_bf16 v[126:129], v[134:137], v[188:191], v[126:129]
	v_mfma_f32_16x16x32_bf16 v[118:121], v[148:151], v[184:187], v[118:121]
	v_mfma_f32_16x16x32_bf16 v[118:121], v[152:155], v[188:191], v[118:121]
	v_mfma_f32_16x16x32_bf16 v[122:125], v[156:159], v[184:187], v[122:125]
	v_mfma_f32_16x16x32_bf16 v[122:125], v[160:163], v[188:191], v[122:125]
	v_mfma_f32_16x16x32_bf16 v[114:117], v[164:167], v[184:187], v[114:117]
	v_mfma_f32_16x16x32_bf16 v[114:117], v[180:183], v[188:191], v[114:117]
	v_mfma_f32_16x16x32_bf16 v[98:101], v[164:167], v[192:195], v[98:101]
	v_mfma_f32_16x16x32_bf16 v[98:101], v[180:183], v[196:199], v[98:101]
	v_mfma_f32_16x16x32_bf16 v[106:109], v[156:159], v[192:195], v[106:109]
	v_mfma_f32_16x16x32_bf16 v[106:109], v[160:163], v[196:199], v[106:109]
	v_mfma_f32_16x16x32_bf16 v[102:105], v[148:151], v[192:195], v[102:105]
	v_mfma_f32_16x16x32_bf16 v[102:105], v[152:155], v[196:199], v[102:105]
	v_mfma_f32_16x16x32_bf16 v[110:113], v[130:133], v[192:195], v[110:113]
	v_mfma_f32_16x16x32_bf16 v[110:113], v[134:137], v[196:199], v[110:113]
	v_mfma_f32_16x16x32_bf16 v[94:97], v[130:133], v[200:203], v[94:97]
	v_mfma_f32_16x16x32_bf16 v[94:97], v[134:137], v[204:207], v[94:97]
	v_mfma_f32_16x16x32_bf16 v[90:93], v[148:151], v[200:203], v[90:93]
	v_mfma_f32_16x16x32_bf16 v[90:93], v[152:155], v[204:207], v[90:93]
	v_mfma_f32_16x16x32_bf16 v[86:89], v[156:159], v[200:203], v[86:89]
	v_mfma_f32_16x16x32_bf16 v[86:89], v[160:163], v[204:207], v[86:89]
	v_mfma_f32_16x16x32_bf16 v[82:85], v[164:167], v[200:203], v[82:85]
	v_mfma_f32_16x16x32_bf16 v[82:85], v[180:183], v[204:207], v[82:85]
	v_mfma_f32_16x16x32_bf16 v[66:69], v[164:167], v[208:211], v[66:69]
	v_mfma_f32_16x16x32_bf16 v[66:69], v[180:183], v[212:215], v[66:69]
	v_mfma_f32_16x16x32_bf16 v[74:77], v[156:159], v[208:211], v[74:77]
	v_mfma_f32_16x16x32_bf16 v[74:77], v[160:163], v[212:215], v[74:77]
	v_mfma_f32_16x16x32_bf16 v[70:73], v[148:151], v[208:211], v[70:73]
	v_mfma_f32_16x16x32_bf16 v[70:73], v[152:155], v[212:215], v[70:73]
	v_mfma_f32_16x16x32_bf16 v[78:81], v[130:133], v[208:211], v[78:81]
	v_mfma_f32_16x16x32_bf16 v[78:81], v[134:137], v[212:215], v[78:81]
	s_setprio 0
	s_barrier
	ds_read_b128 v[184:187], v174 offset:16384
	ds_read_b128 v[188:191], v174 offset:17408
	ds_read_b128 v[192:195], v174 offset:18432
	ds_read_b128 v[196:199], v174 offset:19456
	ds_read_b128 v[200:203], v174 offset:20480
	ds_read_b128 v[204:207], v174 offset:21504
	ds_read_b128 v[208:211], v174 offset:22528
	ds_read_b128 v[212:215], v174 offset:23552
	s_mov_b32 m0, s27
	s_mov_b32 s18, s14
	s_mov_b32 s19, s15
	buffer_load_dwordx4 v171, s[16:19], s58 offen lds
	s_mov_b32 m0, s60
	s_add_i32 s59, s58, 0x80000
	buffer_load_dwordx4 v171, s[16:19], s59 offen lds
	s_mov_b32 m0, s61
	s_add_i32 s59, s58, 0x100000
	buffer_load_dwordx4 v171, s[16:19], s59 offen lds
	s_mov_b32 m0, s62
	s_add_i32 s59, s58, 0x180000
	buffer_load_dwordx4 v171, s[16:19], s59 offen lds
	s_mov_b32 m0, s25
	s_add_i32 s59, s53, 0x80000
	buffer_load_dwordx4 v170, s[12:15], s53 offen lds
	s_mov_b32 m0, s63
	s_nop 0
	buffer_load_dwordx4 v170, s[12:15], s59 offen lds
	s_waitcnt vmcnt(8) lgkmcnt(0)
	s_setprio 1
	v_mfma_f32_16x16x32_bf16 v[62:65], v[130:133], v[184:187], v[62:65]
	s_barrier
	v_mfma_f32_16x16x32_bf16 v[62:65], v[134:137], v[188:191], v[62:65]
	v_mfma_f32_16x16x32_bf16 v[54:57], v[148:151], v[184:187], v[54:57]
	v_mfma_f32_16x16x32_bf16 v[54:57], v[152:155], v[188:191], v[54:57]
	v_mfma_f32_16x16x32_bf16 v[58:61], v[156:159], v[184:187], v[58:61]
	v_mfma_f32_16x16x32_bf16 v[58:61], v[160:163], v[188:191], v[58:61]
	v_mfma_f32_16x16x32_bf16 v[50:53], v[164:167], v[184:187], v[50:53]
	v_mfma_f32_16x16x32_bf16 v[50:53], v[180:183], v[188:191], v[50:53]
	v_mfma_f32_16x16x32_bf16 v[34:37], v[164:167], v[192:195], v[34:37]
	v_mfma_f32_16x16x32_bf16 v[34:37], v[180:183], v[196:199], v[34:37]
	v_mfma_f32_16x16x32_bf16 v[42:45], v[156:159], v[192:195], v[42:45]
	v_mfma_f32_16x16x32_bf16 v[42:45], v[160:163], v[196:199], v[42:45]
	v_mfma_f32_16x16x32_bf16 v[38:41], v[148:151], v[192:195], v[38:41]
	v_mfma_f32_16x16x32_bf16 v[38:41], v[152:155], v[196:199], v[38:41]
	v_mfma_f32_16x16x32_bf16 v[46:49], v[130:133], v[192:195], v[46:49]
	v_mfma_f32_16x16x32_bf16 v[46:49], v[134:137], v[196:199], v[46:49]
	v_mfma_f32_16x16x32_bf16 v[30:33], v[130:133], v[200:203], v[30:33]
	v_mfma_f32_16x16x32_bf16 v[30:33], v[134:137], v[204:207], v[30:33]
	v_mfma_f32_16x16x32_bf16 v[22:25], v[148:151], v[200:203], v[22:25]
	v_mfma_f32_16x16x32_bf16 v[22:25], v[152:155], v[204:207], v[22:25]
	v_mfma_f32_16x16x32_bf16 v[26:29], v[156:159], v[200:203], v[26:29]
	v_mfma_f32_16x16x32_bf16 v[26:29], v[160:163], v[204:207], v[26:29]
	v_mfma_f32_16x16x32_bf16 v[18:21], v[164:167], v[200:203], v[18:21]
	v_mfma_f32_16x16x32_bf16 v[18:21], v[180:183], v[204:207], v[18:21]
	v_mfma_f32_16x16x32_bf16 v[2:5], v[164:167], v[208:211], v[2:5]
	v_mfma_f32_16x16x32_bf16 v[2:5], v[180:183], v[212:215], v[2:5]
	v_mfma_f32_16x16x32_bf16 v[10:13], v[156:159], v[208:211], v[10:13]
	v_mfma_f32_16x16x32_bf16 v[10:13], v[160:163], v[212:215], v[10:13]
	v_mfma_f32_16x16x32_bf16 v[6:9], v[148:151], v[208:211], v[6:9]
	v_mfma_f32_16x16x32_bf16 v[6:9], v[152:155], v[212:215], v[6:9]
	v_mfma_f32_16x16x32_bf16 v[14:17], v[130:133], v[208:211], v[14:17]
	v_mfma_f32_16x16x32_bf16 v[14:17], v[134:137], v[212:215], v[14:17]
	s_setprio 0
	s_barrier
	ds_read_b128 v[130:133], v175
	ds_read_b128 v[134:137], v175 offset:1024
	ds_read_b128 v[148:151], v175 offset:2048
	ds_read_b128 v[152:155], v175 offset:3072
	ds_read_b128 v[156:159], v176
	ds_read_b128 v[160:163], v176 offset:1024
	ds_read_b128 v[164:167], v176 offset:2048
	ds_read_b128 v[180:183], v176 offset:3072
	s_mov_b32 m0, s64
	s_add_i32 s59, s53, 0x100000
	ds_read_b128 v[184:187], v174 offset:32768
	ds_read_b128 v[188:191], v174 offset:33792
	ds_read_b128 v[192:195], v174 offset:34816
	ds_read_b128 v[196:199], v174 offset:35840
	ds_read_b128 v[200:203], v174 offset:36864
	ds_read_b128 v[204:207], v174 offset:37888
	ds_read_b128 v[208:211], v174 offset:38912
	ds_read_b128 v[212:215], v174 offset:39936
	buffer_load_dwordx4 v170, s[12:15], s59 offen lds
	s_mov_b32 m0, s65
	s_add_i32 s59, s53, 0x180000
	buffer_load_dwordx4 v170, s[12:15], s59 offen lds
	s_waitcnt vmcnt(8) lgkmcnt(0)
	s_setprio 1
	v_mfma_f32_16x16x32_bf16 v[126:129], v[130:133], v[184:187], v[126:129]
	s_barrier
	v_mfma_f32_16x16x32_bf16 v[126:129], v[134:137], v[188:191], v[126:129]
	v_mfma_f32_16x16x32_bf16 v[118:121], v[148:151], v[184:187], v[118:121]
	v_mfma_f32_16x16x32_bf16 v[118:121], v[152:155], v[188:191], v[118:121]
	v_mfma_f32_16x16x32_bf16 v[122:125], v[156:159], v[184:187], v[122:125]
	v_mfma_f32_16x16x32_bf16 v[122:125], v[160:163], v[188:191], v[122:125]
	v_mfma_f32_16x16x32_bf16 v[114:117], v[164:167], v[184:187], v[114:117]
	v_mfma_f32_16x16x32_bf16 v[114:117], v[180:183], v[188:191], v[114:117]
	v_mfma_f32_16x16x32_bf16 v[98:101], v[164:167], v[192:195], v[98:101]
	v_mfma_f32_16x16x32_bf16 v[98:101], v[180:183], v[196:199], v[98:101]
	v_mfma_f32_16x16x32_bf16 v[106:109], v[156:159], v[192:195], v[106:109]
	v_mfma_f32_16x16x32_bf16 v[106:109], v[160:163], v[196:199], v[106:109]
	v_mfma_f32_16x16x32_bf16 v[102:105], v[148:151], v[192:195], v[102:105]
	v_mfma_f32_16x16x32_bf16 v[102:105], v[152:155], v[196:199], v[102:105]
	v_mfma_f32_16x16x32_bf16 v[110:113], v[130:133], v[192:195], v[110:113]
	v_mfma_f32_16x16x32_bf16 v[110:113], v[134:137], v[196:199], v[110:113]
	v_mfma_f32_16x16x32_bf16 v[94:97], v[130:133], v[200:203], v[94:97]
	v_mfma_f32_16x16x32_bf16 v[94:97], v[134:137], v[204:207], v[94:97]
	v_mfma_f32_16x16x32_bf16 v[90:93], v[148:151], v[200:203], v[90:93]
	v_mfma_f32_16x16x32_bf16 v[90:93], v[152:155], v[204:207], v[90:93]
	v_mfma_f32_16x16x32_bf16 v[86:89], v[156:159], v[200:203], v[86:89]
	v_mfma_f32_16x16x32_bf16 v[86:89], v[160:163], v[204:207], v[86:89]
	v_mfma_f32_16x16x32_bf16 v[82:85], v[164:167], v[200:203], v[82:85]
	v_mfma_f32_16x16x32_bf16 v[82:85], v[180:183], v[204:207], v[82:85]
	v_mfma_f32_16x16x32_bf16 v[66:69], v[164:167], v[208:211], v[66:69]
	v_mfma_f32_16x16x32_bf16 v[66:69], v[180:183], v[212:215], v[66:69]
	v_mfma_f32_16x16x32_bf16 v[74:77], v[156:159], v[208:211], v[74:77]
	v_mfma_f32_16x16x32_bf16 v[74:77], v[160:163], v[212:215], v[74:77]
	v_mfma_f32_16x16x32_bf16 v[70:73], v[148:151], v[208:211], v[70:73]
	v_mfma_f32_16x16x32_bf16 v[70:73], v[152:155], v[212:215], v[70:73]
	v_mfma_f32_16x16x32_bf16 v[78:81], v[130:133], v[208:211], v[78:81]
	v_mfma_f32_16x16x32_bf16 v[78:81], v[134:137], v[212:215], v[78:81]
	s_setprio 0
	s_barrier
	ds_read_b128 v[184:187], v174 offset:49152
	ds_read_b128 v[188:191], v174 offset:50176
	ds_read_b128 v[192:195], v174 offset:51200
	ds_read_b128 v[196:199], v174 offset:52224
	ds_read_b128 v[200:203], v174 offset:53248
	ds_read_b128 v[204:207], v174 offset:54272
	ds_read_b128 v[208:211], v174 offset:55296
	ds_read_b128 v[212:215], v174 offset:56320
	s_mov_b32 m0, s70
	s_or_b32 s59, s58, 0x80
	buffer_load_dwordx4 v171, s[16:19], s59 offen lds
	s_add_i32 s59, s58, 0x80080
	s_mov_b32 m0, s71
	s_add_i32 s53, s53, 0x80080
	buffer_load_dwordx4 v171, s[16:19], s59 offen lds
	s_add_i32 s59, s58, 0x100080
	s_mov_b32 m0, s74
	s_add_i32 s58, s58, 0x180080
	buffer_load_dwordx4 v171, s[16:19], s59 offen lds
	s_mov_b32 m0, s75
	s_nop 0
	buffer_load_dwordx4 v171, s[16:19], s58 offen lds
	s_mov_b32 m0, s72
	s_nop 0
	buffer_load_dwordx4 v170, s[12:15], s57 offen lds
	s_mov_b32 m0, s73
	s_nop 0
	buffer_load_dwordx4 v170, s[12:15], s53 offen lds
	s_waitcnt vmcnt(8) lgkmcnt(0)
	s_setprio 1
	v_mfma_f32_16x16x32_bf16 v[62:65], v[130:133], v[184:187], v[62:65]
	s_barrier
	v_mfma_f32_16x16x32_bf16 v[62:65], v[134:137], v[188:191], v[62:65]
	v_mfma_f32_16x16x32_bf16 v[54:57], v[148:151], v[184:187], v[54:57]
	v_mfma_f32_16x16x32_bf16 v[54:57], v[152:155], v[188:191], v[54:57]
	v_mfma_f32_16x16x32_bf16 v[58:61], v[156:159], v[184:187], v[58:61]
	v_mfma_f32_16x16x32_bf16 v[58:61], v[160:163], v[188:191], v[58:61]
	v_mfma_f32_16x16x32_bf16 v[50:53], v[164:167], v[184:187], v[50:53]
	v_mfma_f32_16x16x32_bf16 v[50:53], v[180:183], v[188:191], v[50:53]
	v_mfma_f32_16x16x32_bf16 v[34:37], v[164:167], v[192:195], v[34:37]
	v_mfma_f32_16x16x32_bf16 v[34:37], v[180:183], v[196:199], v[34:37]
	v_mfma_f32_16x16x32_bf16 v[42:45], v[156:159], v[192:195], v[42:45]
	v_mfma_f32_16x16x32_bf16 v[42:45], v[160:163], v[196:199], v[42:45]
	v_mfma_f32_16x16x32_bf16 v[38:41], v[148:151], v[192:195], v[38:41]
	v_mfma_f32_16x16x32_bf16 v[38:41], v[152:155], v[196:199], v[38:41]
	v_mfma_f32_16x16x32_bf16 v[46:49], v[130:133], v[192:195], v[46:49]
	v_mfma_f32_16x16x32_bf16 v[46:49], v[134:137], v[196:199], v[46:49]
	v_mfma_f32_16x16x32_bf16 v[30:33], v[130:133], v[200:203], v[30:33]
	v_mfma_f32_16x16x32_bf16 v[30:33], v[134:137], v[204:207], v[30:33]
	v_mfma_f32_16x16x32_bf16 v[22:25], v[148:151], v[200:203], v[22:25]
	v_mfma_f32_16x16x32_bf16 v[22:25], v[152:155], v[204:207], v[22:25]
	v_mfma_f32_16x16x32_bf16 v[26:29], v[156:159], v[200:203], v[26:29]
	v_mfma_f32_16x16x32_bf16 v[26:29], v[160:163], v[204:207], v[26:29]
	v_mfma_f32_16x16x32_bf16 v[18:21], v[164:167], v[200:203], v[18:21]
	v_mfma_f32_16x16x32_bf16 v[18:21], v[180:183], v[204:207], v[18:21]
	v_mfma_f32_16x16x32_bf16 v[2:5], v[164:167], v[208:211], v[2:5]
	v_mfma_f32_16x16x32_bf16 v[2:5], v[180:183], v[212:215], v[2:5]
	v_mfma_f32_16x16x32_bf16 v[10:13], v[156:159], v[208:211], v[10:13]
	v_mfma_f32_16x16x32_bf16 v[10:13], v[160:163], v[212:215], v[10:13]
	v_mfma_f32_16x16x32_bf16 v[6:9], v[148:151], v[208:211], v[6:9]
	v_mfma_f32_16x16x32_bf16 v[6:9], v[152:155], v[212:215], v[6:9]
	v_mfma_f32_16x16x32_bf16 v[14:17], v[130:133], v[208:211], v[14:17]
	v_mfma_f32_16x16x32_bf16 v[14:17], v[134:137], v[212:215], v[14:17]
	s_setprio 0
	s_barrier
	s_add_i32 s52, s52, 2
	s_addk_i32 s8, 0x100
	s_addk_i32 s9, 0x100
	s_cmp_ge_i32 s52, s21
	s_cbranch_scc0 .LBB0_892
	s_and_b64 vcc, exec, s[48:49]
	s_cbranch_vccz .LBB0_895

.LBB0_1020:
	v_add_u32_e32 v142, 0x10000, v162
	v_add_u32_e32 v150, 0x14000, v162
	ds_read_b128 v[130:133], v142
	ds_read_b128 v[134:137], v142 offset:1024
	ds_read_b128 v[138:141], v142 offset:2048
	ds_read_b128 v[142:145], v142 offset:3072
	ds_read_b128 v[154:157], v150
	ds_read_b128 v[164:167], v150 offset:1024
	ds_read_b128 v[168:171], v150 offset:2048
	ds_read_b128 v[172:175], v150 offset:3072
	s_add_i32 s90, s6, 0x100
	s_add_i32 s7, s88, s6
	s_cmp_eq_u32 s81, s89
	s_cselect_b32 s91, 0, s90
	s_cselect_b32 s93, s87, s7
	s_add_i32 s91, s91, s70
	s_or_b32 s92, s91, 0x80
	s_add_i32 s6, s3, s6
	s_mov_b32 m0, s82
	s_add_i32 s7, s6, 0x20080
	ds_read_b128 v[176:179], v163
	ds_read_b128 v[180:183], v163 offset:1024
	ds_read_b128 v[184:187], v163 offset:2048
	ds_read_b128 v[188:191], v163 offset:3072
	ds_read_b128 v[192:195], v163 offset:4096
	ds_read_b128 v[196:199], v163 offset:5120
	ds_read_b128 v[200:203], v163 offset:6144
	ds_read_b128 v[204:207], v163 offset:7168
	buffer_load_dwordx4 v161, s[12:15], s7 offen lds
	s_mov_b32 m0, s83
	s_add_i32 s6, s6, 0x30080
	buffer_load_dwordx4 v161, s[12:15], s6 offen lds
	s_waitcnt vmcnt(8) lgkmcnt(0)
	s_setprio 1
	v_mfma_f32_16x16x32_bf16 v[126:129], v[130:133], v[176:179], v[126:129]
	s_barrier
	v_mfma_f32_16x16x32_bf16 v[126:129], v[134:137], v[180:183], v[126:129]
	v_mfma_f32_16x16x32_bf16 v[122:125], v[138:141], v[176:179], v[122:125]
	v_mfma_f32_16x16x32_bf16 v[122:125], v[142:145], v[180:183], v[122:125]
	v_mfma_f32_16x16x32_bf16 v[118:121], v[154:157], v[176:179], v[118:121]
	v_mfma_f32_16x16x32_bf16 v[118:121], v[164:167], v[180:183], v[118:121]
	v_mfma_f32_16x16x32_bf16 v[114:117], v[168:171], v[176:179], v[114:117]
	v_mfma_f32_16x16x32_bf16 v[114:117], v[172:175], v[180:183], v[114:117]
	v_mfma_f32_16x16x32_bf16 v[98:101], v[168:171], v[184:187], v[98:101]
	v_mfma_f32_16x16x32_bf16 v[98:101], v[172:175], v[188:191], v[98:101]
	v_mfma_f32_16x16x32_bf16 v[102:105], v[154:157], v[184:187], v[102:105]
	v_mfma_f32_16x16x32_bf16 v[102:105], v[164:167], v[188:191], v[102:105]
	v_mfma_f32_16x16x32_bf16 v[106:109], v[138:141], v[184:187], v[106:109]
	v_mfma_f32_16x16x32_bf16 v[106:109], v[142:145], v[188:191], v[106:109]
	v_mfma_f32_16x16x32_bf16 v[110:113], v[130:133], v[184:187], v[110:113]
	v_mfma_f32_16x16x32_bf16 v[110:113], v[134:137], v[188:191], v[110:113]
	v_mfma_f32_16x16x32_bf16 v[94:97], v[130:133], v[192:195], v[94:97]
	v_mfma_f32_16x16x32_bf16 v[94:97], v[134:137], v[196:199], v[94:97]
	v_mfma_f32_16x16x32_bf16 v[90:93], v[138:141], v[192:195], v[90:93]
	v_mfma_f32_16x16x32_bf16 v[90:93], v[142:145], v[196:199], v[90:93]
	v_mfma_f32_16x16x32_bf16 v[86:89], v[154:157], v[192:195], v[86:89]
	v_mfma_f32_16x16x32_bf16 v[86:89], v[164:167], v[196:199], v[86:89]
	v_mfma_f32_16x16x32_bf16 v[82:85], v[168:171], v[192:195], v[82:85]
	v_mfma_f32_16x16x32_bf16 v[82:85], v[172:175], v[196:199], v[82:85]
	v_mfma_f32_16x16x32_bf16 v[66:69], v[168:171], v[200:203], v[66:69]
	v_mfma_f32_16x16x32_bf16 v[66:69], v[172:175], v[204:207], v[66:69]
	v_mfma_f32_16x16x32_bf16 v[70:73], v[154:157], v[200:203], v[70:73]
	v_mfma_f32_16x16x32_bf16 v[70:73], v[164:167], v[204:207], v[70:73]
	v_mfma_f32_16x16x32_bf16 v[74:77], v[138:141], v[200:203], v[74:77]
	v_mfma_f32_16x16x32_bf16 v[74:77], v[142:145], v[204:207], v[74:77]
	v_mfma_f32_16x16x32_bf16 v[78:81], v[130:133], v[200:203], v[78:81]
	v_mfma_f32_16x16x32_bf16 v[78:81], v[134:137], v[204:207], v[78:81]
	s_setprio 0
	s_barrier
	ds_read_b128 v[176:179], v163 offset:16384
	ds_read_b128 v[180:183], v163 offset:17408
	ds_read_b128 v[184:187], v163 offset:18432
	ds_read_b128 v[188:191], v163 offset:19456
	ds_read_b128 v[192:195], v163 offset:20480
	ds_read_b128 v[196:199], v163 offset:21504
	ds_read_b128 v[200:203], v163 offset:22528
	ds_read_b128 v[204:207], v163 offset:23552
	s_mov_b32 m0, s66
	s_mov_b32 s6, s14
	s_mov_b32 s7, s15
	buffer_load_dwordx4 v160, s[4:7], s93 offen lds
	s_mov_b32 m0, s67
	s_add_i32 s94, s93, 0x10000
	buffer_load_dwordx4 v160, s[4:7], s94 offen lds
	s_mov_b32 m0, s68
	s_add_i32 s94, s93, 0x20000
	buffer_load_dwordx4 v160, s[4:7], s94 offen lds
	s_mov_b32 m0, s69
	s_add_i32 s94, s93, 0x30000
	buffer_load_dwordx4 v160, s[4:7], s94 offen lds
	s_mov_b32 m0, s65
	s_add_i32 s94, s91, 0x10000
	buffer_load_dwordx4 v161, s[12:15], s91 offen lds
	s_mov_b32 m0, s71
	s_nop 0
	buffer_load_dwordx4 v161, s[12:15], s94 offen lds
	s_waitcnt vmcnt(8) lgkmcnt(0)
	s_setprio 1
	v_mfma_f32_16x16x32_bf16 v[62:65], v[130:133], v[176:179], v[62:65]
	s_barrier
	v_mfma_f32_16x16x32_bf16 v[62:65], v[134:137], v[180:183], v[62:65]
	v_mfma_f32_16x16x32_bf16 v[58:61], v[138:141], v[176:179], v[58:61]
	v_mfma_f32_16x16x32_bf16 v[58:61], v[142:145], v[180:183], v[58:61]
	v_mfma_f32_16x16x32_bf16 v[54:57], v[154:157], v[176:179], v[54:57]
	v_mfma_f32_16x16x32_bf16 v[54:57], v[164:167], v[180:183], v[54:57]
	v_mfma_f32_16x16x32_bf16 v[50:53], v[168:171], v[176:179], v[50:53]
	v_mfma_f32_16x16x32_bf16 v[50:53], v[172:175], v[180:183], v[50:53]
	v_mfma_f32_16x16x32_bf16 v[34:37], v[168:171], v[184:187], v[34:37]
	v_mfma_f32_16x16x32_bf16 v[34:37], v[172:175], v[188:191], v[34:37]
	v_mfma_f32_16x16x32_bf16 v[38:41], v[154:157], v[184:187], v[38:41]
	v_mfma_f32_16x16x32_bf16 v[38:41], v[164:167], v[188:191], v[38:41]
	v_mfma_f32_16x16x32_bf16 v[42:45], v[138:141], v[184:187], v[42:45]
	v_mfma_f32_16x16x32_bf16 v[42:45], v[142:145], v[188:191], v[42:45]
	v_mfma_f32_16x16x32_bf16 v[46:49], v[130:133], v[184:187], v[46:49]
	v_mfma_f32_16x16x32_bf16 v[46:49], v[134:137], v[188:191], v[46:49]
	v_mfma_f32_16x16x32_bf16 v[30:33], v[130:133], v[192:195], v[30:33]
	v_mfma_f32_16x16x32_bf16 v[30:33], v[134:137], v[196:199], v[30:33]
	v_mfma_f32_16x16x32_bf16 v[26:29], v[138:141], v[192:195], v[26:29]
	v_mfma_f32_16x16x32_bf16 v[26:29], v[142:145], v[196:199], v[26:29]
	v_mfma_f32_16x16x32_bf16 v[22:25], v[154:157], v[192:195], v[22:25]
	v_mfma_f32_16x16x32_bf16 v[22:25], v[164:167], v[196:199], v[22:25]
	v_mfma_f32_16x16x32_bf16 v[18:21], v[168:171], v[192:195], v[18:21]
	v_mfma_f32_16x16x32_bf16 v[18:21], v[172:175], v[196:199], v[18:21]
	v_mfma_f32_16x16x32_bf16 v[2:5], v[168:171], v[200:203], v[2:5]
	v_mfma_f32_16x16x32_bf16 v[2:5], v[172:175], v[204:207], v[2:5]
	v_mfma_f32_16x16x32_bf16 v[6:9], v[154:157], v[200:203], v[6:9]
	v_mfma_f32_16x16x32_bf16 v[6:9], v[164:167], v[204:207], v[6:9]
	v_mfma_f32_16x16x32_bf16 v[10:13], v[138:141], v[200:203], v[10:13]
	v_mfma_f32_16x16x32_bf16 v[10:13], v[142:145], v[204:207], v[10:13]
	v_mfma_f32_16x16x32_bf16 v[14:17], v[130:133], v[200:203], v[14:17]
	v_mfma_f32_16x16x32_bf16 v[14:17], v[134:137], v[204:207], v[14:17]
	s_setprio 0
	s_barrier
	v_add_u32_e32 v142, 0x18000, v162
	v_add_u32_e32 v150, 0x1c000, v162
	ds_read_b128 v[130:133], v142
	ds_read_b128 v[134:137], v142 offset:1024
	ds_read_b128 v[138:141], v142 offset:2048
	ds_read_b128 v[142:145], v142 offset:3072
	ds_read_b128 v[154:157], v150
	ds_read_b128 v[164:167], v150 offset:1024
	ds_read_b128 v[168:171], v150 offset:2048
	ds_read_b128 v[172:175], v150 offset:3072
	s_mov_b32 m0, s72
	s_add_i32 s94, s91, 0x20000
	ds_read_b128 v[176:179], v163 offset:32768
	ds_read_b128 v[180:183], v163 offset:33792
	ds_read_b128 v[184:187], v163 offset:34816
	ds_read_b128 v[188:191], v163 offset:35840
	ds_read_b128 v[192:195], v163 offset:36864
	ds_read_b128 v[196:199], v163 offset:37888
	ds_read_b128 v[200:203], v163 offset:38912
	ds_read_b128 v[204:207], v163 offset:39936
	buffer_load_dwordx4 v161, s[12:15], s94 offen lds
	s_mov_b32 m0, s73
	s_add_i32 s94, s91, 0x30000
	buffer_load_dwordx4 v161, s[12:15], s94 offen lds
	s_waitcnt vmcnt(8) lgkmcnt(0)
	s_setprio 1
	v_mfma_f32_16x16x32_bf16 v[126:129], v[130:133], v[176:179], v[126:129]
	s_barrier
	v_mfma_f32_16x16x32_bf16 v[126:129], v[134:137], v[180:183], v[126:129]
	v_mfma_f32_16x16x32_bf16 v[122:125], v[138:141], v[176:179], v[122:125]
	v_mfma_f32_16x16x32_bf16 v[122:125], v[142:145], v[180:183], v[122:125]
	v_mfma_f32_16x16x32_bf16 v[118:121], v[154:157], v[176:179], v[118:121]
	v_mfma_f32_16x16x32_bf16 v[118:121], v[164:167], v[180:183], v[118:121]
	v_mfma_f32_16x16x32_bf16 v[114:117], v[168:171], v[176:179], v[114:117]
	v_mfma_f32_16x16x32_bf16 v[114:117], v[172:175], v[180:183], v[114:117]
	v_mfma_f32_16x16x32_bf16 v[98:101], v[168:171], v[184:187], v[98:101]
	v_mfma_f32_16x16x32_bf16 v[98:101], v[172:175], v[188:191], v[98:101]
	v_mfma_f32_16x16x32_bf16 v[102:105], v[154:157], v[184:187], v[102:105]
	v_mfma_f32_16x16x32_bf16 v[102:105], v[164:167], v[188:191], v[102:105]
	v_mfma_f32_16x16x32_bf16 v[106:109], v[138:141], v[184:187], v[106:109]
	v_mfma_f32_16x16x32_bf16 v[106:109], v[142:145], v[188:191], v[106:109]
	v_mfma_f32_16x16x32_bf16 v[110:113], v[130:133], v[184:187], v[110:113]
	v_mfma_f32_16x16x32_bf16 v[110:113], v[134:137], v[188:191], v[110:113]
	v_mfma_f32_16x16x32_bf16 v[94:97], v[130:133], v[192:195], v[94:97]
	v_mfma_f32_16x16x32_bf16 v[94:97], v[134:137], v[196:199], v[94:97]
	v_mfma_f32_16x16x32_bf16 v[90:93], v[138:141], v[192:195], v[90:93]
	v_mfma_f32_16x16x32_bf16 v[90:93], v[142:145], v[196:199], v[90:93]
	v_mfma_f32_16x16x32_bf16 v[86:89], v[154:157], v[192:195], v[86:89]
	v_mfma_f32_16x16x32_bf16 v[86:89], v[164:167], v[196:199], v[86:89]
	v_mfma_f32_16x16x32_bf16 v[82:85], v[168:171], v[192:195], v[82:85]
	v_mfma_f32_16x16x32_bf16 v[82:85], v[172:175], v[196:199], v[82:85]
	v_mfma_f32_16x16x32_bf16 v[66:69], v[168:171], v[200:203], v[66:69]
	v_mfma_f32_16x16x32_bf16 v[66:69], v[172:175], v[204:207], v[66:69]
	v_mfma_f32_16x16x32_bf16 v[70:73], v[154:157], v[200:203], v[70:73]
	v_mfma_f32_16x16x32_bf16 v[70:73], v[164:167], v[204:207], v[70:73]
	v_mfma_f32_16x16x32_bf16 v[74:77], v[138:141], v[200:203], v[74:77]
	v_mfma_f32_16x16x32_bf16 v[74:77], v[142:145], v[204:207], v[74:77]
	v_mfma_f32_16x16x32_bf16 v[78:81], v[130:133], v[200:203], v[78:81]
	v_mfma_f32_16x16x32_bf16 v[78:81], v[134:137], v[204:207], v[78:81]
	s_setprio 0
	s_barrier
	ds_read_b128 v[176:179], v163 offset:49152
	ds_read_b128 v[180:183], v163 offset:50176
	ds_read_b128 v[184:187], v163 offset:51200
	ds_read_b128 v[188:191], v163 offset:52224
	ds_read_b128 v[192:195], v163 offset:53248
	ds_read_b128 v[196:199], v163 offset:54272
	ds_read_b128 v[200:203], v163 offset:55296
	ds_read_b128 v[204:207], v163 offset:56320
	s_mov_b32 m0, s74
	s_or_b32 s94, s93, 0x80
	buffer_load_dwordx4 v160, s[4:7], s94 offen lds
	s_add_i32 s94, s93, 0x10080
	s_mov_b32 m0, s75
	s_add_i32 s91, s91, 0x10080
	buffer_load_dwordx4 v160, s[4:7], s94 offen lds
	s_add_i32 s94, s93, 0x20080
	s_mov_b32 m0, s78
	s_add_i32 s93, s93, 0x30080
	buffer_load_dwordx4 v160, s[4:7], s94 offen lds
	s_mov_b32 m0, s79
	s_nop 0
	buffer_load_dwordx4 v160, s[4:7], s93 offen lds
	s_mov_b32 m0, s76
	s_nop 0
	buffer_load_dwordx4 v161, s[12:15], s92 offen lds
	s_mov_b32 m0, s77
	s_nop 0
	buffer_load_dwordx4 v161, s[12:15], s91 offen lds
	s_waitcnt vmcnt(8) lgkmcnt(0)
	s_setprio 1
	v_mfma_f32_16x16x32_bf16 v[62:65], v[130:133], v[176:179], v[62:65]
	s_barrier
	v_mfma_f32_16x16x32_bf16 v[62:65], v[134:137], v[180:183], v[62:65]
	v_mfma_f32_16x16x32_bf16 v[58:61], v[138:141], v[176:179], v[58:61]
	v_mfma_f32_16x16x32_bf16 v[58:61], v[142:145], v[180:183], v[58:61]
	v_mfma_f32_16x16x32_bf16 v[54:57], v[154:157], v[176:179], v[54:57]
	v_mfma_f32_16x16x32_bf16 v[54:57], v[164:167], v[180:183], v[54:57]
	v_mfma_f32_16x16x32_bf16 v[50:53], v[168:171], v[176:179], v[50:53]
	v_mfma_f32_16x16x32_bf16 v[50:53], v[172:175], v[180:183], v[50:53]
	v_mfma_f32_16x16x32_bf16 v[34:37], v[168:171], v[184:187], v[34:37]
	v_mfma_f32_16x16x32_bf16 v[34:37], v[172:175], v[188:191], v[34:37]
	v_mfma_f32_16x16x32_bf16 v[38:41], v[154:157], v[184:187], v[38:41]
	v_mfma_f32_16x16x32_bf16 v[38:41], v[164:167], v[188:191], v[38:41]
	v_mfma_f32_16x16x32_bf16 v[42:45], v[138:141], v[184:187], v[42:45]
	v_mfma_f32_16x16x32_bf16 v[42:45], v[142:145], v[188:191], v[42:45]
	v_mfma_f32_16x16x32_bf16 v[46:49], v[130:133], v[184:187], v[46:49]
	v_mfma_f32_16x16x32_bf16 v[46:49], v[134:137], v[188:191], v[46:49]
	v_mfma_f32_16x16x32_bf16 v[30:33], v[130:133], v[192:195], v[30:33]
	v_mfma_f32_16x16x32_bf16 v[30:33], v[134:137], v[196:199], v[30:33]
	v_mfma_f32_16x16x32_bf16 v[26:29], v[138:141], v[192:195], v[26:29]
	v_mfma_f32_16x16x32_bf16 v[26:29], v[142:145], v[196:199], v[26:29]
	v_mfma_f32_16x16x32_bf16 v[22:25], v[154:157], v[192:195], v[22:25]
	v_mfma_f32_16x16x32_bf16 v[22:25], v[164:167], v[196:199], v[22:25]
	v_mfma_f32_16x16x32_bf16 v[18:21], v[168:171], v[192:195], v[18:21]
	v_mfma_f32_16x16x32_bf16 v[18:21], v[172:175], v[196:199], v[18:21]
	v_mfma_f32_16x16x32_bf16 v[2:5], v[168:171], v[200:203], v[2:5]
	v_mfma_f32_16x16x32_bf16 v[2:5], v[172:175], v[204:207], v[2:5]
	v_mfma_f32_16x16x32_bf16 v[6:9], v[154:157], v[200:203], v[6:9]
	v_mfma_f32_16x16x32_bf16 v[6:9], v[164:167], v[204:207], v[6:9]
	v_mfma_f32_16x16x32_bf16 v[10:13], v[138:141], v[200:203], v[10:13]
	v_mfma_f32_16x16x32_bf16 v[10:13], v[142:145], v[204:207], v[10:13]
	v_mfma_f32_16x16x32_bf16 v[14:17], v[130:133], v[200:203], v[14:17]
	v_mfma_f32_16x16x32_bf16 v[14:17], v[134:137], v[204:207], v[14:17]
	s_setprio 0
	s_barrier
	s_add_i32 s89, s89, 2
	s_cmp_ge_i32 s89, s63
	s_mov_b32 s6, s90
	s_cbranch_scc0 .LBB0_1020
	s_and_b64 vcc, exec, s[54:55]
	s_cbranch_vccz .LBB0_1023

.LBB0_1035:
	ds_read_b128 v[140:143], v134
	ds_read_b128 v[148:151], v134 offset:1024
	ds_read_b128 v[152:155], v134 offset:2048
	ds_read_b128 v[156:159], v134 offset:3072
	ds_read_b128 v[160:163], v135
	ds_read_b128 v[164:167], v135 offset:1024
	ds_read_b128 v[168:171], v135 offset:2048
	ds_read_b128 v[172:175], v135 offset:3072
	s_add_i32 s73, s70, 0xfffb8080
	s_cmp_eq_u32 s53, s72
	s_cselect_b32 s73, s68, s73
	s_cselect_b32 s75, s69, s71
	s_add_i32 s74, s73, 0x80
	s_add_i32 s76, s70, 0xfffe8000
	s_mov_b32 m0, s54
	ds_read_b128 v[176:179], v136
	ds_read_b128 v[180:183], v136 offset:1024
	ds_read_b128 v[184:187], v136 offset:2048
	ds_read_b128 v[188:191], v136 offset:3072
	ds_read_b128 v[192:195], v136 offset:4096
	ds_read_b128 v[196:199], v136 offset:5120
	ds_read_b128 v[200:203], v136 offset:6144
	ds_read_b128 v[204:207], v136 offset:7168
	buffer_load_dwordx4 v132, s[12:15], s76 offen lds
	s_mov_b32 m0, s55
	s_nop 0
	buffer_load_dwordx4 v132, s[12:15], s70 offen lds
	s_waitcnt vmcnt(8) lgkmcnt(0)
	s_setprio 1
	v_mfma_f32_16x16x32_bf16 v[126:129], v[140:143], v[176:179], v[126:129]
	s_barrier
	v_mfma_f32_16x16x32_bf16 v[126:129], v[148:151], v[180:183], v[126:129]
	v_mfma_f32_16x16x32_bf16 v[122:125], v[152:155], v[176:179], v[122:125]
	v_mfma_f32_16x16x32_bf16 v[122:125], v[156:159], v[180:183], v[122:125]
	v_mfma_f32_16x16x32_bf16 v[118:121], v[160:163], v[176:179], v[118:121]
	v_mfma_f32_16x16x32_bf16 v[118:121], v[164:167], v[180:183], v[118:121]
	v_mfma_f32_16x16x32_bf16 v[114:117], v[168:171], v[176:179], v[114:117]
	v_mfma_f32_16x16x32_bf16 v[114:117], v[172:175], v[180:183], v[114:117]
	v_mfma_f32_16x16x32_bf16 v[98:101], v[168:171], v[184:187], v[98:101]
	v_mfma_f32_16x16x32_bf16 v[98:101], v[172:175], v[188:191], v[98:101]
	v_mfma_f32_16x16x32_bf16 v[102:105], v[160:163], v[184:187], v[102:105]
	v_mfma_f32_16x16x32_bf16 v[102:105], v[164:167], v[188:191], v[102:105]
	v_mfma_f32_16x16x32_bf16 v[106:109], v[152:155], v[184:187], v[106:109]
	v_mfma_f32_16x16x32_bf16 v[106:109], v[156:159], v[188:191], v[106:109]
	v_mfma_f32_16x16x32_bf16 v[110:113], v[140:143], v[184:187], v[110:113]
	v_mfma_f32_16x16x32_bf16 v[110:113], v[148:151], v[188:191], v[110:113]
	v_mfma_f32_16x16x32_bf16 v[94:97], v[140:143], v[192:195], v[94:97]
	v_mfma_f32_16x16x32_bf16 v[94:97], v[148:151], v[196:199], v[94:97]
	v_mfma_f32_16x16x32_bf16 v[90:93], v[152:155], v[192:195], v[90:93]
	v_mfma_f32_16x16x32_bf16 v[90:93], v[156:159], v[196:199], v[90:93]
	v_mfma_f32_16x16x32_bf16 v[86:89], v[160:163], v[192:195], v[86:89]
	v_mfma_f32_16x16x32_bf16 v[86:89], v[164:167], v[196:199], v[86:89]
	v_mfma_f32_16x16x32_bf16 v[82:85], v[168:171], v[192:195], v[82:85]
	v_mfma_f32_16x16x32_bf16 v[82:85], v[172:175], v[196:199], v[82:85]
	v_mfma_f32_16x16x32_bf16 v[66:69], v[168:171], v[200:203], v[66:69]
	v_mfma_f32_16x16x32_bf16 v[66:69], v[172:175], v[204:207], v[66:69]
	v_mfma_f32_16x16x32_bf16 v[70:73], v[160:163], v[200:203], v[70:73]
	v_mfma_f32_16x16x32_bf16 v[70:73], v[164:167], v[204:207], v[70:73]
	v_mfma_f32_16x16x32_bf16 v[74:77], v[152:155], v[200:203], v[74:77]
	v_mfma_f32_16x16x32_bf16 v[74:77], v[156:159], v[204:207], v[74:77]
	v_mfma_f32_16x16x32_bf16 v[78:81], v[140:143], v[200:203], v[78:81]
	v_mfma_f32_16x16x32_bf16 v[78:81], v[148:151], v[204:207], v[78:81]
	s_setprio 0
	s_barrier
	ds_read_b128 v[176:179], v136 offset:16384
	ds_read_b128 v[180:183], v136 offset:17408
	ds_read_b128 v[184:187], v136 offset:18432
	ds_read_b128 v[188:191], v136 offset:19456
	ds_read_b128 v[192:195], v136 offset:20480
	ds_read_b128 v[196:199], v136 offset:21504
	ds_read_b128 v[200:203], v136 offset:22528
	ds_read_b128 v[204:207], v136 offset:23552
	s_mov_b32 m0, s30
	s_nop 0
	buffer_load_dwordx4 v133, s[16:19], s75 offen lds
	s_mov_b32 m0, s31
	s_add_i32 s76, s75, 0x200000
	buffer_load_dwordx4 v133, s[16:19], s76 offen lds
	s_mov_b32 m0, s35
	s_add_i32 s76, s75, 0x400000
	buffer_load_dwordx4 v133, s[16:19], s76 offen lds
	s_mov_b32 m0, s42
	s_add_i32 s76, s75, 0x600000
	buffer_load_dwordx4 v133, s[16:19], s76 offen lds
	s_mov_b32 m0, s27
	s_add_i32 s76, s73, 0x18000
	buffer_load_dwordx4 v132, s[12:15], s73 offen lds
	s_mov_b32 m0, s43
	s_nop 0
	buffer_load_dwordx4 v132, s[12:15], s76 offen lds
	s_waitcnt vmcnt(8) lgkmcnt(0)
	s_setprio 1
	v_mfma_f32_16x16x32_bf16 v[62:65], v[140:143], v[176:179], v[62:65]
	s_barrier
	v_mfma_f32_16x16x32_bf16 v[62:65], v[148:151], v[180:183], v[62:65]
	v_mfma_f32_16x16x32_bf16 v[58:61], v[152:155], v[176:179], v[58:61]
	v_mfma_f32_16x16x32_bf16 v[58:61], v[156:159], v[180:183], v[58:61]
	v_mfma_f32_16x16x32_bf16 v[54:57], v[160:163], v[176:179], v[54:57]
	v_mfma_f32_16x16x32_bf16 v[54:57], v[164:167], v[180:183], v[54:57]
	v_mfma_f32_16x16x32_bf16 v[50:53], v[168:171], v[176:179], v[50:53]
	v_mfma_f32_16x16x32_bf16 v[50:53], v[172:175], v[180:183], v[50:53]
	v_mfma_f32_16x16x32_bf16 v[34:37], v[168:171], v[184:187], v[34:37]
	v_mfma_f32_16x16x32_bf16 v[34:37], v[172:175], v[188:191], v[34:37]
	v_mfma_f32_16x16x32_bf16 v[38:41], v[160:163], v[184:187], v[38:41]
	v_mfma_f32_16x16x32_bf16 v[38:41], v[164:167], v[188:191], v[38:41]
	v_mfma_f32_16x16x32_bf16 v[42:45], v[152:155], v[184:187], v[42:45]
	v_mfma_f32_16x16x32_bf16 v[42:45], v[156:159], v[188:191], v[42:45]
	v_mfma_f32_16x16x32_bf16 v[46:49], v[140:143], v[184:187], v[46:49]
	v_mfma_f32_16x16x32_bf16 v[46:49], v[148:151], v[188:191], v[46:49]
	v_mfma_f32_16x16x32_bf16 v[30:33], v[140:143], v[192:195], v[30:33]
	v_mfma_f32_16x16x32_bf16 v[30:33], v[148:151], v[196:199], v[30:33]
	v_mfma_f32_16x16x32_bf16 v[26:29], v[152:155], v[192:195], v[26:29]
	v_mfma_f32_16x16x32_bf16 v[26:29], v[156:159], v[196:199], v[26:29]
	v_mfma_f32_16x16x32_bf16 v[22:25], v[160:163], v[192:195], v[22:25]
	v_mfma_f32_16x16x32_bf16 v[22:25], v[164:167], v[196:199], v[22:25]
	v_mfma_f32_16x16x32_bf16 v[18:21], v[168:171], v[192:195], v[18:21]
	v_mfma_f32_16x16x32_bf16 v[18:21], v[172:175], v[196:199], v[18:21]
	v_mfma_f32_16x16x32_bf16 v[2:5], v[168:171], v[200:203], v[2:5]
	v_mfma_f32_16x16x32_bf16 v[2:5], v[172:175], v[204:207], v[2:5]
	v_mfma_f32_16x16x32_bf16 v[6:9], v[160:163], v[200:203], v[6:9]
	v_mfma_f32_16x16x32_bf16 v[6:9], v[164:167], v[204:207], v[6:9]
	v_mfma_f32_16x16x32_bf16 v[10:13], v[152:155], v[200:203], v[10:13]
	v_mfma_f32_16x16x32_bf16 v[10:13], v[156:159], v[204:207], v[10:13]
	v_mfma_f32_16x16x32_bf16 v[14:17], v[140:143], v[200:203], v[14:17]
	v_mfma_f32_16x16x32_bf16 v[14:17], v[148:151], v[204:207], v[14:17]
	s_setprio 0
	s_barrier
	ds_read_b128 v[140:143], v137
	ds_read_b128 v[148:151], v137 offset:1024
	ds_read_b128 v[152:155], v137 offset:2048
	ds_read_b128 v[156:159], v137 offset:3072
	ds_read_b128 v[160:163], v138
	ds_read_b128 v[164:167], v138 offset:1024
	ds_read_b128 v[168:171], v138 offset:2048
	ds_read_b128 v[172:175], v138 offset:3072
	s_mov_b32 m0, s44
	s_add_i32 s76, s73, 0x30000
	ds_read_b128 v[176:179], v136 offset:32768
	ds_read_b128 v[180:183], v136 offset:33792
	ds_read_b128 v[184:187], v136 offset:34816
	ds_read_b128 v[188:191], v136 offset:35840
	ds_read_b128 v[192:195], v136 offset:36864
	ds_read_b128 v[196:199], v136 offset:37888
	ds_read_b128 v[200:203], v136 offset:38912
	ds_read_b128 v[204:207], v136 offset:39936
	buffer_load_dwordx4 v132, s[12:15], s76 offen lds
	s_mov_b32 m0, s45
	s_add_i32 s76, s73, 0x48000
	buffer_load_dwordx4 v132, s[12:15], s76 offen lds
	s_waitcnt vmcnt(8) lgkmcnt(0)
	s_setprio 1
	v_mfma_f32_16x16x32_bf16 v[126:129], v[140:143], v[176:179], v[126:129]
	s_barrier
	v_mfma_f32_16x16x32_bf16 v[126:129], v[148:151], v[180:183], v[126:129]
	v_mfma_f32_16x16x32_bf16 v[122:125], v[152:155], v[176:179], v[122:125]
	v_mfma_f32_16x16x32_bf16 v[122:125], v[156:159], v[180:183], v[122:125]
	v_mfma_f32_16x16x32_bf16 v[118:121], v[160:163], v[176:179], v[118:121]
	v_mfma_f32_16x16x32_bf16 v[118:121], v[164:167], v[180:183], v[118:121]
	v_mfma_f32_16x16x32_bf16 v[114:117], v[168:171], v[176:179], v[114:117]
	v_mfma_f32_16x16x32_bf16 v[114:117], v[172:175], v[180:183], v[114:117]
	v_mfma_f32_16x16x32_bf16 v[98:101], v[168:171], v[184:187], v[98:101]
	v_mfma_f32_16x16x32_bf16 v[98:101], v[172:175], v[188:191], v[98:101]
	v_mfma_f32_16x16x32_bf16 v[102:105], v[160:163], v[184:187], v[102:105]
	v_mfma_f32_16x16x32_bf16 v[102:105], v[164:167], v[188:191], v[102:105]
	v_mfma_f32_16x16x32_bf16 v[106:109], v[152:155], v[184:187], v[106:109]
	v_mfma_f32_16x16x32_bf16 v[106:109], v[156:159], v[188:191], v[106:109]
	v_mfma_f32_16x16x32_bf16 v[110:113], v[140:143], v[184:187], v[110:113]
	v_mfma_f32_16x16x32_bf16 v[110:113], v[148:151], v[188:191], v[110:113]
	v_mfma_f32_16x16x32_bf16 v[94:97], v[140:143], v[192:195], v[94:97]
	v_mfma_f32_16x16x32_bf16 v[94:97], v[148:151], v[196:199], v[94:97]
	v_mfma_f32_16x16x32_bf16 v[90:93], v[152:155], v[192:195], v[90:93]
	v_mfma_f32_16x16x32_bf16 v[90:93], v[156:159], v[196:199], v[90:93]
	v_mfma_f32_16x16x32_bf16 v[86:89], v[160:163], v[192:195], v[86:89]
	v_mfma_f32_16x16x32_bf16 v[86:89], v[164:167], v[196:199], v[86:89]
	v_mfma_f32_16x16x32_bf16 v[82:85], v[168:171], v[192:195], v[82:85]
	v_mfma_f32_16x16x32_bf16 v[82:85], v[172:175], v[196:199], v[82:85]
	v_mfma_f32_16x16x32_bf16 v[66:69], v[168:171], v[200:203], v[66:69]
	v_mfma_f32_16x16x32_bf16 v[66:69], v[172:175], v[204:207], v[66:69]
	v_mfma_f32_16x16x32_bf16 v[70:73], v[160:163], v[200:203], v[70:73]
	v_mfma_f32_16x16x32_bf16 v[70:73], v[164:167], v[204:207], v[70:73]
	v_mfma_f32_16x16x32_bf16 v[74:77], v[152:155], v[200:203], v[74:77]
	v_mfma_f32_16x16x32_bf16 v[74:77], v[156:159], v[204:207], v[74:77]
	v_mfma_f32_16x16x32_bf16 v[78:81], v[140:143], v[200:203], v[78:81]
	v_mfma_f32_16x16x32_bf16 v[78:81], v[148:151], v[204:207], v[78:81]
	s_setprio 0
	s_barrier
	ds_read_b128 v[176:179], v136 offset:49152
	ds_read_b128 v[180:183], v136 offset:50176
	ds_read_b128 v[184:187], v136 offset:51200
	ds_read_b128 v[188:191], v136 offset:52224
	ds_read_b128 v[192:195], v136 offset:53248
	ds_read_b128 v[196:199], v136 offset:54272
	ds_read_b128 v[200:203], v136 offset:55296
	ds_read_b128 v[204:207], v136 offset:56320
	s_mov_b32 m0, s46
	s_add_i32 s76, s75, 0x80
	buffer_load_dwordx4 v133, s[16:19], s76 offen lds
	s_add_i32 s76, s75, 0x200080
	s_mov_b32 m0, s47
	s_add_i32 s73, s73, 0x18080
	buffer_load_dwordx4 v133, s[16:19], s76 offen lds
	s_add_i32 s76, s75, 0x400080
	s_mov_b32 m0, s50
	s_add_i32 s75, s75, 0x600080
	buffer_load_dwordx4 v133, s[16:19], s76 offen lds
	s_mov_b32 m0, s51
	s_nop 0
	buffer_load_dwordx4 v133, s[16:19], s75 offen lds
	s_mov_b32 m0, s48
	s_nop 0
	buffer_load_dwordx4 v132, s[12:15], s74 offen lds
	s_mov_b32 m0, s49
	s_nop 0
	buffer_load_dwordx4 v132, s[12:15], s73 offen lds
	s_waitcnt vmcnt(8) lgkmcnt(0)
	s_setprio 1
	v_mfma_f32_16x16x32_bf16 v[62:65], v[140:143], v[176:179], v[62:65]
	s_barrier
	v_mfma_f32_16x16x32_bf16 v[62:65], v[148:151], v[180:183], v[62:65]
	v_mfma_f32_16x16x32_bf16 v[58:61], v[152:155], v[176:179], v[58:61]
	v_mfma_f32_16x16x32_bf16 v[58:61], v[156:159], v[180:183], v[58:61]
	v_mfma_f32_16x16x32_bf16 v[54:57], v[160:163], v[176:179], v[54:57]
	v_mfma_f32_16x16x32_bf16 v[54:57], v[164:167], v[180:183], v[54:57]
	v_mfma_f32_16x16x32_bf16 v[50:53], v[168:171], v[176:179], v[50:53]
	v_mfma_f32_16x16x32_bf16 v[50:53], v[172:175], v[180:183], v[50:53]
	v_mfma_f32_16x16x32_bf16 v[34:37], v[168:171], v[184:187], v[34:37]
	v_mfma_f32_16x16x32_bf16 v[34:37], v[172:175], v[188:191], v[34:37]
	v_mfma_f32_16x16x32_bf16 v[38:41], v[160:163], v[184:187], v[38:41]
	v_mfma_f32_16x16x32_bf16 v[38:41], v[164:167], v[188:191], v[38:41]
	v_mfma_f32_16x16x32_bf16 v[42:45], v[152:155], v[184:187], v[42:45]
	v_mfma_f32_16x16x32_bf16 v[42:45], v[156:159], v[188:191], v[42:45]
	v_mfma_f32_16x16x32_bf16 v[46:49], v[140:143], v[184:187], v[46:49]
	v_mfma_f32_16x16x32_bf16 v[46:49], v[148:151], v[188:191], v[46:49]
	v_mfma_f32_16x16x32_bf16 v[30:33], v[140:143], v[192:195], v[30:33]
	v_mfma_f32_16x16x32_bf16 v[30:33], v[148:151], v[196:199], v[30:33]
	v_mfma_f32_16x16x32_bf16 v[26:29], v[152:155], v[192:195], v[26:29]
	v_mfma_f32_16x16x32_bf16 v[26:29], v[156:159], v[196:199], v[26:29]
	v_mfma_f32_16x16x32_bf16 v[22:25], v[160:163], v[192:195], v[22:25]
	v_mfma_f32_16x16x32_bf16 v[22:25], v[164:167], v[196:199], v[22:25]
	v_mfma_f32_16x16x32_bf16 v[18:21], v[168:171], v[192:195], v[18:21]
	v_mfma_f32_16x16x32_bf16 v[18:21], v[172:175], v[196:199], v[18:21]
	v_mfma_f32_16x16x32_bf16 v[2:5], v[168:171], v[200:203], v[2:5]
	v_mfma_f32_16x16x32_bf16 v[2:5], v[172:175], v[204:207], v[2:5]
	v_mfma_f32_16x16x32_bf16 v[6:9], v[160:163], v[200:203], v[6:9]
	v_mfma_f32_16x16x32_bf16 v[6:9], v[164:167], v[204:207], v[6:9]
	v_mfma_f32_16x16x32_bf16 v[10:13], v[152:155], v[200:203], v[10:13]
	v_mfma_f32_16x16x32_bf16 v[10:13], v[156:159], v[204:207], v[10:13]
	v_mfma_f32_16x16x32_bf16 v[14:17], v[140:143], v[200:203], v[14:17]
	v_mfma_f32_16x16x32_bf16 v[14:17], v[148:151], v[204:207], v[14:17]
	s_setprio 0
	s_barrier
	s_add_i32 s72, s72, 2
	s_addk_i32 s70, 0x100
	s_addk_i32 s71, 0x100
	s_cmp_ge_i32 s72, s21
	s_cbranch_scc0 .LBB0_1035

.LBB0_1050:
	ds_read_b128 v[132:135], v142
	ds_read_b128 v[136:139], v142 offset:1024
	ds_read_b128 v[148:151], v142 offset:2048
	ds_read_b128 v[152:155], v142 offset:3072
	ds_read_b128 v[156:159], v143
	ds_read_b128 v[160:163], v143 offset:1024
	ds_read_b128 v[164:167], v143 offset:2048
	ds_read_b128 v[168:171], v143 offset:3072
	s_add_i32 s18, s61, 0xfff40080
	s_cmp_eq_u32 s54, s62
	s_cselect_b32 s64, s35, s18
	s_add_i32 s63, s64, 0x80
	s_add_i32 s18, s61, 0xfffc0000
	s_mov_b32 m0, s55
	ds_read_b128 v[172:175], v144
	ds_read_b128 v[176:179], v144 offset:1024
	ds_read_b128 v[180:183], v144 offset:2048
	ds_read_b128 v[184:187], v144 offset:3072
	ds_read_b128 v[188:191], v144 offset:4096
	ds_read_b128 v[192:195], v144 offset:5120
	ds_read_b128 v[196:199], v144 offset:6144
	ds_read_b128 v[200:203], v144 offset:7168
	buffer_load_dwordx4 v140, s[12:15], s18 offen lds
	s_mov_b32 m0, s56
	s_nop 0
	buffer_load_dwordx4 v140, s[12:15], s61 offen lds
	s_waitcnt vmcnt(8) lgkmcnt(0)
	s_setprio 1
	v_mfma_f32_16x16x32_bf16 v[126:129], v[132:135], v[172:175], v[126:129]
	s_barrier
	v_mfma_f32_16x16x32_bf16 v[126:129], v[136:139], v[176:179], v[126:129]
	v_mfma_f32_16x16x32_bf16 v[122:125], v[148:151], v[172:175], v[122:125]
	v_mfma_f32_16x16x32_bf16 v[122:125], v[152:155], v[176:179], v[122:125]
	v_mfma_f32_16x16x32_bf16 v[118:121], v[156:159], v[172:175], v[118:121]
	v_mfma_f32_16x16x32_bf16 v[118:121], v[160:163], v[176:179], v[118:121]
	v_mfma_f32_16x16x32_bf16 v[114:117], v[164:167], v[172:175], v[114:117]
	v_mfma_f32_16x16x32_bf16 v[114:117], v[168:171], v[176:179], v[114:117]
	v_mfma_f32_16x16x32_bf16 v[98:101], v[164:167], v[180:183], v[98:101]
	v_mfma_f32_16x16x32_bf16 v[98:101], v[168:171], v[184:187], v[98:101]
	v_mfma_f32_16x16x32_bf16 v[102:105], v[156:159], v[180:183], v[102:105]
	v_mfma_f32_16x16x32_bf16 v[102:105], v[160:163], v[184:187], v[102:105]
	v_mfma_f32_16x16x32_bf16 v[106:109], v[148:151], v[180:183], v[106:109]
	v_mfma_f32_16x16x32_bf16 v[106:109], v[152:155], v[184:187], v[106:109]
	v_mfma_f32_16x16x32_bf16 v[110:113], v[132:135], v[180:183], v[110:113]
	v_mfma_f32_16x16x32_bf16 v[110:113], v[136:139], v[184:187], v[110:113]
	v_mfma_f32_16x16x32_bf16 v[94:97], v[132:135], v[188:191], v[94:97]
	v_mfma_f32_16x16x32_bf16 v[94:97], v[136:139], v[192:195], v[94:97]
	v_mfma_f32_16x16x32_bf16 v[90:93], v[148:151], v[188:191], v[90:93]
	v_mfma_f32_16x16x32_bf16 v[90:93], v[152:155], v[192:195], v[90:93]
	v_mfma_f32_16x16x32_bf16 v[86:89], v[156:159], v[188:191], v[86:89]
	v_mfma_f32_16x16x32_bf16 v[86:89], v[160:163], v[192:195], v[86:89]
	v_mfma_f32_16x16x32_bf16 v[82:85], v[164:167], v[188:191], v[82:85]
	v_mfma_f32_16x16x32_bf16 v[82:85], v[168:171], v[192:195], v[82:85]
	v_mfma_f32_16x16x32_bf16 v[66:69], v[164:167], v[196:199], v[66:69]
	v_mfma_f32_16x16x32_bf16 v[66:69], v[168:171], v[200:203], v[66:69]
	v_mfma_f32_16x16x32_bf16 v[70:73], v[156:159], v[196:199], v[70:73]
	v_mfma_f32_16x16x32_bf16 v[70:73], v[160:163], v[200:203], v[70:73]
	v_mfma_f32_16x16x32_bf16 v[74:77], v[148:151], v[196:199], v[74:77]
	v_mfma_f32_16x16x32_bf16 v[74:77], v[152:155], v[200:203], v[74:77]
	v_mfma_f32_16x16x32_bf16 v[78:81], v[132:135], v[196:199], v[78:81]
	v_mfma_f32_16x16x32_bf16 v[78:81], v[136:139], v[200:203], v[78:81]
	s_setprio 0
	s_barrier
	ds_read_b128 v[172:175], v144 offset:16384
	ds_read_b128 v[176:179], v144 offset:17408
	ds_read_b128 v[180:183], v144 offset:18432
	ds_read_b128 v[184:187], v144 offset:19456
	ds_read_b128 v[188:191], v144 offset:20480
	ds_read_b128 v[192:195], v144 offset:21504
	ds_read_b128 v[196:199], v144 offset:22528
	ds_read_b128 v[200:203], v144 offset:23552
	s_mov_b32 m0, s25
	s_mov_b32 s18, s14
	s_mov_b32 s19, s15
	buffer_load_dwordx4 v141, s[16:19], s64 offen lds
	s_add_i32 s65, s64, 0x40000
	s_mov_b32 m0, s27
	s_add_i32 s66, s64, 0x80000
	buffer_load_dwordx4 v141, s[16:19], s65 offen lds
	s_mov_b32 m0, s30
	s_add_i32 s67, s64, 0xc0000
	buffer_load_dwordx4 v141, s[16:19], s66 offen lds
	s_mov_b32 m0, s31
	s_nop 0
	buffer_load_dwordx4 v141, s[16:19], s67 offen lds
	s_mov_b32 m0, s21
	s_nop 0
	buffer_load_dwordx4 v140, s[12:15], s64 offen lds
	s_mov_b32 m0, s38
	s_nop 0
	buffer_load_dwordx4 v140, s[12:15], s65 offen lds
	s_waitcnt vmcnt(8) lgkmcnt(0)
	s_setprio 1
	v_mfma_f32_16x16x32_bf16 v[62:65], v[132:135], v[172:175], v[62:65]
	s_barrier
	v_mfma_f32_16x16x32_bf16 v[62:65], v[136:139], v[176:179], v[62:65]
	v_mfma_f32_16x16x32_bf16 v[58:61], v[148:151], v[172:175], v[58:61]
	v_mfma_f32_16x16x32_bf16 v[58:61], v[152:155], v[176:179], v[58:61]
	v_mfma_f32_16x16x32_bf16 v[54:57], v[156:159], v[172:175], v[54:57]
	v_mfma_f32_16x16x32_bf16 v[54:57], v[160:163], v[176:179], v[54:57]
	v_mfma_f32_16x16x32_bf16 v[50:53], v[164:167], v[172:175], v[50:53]
	v_mfma_f32_16x16x32_bf16 v[50:53], v[168:171], v[176:179], v[50:53]
	v_mfma_f32_16x16x32_bf16 v[34:37], v[164:167], v[180:183], v[34:37]
	v_mfma_f32_16x16x32_bf16 v[34:37], v[168:171], v[184:187], v[34:37]
	v_mfma_f32_16x16x32_bf16 v[38:41], v[156:159], v[180:183], v[38:41]
	v_mfma_f32_16x16x32_bf16 v[38:41], v[160:163], v[184:187], v[38:41]
	v_mfma_f32_16x16x32_bf16 v[42:45], v[148:151], v[180:183], v[42:45]
	v_mfma_f32_16x16x32_bf16 v[42:45], v[152:155], v[184:187], v[42:45]
	v_mfma_f32_16x16x32_bf16 v[46:49], v[132:135], v[180:183], v[46:49]
	v_mfma_f32_16x16x32_bf16 v[46:49], v[136:139], v[184:187], v[46:49]
	v_mfma_f32_16x16x32_bf16 v[30:33], v[132:135], v[188:191], v[30:33]
	v_mfma_f32_16x16x32_bf16 v[30:33], v[136:139], v[192:195], v[30:33]
	v_mfma_f32_16x16x32_bf16 v[26:29], v[148:151], v[188:191], v[26:29]
	v_mfma_f32_16x16x32_bf16 v[26:29], v[152:155], v[192:195], v[26:29]
	v_mfma_f32_16x16x32_bf16 v[22:25], v[156:159], v[188:191], v[22:25]
	v_mfma_f32_16x16x32_bf16 v[22:25], v[160:163], v[192:195], v[22:25]
	v_mfma_f32_16x16x32_bf16 v[18:21], v[164:167], v[188:191], v[18:21]
	v_mfma_f32_16x16x32_bf16 v[18:21], v[168:171], v[192:195], v[18:21]
	v_mfma_f32_16x16x32_bf16 v[2:5], v[164:167], v[196:199], v[2:5]
	v_mfma_f32_16x16x32_bf16 v[2:5], v[168:171], v[200:203], v[2:5]
	v_mfma_f32_16x16x32_bf16 v[6:9], v[156:159], v[196:199], v[6:9]
	v_mfma_f32_16x16x32_bf16 v[6:9], v[160:163], v[200:203], v[6:9]
	v_mfma_f32_16x16x32_bf16 v[10:13], v[148:151], v[196:199], v[10:13]
	v_mfma_f32_16x16x32_bf16 v[10:13], v[152:155], v[200:203], v[10:13]
	v_mfma_f32_16x16x32_bf16 v[14:17], v[132:135], v[196:199], v[14:17]
	v_mfma_f32_16x16x32_bf16 v[14:17], v[136:139], v[200:203], v[14:17]
	s_setprio 0
	s_barrier
	ds_read_b128 v[132:135], v145
	ds_read_b128 v[136:139], v145 offset:1024
	ds_read_b128 v[148:151], v145 offset:2048
	ds_read_b128 v[152:155], v145 offset:3072
	ds_read_b128 v[156:159], v147
	ds_read_b128 v[160:163], v147 offset:1024
	ds_read_b128 v[164:167], v147 offset:2048
	ds_read_b128 v[168:171], v147 offset:3072
	s_mov_b32 m0, s39
	ds_read_b128 v[172:175], v144 offset:32768
	ds_read_b128 v[176:179], v144 offset:33792
	ds_read_b128 v[180:183], v144 offset:34816
	ds_read_b128 v[184:187], v144 offset:35840
	ds_read_b128 v[188:191], v144 offset:36864
	ds_read_b128 v[192:195], v144 offset:37888
	ds_read_b128 v[196:199], v144 offset:38912
	ds_read_b128 v[200:203], v144 offset:39936
	buffer_load_dwordx4 v140, s[12:15], s66 offen lds
	s_mov_b32 m0, s40
	s_nop 0
	buffer_load_dwordx4 v140, s[12:15], s67 offen lds
	s_waitcnt vmcnt(8) lgkmcnt(0)
	s_setprio 1
	v_mfma_f32_16x16x32_bf16 v[126:129], v[132:135], v[172:175], v[126:129]
	s_barrier
	v_mfma_f32_16x16x32_bf16 v[126:129], v[136:139], v[176:179], v[126:129]
	v_mfma_f32_16x16x32_bf16 v[122:125], v[148:151], v[172:175], v[122:125]
	v_mfma_f32_16x16x32_bf16 v[122:125], v[152:155], v[176:179], v[122:125]
	v_mfma_f32_16x16x32_bf16 v[118:121], v[156:159], v[172:175], v[118:121]
	v_mfma_f32_16x16x32_bf16 v[118:121], v[160:163], v[176:179], v[118:121]
	v_mfma_f32_16x16x32_bf16 v[114:117], v[164:167], v[172:175], v[114:117]
	v_mfma_f32_16x16x32_bf16 v[114:117], v[168:171], v[176:179], v[114:117]
	v_mfma_f32_16x16x32_bf16 v[98:101], v[164:167], v[180:183], v[98:101]
	v_mfma_f32_16x16x32_bf16 v[98:101], v[168:171], v[184:187], v[98:101]
	v_mfma_f32_16x16x32_bf16 v[102:105], v[156:159], v[180:183], v[102:105]
	v_mfma_f32_16x16x32_bf16 v[102:105], v[160:163], v[184:187], v[102:105]
	v_mfma_f32_16x16x32_bf16 v[106:109], v[148:151], v[180:183], v[106:109]
	v_mfma_f32_16x16x32_bf16 v[106:109], v[152:155], v[184:187], v[106:109]
	v_mfma_f32_16x16x32_bf16 v[110:113], v[132:135], v[180:183], v[110:113]
	v_mfma_f32_16x16x32_bf16 v[110:113], v[136:139], v[184:187], v[110:113]
	v_mfma_f32_16x16x32_bf16 v[94:97], v[132:135], v[188:191], v[94:97]
	v_mfma_f32_16x16x32_bf16 v[94:97], v[136:139], v[192:195], v[94:97]
	v_mfma_f32_16x16x32_bf16 v[90:93], v[148:151], v[188:191], v[90:93]
	v_mfma_f32_16x16x32_bf16 v[90:93], v[152:155], v[192:195], v[90:93]
	v_mfma_f32_16x16x32_bf16 v[86:89], v[156:159], v[188:191], v[86:89]
	v_mfma_f32_16x16x32_bf16 v[86:89], v[160:163], v[192:195], v[86:89]
	v_mfma_f32_16x16x32_bf16 v[82:85], v[164:167], v[188:191], v[82:85]
	v_mfma_f32_16x16x32_bf16 v[82:85], v[168:171], v[192:195], v[82:85]
	v_mfma_f32_16x16x32_bf16 v[66:69], v[164:167], v[196:199], v[66:69]
	v_mfma_f32_16x16x32_bf16 v[66:69], v[168:171], v[200:203], v[66:69]
	v_mfma_f32_16x16x32_bf16 v[70:73], v[156:159], v[196:199], v[70:73]
	v_mfma_f32_16x16x32_bf16 v[70:73], v[160:163], v[200:203], v[70:73]
	v_mfma_f32_16x16x32_bf16 v[74:77], v[148:151], v[196:199], v[74:77]
	v_mfma_f32_16x16x32_bf16 v[74:77], v[152:155], v[200:203], v[74:77]
	v_mfma_f32_16x16x32_bf16 v[78:81], v[132:135], v[196:199], v[78:81]
	v_mfma_f32_16x16x32_bf16 v[78:81], v[136:139], v[200:203], v[78:81]
	s_setprio 0
	s_barrier
	ds_read_b128 v[172:175], v144 offset:49152
	ds_read_b128 v[176:179], v144 offset:50176
	ds_read_b128 v[180:183], v144 offset:51200
	ds_read_b128 v[184:187], v144 offset:52224
	ds_read_b128 v[188:191], v144 offset:53248
	ds_read_b128 v[192:195], v144 offset:54272
	ds_read_b128 v[196:199], v144 offset:55296
	ds_read_b128 v[200:203], v144 offset:56320
	s_mov_b32 m0, s48
	s_nop 0
	buffer_load_dwordx4 v141, s[16:19], s63 offen lds
	s_add_i32 s65, s64, 0x40080
	s_mov_b32 m0, s49
	s_add_i32 s66, s64, 0x80080
	buffer_load_dwordx4 v141, s[16:19], s65 offen lds
	s_mov_b32 m0, s52
	s_add_i32 s64, s64, 0xc0080
	buffer_load_dwordx4 v141, s[16:19], s66 offen lds
	s_mov_b32 m0, s53
	s_nop 0
	buffer_load_dwordx4 v141, s[16:19], s64 offen lds
	s_mov_b32 m0, s50
	s_nop 0
	buffer_load_dwordx4 v140, s[12:15], s63 offen lds
	s_mov_b32 m0, s51
	s_nop 0
	buffer_load_dwordx4 v140, s[12:15], s65 offen lds
	s_waitcnt vmcnt(8) lgkmcnt(0)
	s_setprio 1
	v_mfma_f32_16x16x32_bf16 v[62:65], v[132:135], v[172:175], v[62:65]
	s_barrier
	v_mfma_f32_16x16x32_bf16 v[62:65], v[136:139], v[176:179], v[62:65]
	v_mfma_f32_16x16x32_bf16 v[58:61], v[148:151], v[172:175], v[58:61]
	v_mfma_f32_16x16x32_bf16 v[58:61], v[152:155], v[176:179], v[58:61]
	v_mfma_f32_16x16x32_bf16 v[54:57], v[156:159], v[172:175], v[54:57]
	v_mfma_f32_16x16x32_bf16 v[54:57], v[160:163], v[176:179], v[54:57]
	v_mfma_f32_16x16x32_bf16 v[50:53], v[164:167], v[172:175], v[50:53]
	v_mfma_f32_16x16x32_bf16 v[50:53], v[168:171], v[176:179], v[50:53]
	v_mfma_f32_16x16x32_bf16 v[34:37], v[164:167], v[180:183], v[34:37]
	v_mfma_f32_16x16x32_bf16 v[34:37], v[168:171], v[184:187], v[34:37]
	v_mfma_f32_16x16x32_bf16 v[38:41], v[156:159], v[180:183], v[38:41]
	v_mfma_f32_16x16x32_bf16 v[38:41], v[160:163], v[184:187], v[38:41]
	v_mfma_f32_16x16x32_bf16 v[42:45], v[148:151], v[180:183], v[42:45]
	v_mfma_f32_16x16x32_bf16 v[42:45], v[152:155], v[184:187], v[42:45]
	v_mfma_f32_16x16x32_bf16 v[46:49], v[132:135], v[180:183], v[46:49]
	v_mfma_f32_16x16x32_bf16 v[46:49], v[136:139], v[184:187], v[46:49]
	v_mfma_f32_16x16x32_bf16 v[30:33], v[132:135], v[188:191], v[30:33]
	v_mfma_f32_16x16x32_bf16 v[30:33], v[136:139], v[192:195], v[30:33]
	v_mfma_f32_16x16x32_bf16 v[26:29], v[148:151], v[188:191], v[26:29]
	v_mfma_f32_16x16x32_bf16 v[26:29], v[152:155], v[192:195], v[26:29]
	v_mfma_f32_16x16x32_bf16 v[22:25], v[156:159], v[188:191], v[22:25]
	v_mfma_f32_16x16x32_bf16 v[22:25], v[160:163], v[192:195], v[22:25]
	v_mfma_f32_16x16x32_bf16 v[18:21], v[164:167], v[188:191], v[18:21]
	v_mfma_f32_16x16x32_bf16 v[18:21], v[168:171], v[192:195], v[18:21]
	v_mfma_f32_16x16x32_bf16 v[2:5], v[164:167], v[196:199], v[2:5]
	v_mfma_f32_16x16x32_bf16 v[2:5], v[168:171], v[200:203], v[2:5]
	v_mfma_f32_16x16x32_bf16 v[6:9], v[156:159], v[196:199], v[6:9]
	v_mfma_f32_16x16x32_bf16 v[6:9], v[160:163], v[200:203], v[6:9]
	v_mfma_f32_16x16x32_bf16 v[10:13], v[148:151], v[196:199], v[10:13]
	v_mfma_f32_16x16x32_bf16 v[10:13], v[152:155], v[200:203], v[10:13]
	v_mfma_f32_16x16x32_bf16 v[14:17], v[132:135], v[196:199], v[14:17]
	v_mfma_f32_16x16x32_bf16 v[14:17], v[136:139], v[200:203], v[14:17]
	s_setprio 0
	s_barrier
	s_add_i32 s62, s62, 2
	s_addk_i32 s61, 0x100
	s_cmp_ge_i32 s62, s3
	s_cbranch_scc0 .LBB0_1050

.LBB0_1181:
	v_add_u32_e32 v2, 0x10000, v232
	ds_read_b128 v[134:137], v2
	ds_read_b128 v[138:141], v2 offset:1024
	ds_read_b128 v[142:145], v2 offset:2048
	ds_read_b128 v[146:149], v2 offset:3072
	v_add_u32_e32 v2, 0x14000, v232
	ds_read_b128 v[150:153], v2
	ds_read_b128 v[154:157], v2 offset:1024
	ds_read_b128 v[158:161], v2 offset:2048
	ds_read_b128 v[162:165], v2 offset:3072
	s_add_i32 s50, s47, s90
	s_and_b64 s[18:19], exec, s[18:19]
	s_cselect_b32 s51, s88, s50
	s_add_i32 s50, s92, 0x80
	s_or_b32 s52, s51, 0x80
	s_add_i32 s18, s89, s93
	s_add_i32 s94, s94, 0x1bfffc80
	s_cmp_lt_u32 s91, 8
	s_cselect_b32 s18, s18, s94
	s_mov_b32 m0, s74
	s_add_i32 s19, s18, 0x80000
	ds_read_b128 v[166:169], v233
	ds_read_b128 v[170:173], v233 offset:1024
	ds_read_b128 v[174:177], v233 offset:2048
	ds_read_b128 v[178:181], v233 offset:3072
	ds_read_b128 v[182:185], v233 offset:4096
	ds_read_b128 v[186:189], v233 offset:5120
	ds_read_b128 v[190:193], v233 offset:6144
	ds_read_b128 v[194:197], v233 offset:7168
	buffer_load_dwordx4 v230, s[12:15], s19 offen lds
	s_mov_b32 m0, s75
	s_add_i32 s18, s18, 0xc0000
	buffer_load_dwordx4 v230, s[12:15], s18 offen lds
	s_waitcnt vmcnt(8) lgkmcnt(0)
	s_setprio 1
	v_mfma_f32_16x16x32_bf16 v[130:133], v[134:137], v[166:169], v[130:133]
	s_barrier
	v_mfma_f32_16x16x32_bf16 v[130:133], v[138:141], v[170:173], v[130:133]
	v_mfma_f32_16x16x32_bf16 v[126:129], v[142:145], v[166:169], v[126:129]
	v_mfma_f32_16x16x32_bf16 v[126:129], v[146:149], v[170:173], v[126:129]
	v_mfma_f32_16x16x32_bf16 v[122:125], v[150:153], v[166:169], v[122:125]
	v_mfma_f32_16x16x32_bf16 v[122:125], v[154:157], v[170:173], v[122:125]
	v_mfma_f32_16x16x32_bf16 v[118:121], v[158:161], v[166:169], v[118:121]
	v_mfma_f32_16x16x32_bf16 v[118:121], v[162:165], v[170:173], v[118:121]
	v_mfma_f32_16x16x32_bf16 v[102:105], v[158:161], v[174:177], v[102:105]
	v_mfma_f32_16x16x32_bf16 v[102:105], v[162:165], v[178:181], v[102:105]
	v_mfma_f32_16x16x32_bf16 v[106:109], v[150:153], v[174:177], v[106:109]
	v_mfma_f32_16x16x32_bf16 v[106:109], v[154:157], v[178:181], v[106:109]
	v_mfma_f32_16x16x32_bf16 v[110:113], v[142:145], v[174:177], v[110:113]
	v_mfma_f32_16x16x32_bf16 v[110:113], v[146:149], v[178:181], v[110:113]
	v_mfma_f32_16x16x32_bf16 v[114:117], v[134:137], v[174:177], v[114:117]
	v_mfma_f32_16x16x32_bf16 v[114:117], v[138:141], v[178:181], v[114:117]
	v_mfma_f32_16x16x32_bf16 v[98:101], v[134:137], v[182:185], v[98:101]
	v_mfma_f32_16x16x32_bf16 v[98:101], v[138:141], v[186:189], v[98:101]
	v_mfma_f32_16x16x32_bf16 v[94:97], v[142:145], v[182:185], v[94:97]
	v_mfma_f32_16x16x32_bf16 v[94:97], v[146:149], v[186:189], v[94:97]
	v_mfma_f32_16x16x32_bf16 v[90:93], v[150:153], v[182:185], v[90:93]
	v_mfma_f32_16x16x32_bf16 v[90:93], v[154:157], v[186:189], v[90:93]
	v_mfma_f32_16x16x32_bf16 v[86:89], v[158:161], v[182:185], v[86:89]
	v_mfma_f32_16x16x32_bf16 v[86:89], v[162:165], v[186:189], v[86:89]
	v_mfma_f32_16x16x32_bf16 v[70:73], v[158:161], v[190:193], v[70:73]
	v_mfma_f32_16x16x32_bf16 v[70:73], v[162:165], v[194:197], v[70:73]
	v_mfma_f32_16x16x32_bf16 v[74:77], v[150:153], v[190:193], v[74:77]
	v_mfma_f32_16x16x32_bf16 v[74:77], v[154:157], v[194:197], v[74:77]
	v_mfma_f32_16x16x32_bf16 v[78:81], v[142:145], v[190:193], v[78:81]
	v_mfma_f32_16x16x32_bf16 v[78:81], v[146:149], v[194:197], v[78:81]
	v_mfma_f32_16x16x32_bf16 v[82:85], v[134:137], v[190:193], v[82:85]
	v_mfma_f32_16x16x32_bf16 v[82:85], v[138:141], v[194:197], v[82:85]
	s_setprio 0
	s_barrier
	ds_read_b128 v[166:169], v233 offset:16384
	ds_read_b128 v[170:173], v233 offset:17408
	ds_read_b128 v[174:177], v233 offset:18432
	ds_read_b128 v[178:181], v233 offset:19456
	ds_read_b128 v[182:185], v233 offset:20480
	ds_read_b128 v[186:189], v233 offset:21504
	ds_read_b128 v[190:193], v233 offset:22528
	ds_read_b128 v[194:197], v233 offset:23552
	s_mov_b32 m0, s27
	s_mov_b32 s18, s14
	s_mov_b32 s19, s15
	buffer_load_dwordx4 v231, s[16:19], s51 offen lds
	s_mov_b32 m0, s30
	s_add_i32 s53, s51, 0x18000
	buffer_load_dwordx4 v231, s[16:19], s53 offen lds
	s_mov_b32 m0, s31
	s_add_i32 s53, s51, 0x30000
	buffer_load_dwordx4 v231, s[16:19], s53 offen lds
	s_mov_b32 m0, s54
	s_add_i32 s53, s51, 0x48000
	buffer_load_dwordx4 v231, s[16:19], s53 offen lds
	s_mov_b32 m0, s25
	s_add_i32 s53, s92, 0x40000
	buffer_load_dwordx4 v230, s[12:15], s92 offen lds
	s_mov_b32 m0, s55
	s_nop 0
	buffer_load_dwordx4 v230, s[12:15], s53 offen lds
	s_waitcnt vmcnt(8) lgkmcnt(0)
	s_setprio 1
	v_mfma_f32_16x16x32_bf16 v[66:69], v[134:137], v[166:169], v[66:69]
	s_barrier
	v_mfma_f32_16x16x32_bf16 v[62:65], v[142:145], v[166:169], v[62:65]
	v_mfma_f32_16x16x32_bf16 v[50:53], v[134:137], v[174:177], v[50:53]
	v_mfma_f32_16x16x32_bf16 v[46:49], v[142:145], v[174:177], v[46:49]
	v_mfma_f32_16x16x32_bf16 v[34:37], v[134:137], v[182:185], v[34:37]
	v_mfma_f32_16x16x32_bf16 v[30:33], v[142:145], v[182:185], v[30:33]
	v_mfma_f32_16x16x32_bf16 v[18:21], v[134:137], v[190:193], v[18:21]
	v_mfma_f32_16x16x32_bf16 v[14:17], v[142:145], v[190:193], v[14:17]
	v_mfma_f32_16x16x32_bf16 v[58:61], v[150:153], v[166:169], v[58:61]
	v_mfma_f32_16x16x32_bf16 v[54:57], v[158:161], v[166:169], v[54:57]
	v_mfma_f32_16x16x32_bf16 v[42:45], v[150:153], v[174:177], v[42:45]
	v_mfma_f32_16x16x32_bf16 v[38:41], v[158:161], v[174:177], v[38:41]
	v_mfma_f32_16x16x32_bf16 v[26:29], v[150:153], v[182:185], v[26:29]
	v_mfma_f32_16x16x32_bf16 v[22:25], v[158:161], v[182:185], v[22:25]
	v_mfma_f32_16x16x32_bf16 v[10:13], v[150:153], v[190:193], v[10:13]
	v_mfma_f32_16x16x32_bf16 v[4:7], v[158:161], v[190:193], v[6:9]
	v_mfma_f32_16x16x32_bf16 v[66:69], v[138:141], v[170:173], v[66:69]
	v_mfma_f32_16x16x32_bf16 v[62:65], v[146:149], v[170:173], v[62:65]
	v_mfma_f32_16x16x32_bf16 v[50:53], v[138:141], v[178:181], v[50:53]
	v_mfma_f32_16x16x32_bf16 v[46:49], v[146:149], v[178:181], v[46:49]
	v_mfma_f32_16x16x32_bf16 v[34:37], v[138:141], v[186:189], v[34:37]
	v_mfma_f32_16x16x32_bf16 v[30:33], v[146:149], v[186:189], v[30:33]
	v_mfma_f32_16x16x32_bf16 v[18:21], v[138:141], v[194:197], v[18:21]
	v_mfma_f32_16x16x32_bf16 v[14:17], v[146:149], v[194:197], v[14:17]
	v_mfma_f32_16x16x32_bf16 v[58:61], v[154:157], v[170:173], v[58:61]
	v_mfma_f32_16x16x32_bf16 v[54:57], v[162:165], v[170:173], v[54:57]
	v_mfma_f32_16x16x32_bf16 v[42:45], v[154:157], v[178:181], v[42:45]
	v_mfma_f32_16x16x32_bf16 v[38:41], v[162:165], v[178:181], v[38:41]
	v_mfma_f32_16x16x32_bf16 v[26:29], v[154:157], v[186:189], v[26:29]
	v_mfma_f32_16x16x32_bf16 v[22:25], v[162:165], v[186:189], v[22:25]
	v_mfma_f32_16x16x32_bf16 v[10:13], v[154:157], v[194:197], v[10:13]
	v_mfma_f32_16x16x32_bf16 v[4:7], v[162:165], v[194:197], v[4:7]
	s_setprio 0
	s_barrier
	v_add_u32_e32 v2, 0x18000, v232
	ds_read_b128 v[134:137], v2
	ds_read_b128 v[138:141], v2 offset:1024
	ds_read_b128 v[142:145], v2 offset:2048
	ds_read_b128 v[146:149], v2 offset:3072
	v_add_u32_e32 v2, 0x1c000, v232
	ds_read_b128 v[150:153], v2
	ds_read_b128 v[154:157], v2 offset:1024
	ds_read_b128 v[158:161], v2 offset:2048
	ds_read_b128 v[162:165], v2 offset:3072
	s_mov_b32 m0, s56
	s_add_i32 s53, s92, 0x80000
	ds_read_b128 v[166:169], v233 offset:32768
	ds_read_b128 v[170:173], v233 offset:33792
	ds_read_b128 v[174:177], v233 offset:34816
	ds_read_b128 v[178:181], v233 offset:35840
	ds_read_b128 v[182:185], v233 offset:36864
	ds_read_b128 v[186:189], v233 offset:37888
	ds_read_b128 v[190:193], v233 offset:38912
	ds_read_b128 v[194:197], v233 offset:39936
	buffer_load_dwordx4 v230, s[12:15], s53 offen lds
	s_mov_b32 m0, s57
	s_add_i32 s53, s92, 0xc0000
	buffer_load_dwordx4 v230, s[12:15], s53 offen lds
	s_waitcnt vmcnt(8) lgkmcnt(0)
	s_setprio 1
	v_mfma_f32_16x16x32_bf16 v[130:133], v[134:137], v[166:169], v[130:133]
	s_barrier
	v_mfma_f32_16x16x32_bf16 v[130:133], v[138:141], v[170:173], v[130:133]
	v_mfma_f32_16x16x32_bf16 v[126:129], v[142:145], v[166:169], v[126:129]
	v_mfma_f32_16x16x32_bf16 v[126:129], v[146:149], v[170:173], v[126:129]
	v_mfma_f32_16x16x32_bf16 v[122:125], v[150:153], v[166:169], v[122:125]
	v_mfma_f32_16x16x32_bf16 v[122:125], v[154:157], v[170:173], v[122:125]
	v_mfma_f32_16x16x32_bf16 v[118:121], v[158:161], v[166:169], v[118:121]
	v_mfma_f32_16x16x32_bf16 v[118:121], v[162:165], v[170:173], v[118:121]
	v_mfma_f32_16x16x32_bf16 v[102:105], v[158:161], v[174:177], v[102:105]
	v_mfma_f32_16x16x32_bf16 v[102:105], v[162:165], v[178:181], v[102:105]
	v_mfma_f32_16x16x32_bf16 v[106:109], v[150:153], v[174:177], v[106:109]
	v_mfma_f32_16x16x32_bf16 v[106:109], v[154:157], v[178:181], v[106:109]
	v_mfma_f32_16x16x32_bf16 v[110:113], v[142:145], v[174:177], v[110:113]
	v_mfma_f32_16x16x32_bf16 v[110:113], v[146:149], v[178:181], v[110:113]
	v_mfma_f32_16x16x32_bf16 v[114:117], v[134:137], v[174:177], v[114:117]
	v_mfma_f32_16x16x32_bf16 v[114:117], v[138:141], v[178:181], v[114:117]
	v_mfma_f32_16x16x32_bf16 v[98:101], v[134:137], v[182:185], v[98:101]
	v_mfma_f32_16x16x32_bf16 v[98:101], v[138:141], v[186:189], v[98:101]
	v_mfma_f32_16x16x32_bf16 v[94:97], v[142:145], v[182:185], v[94:97]
	v_mfma_f32_16x16x32_bf16 v[94:97], v[146:149], v[186:189], v[94:97]
	v_mfma_f32_16x16x32_bf16 v[90:93], v[150:153], v[182:185], v[90:93]
	v_mfma_f32_16x16x32_bf16 v[90:93], v[154:157], v[186:189], v[90:93]
	v_mfma_f32_16x16x32_bf16 v[86:89], v[158:161], v[182:185], v[86:89]
	v_mfma_f32_16x16x32_bf16 v[86:89], v[162:165], v[186:189], v[86:89]
	v_mfma_f32_16x16x32_bf16 v[70:73], v[158:161], v[190:193], v[70:73]
	v_mfma_f32_16x16x32_bf16 v[70:73], v[162:165], v[194:197], v[70:73]
	v_mfma_f32_16x16x32_bf16 v[74:77], v[150:153], v[190:193], v[74:77]
	v_mfma_f32_16x16x32_bf16 v[74:77], v[154:157], v[194:197], v[74:77]
	v_mfma_f32_16x16x32_bf16 v[78:81], v[142:145], v[190:193], v[78:81]
	v_mfma_f32_16x16x32_bf16 v[78:81], v[146:149], v[194:197], v[78:81]
	v_mfma_f32_16x16x32_bf16 v[82:85], v[134:137], v[190:193], v[82:85]
	v_mfma_f32_16x16x32_bf16 v[82:85], v[138:141], v[194:197], v[82:85]
	s_setprio 0
	s_barrier
	ds_read_b128 v[166:169], v233 offset:49152
	ds_read_b128 v[170:173], v233 offset:50176
	ds_read_b128 v[174:177], v233 offset:51200
	ds_read_b128 v[178:181], v233 offset:52224
	ds_read_b128 v[182:185], v233 offset:53248
	ds_read_b128 v[186:189], v233 offset:54272
	ds_read_b128 v[190:193], v233 offset:55296
	ds_read_b128 v[194:197], v233 offset:56320
	s_mov_b32 m0, s64
	s_nop 0
	buffer_load_dwordx4 v231, s[16:19], s52 offen lds
	s_mov_b32 m0, s65
	s_add_i32 s52, s51, 0x18080
	buffer_load_dwordx4 v231, s[16:19], s52 offen lds
	s_add_i32 s52, s51, 0x30080
	s_mov_b32 m0, s68
	s_add_i32 s51, s51, 0x48080
	buffer_load_dwordx4 v231, s[16:19], s52 offen lds
	s_mov_b32 m0, s69
	s_nop 0
	buffer_load_dwordx4 v231, s[16:19], s51 offen lds
	s_mov_b32 m0, s66
	s_add_i32 s18, s92, 0x40080
	buffer_load_dwordx4 v230, s[12:15], s50 offen lds
	s_mov_b32 m0, s67
	s_nop 0
	buffer_load_dwordx4 v230, s[12:15], s18 offen lds
	s_waitcnt vmcnt(8) lgkmcnt(0)
	s_setprio 1
	v_mfma_f32_16x16x32_bf16 v[66:69], v[134:137], v[166:169], v[66:69]
	s_barrier
	v_mfma_f32_16x16x32_bf16 v[62:65], v[142:145], v[166:169], v[62:65]
	v_mfma_f32_16x16x32_bf16 v[50:53], v[134:137], v[174:177], v[50:53]
	v_mfma_f32_16x16x32_bf16 v[46:49], v[142:145], v[174:177], v[46:49]
	v_mfma_f32_16x16x32_bf16 v[34:37], v[134:137], v[182:185], v[34:37]
	v_mfma_f32_16x16x32_bf16 v[30:33], v[142:145], v[182:185], v[30:33]
	v_mfma_f32_16x16x32_bf16 v[18:21], v[134:137], v[190:193], v[18:21]
	v_mfma_f32_16x16x32_bf16 v[14:17], v[142:145], v[190:193], v[14:17]
	v_mfma_f32_16x16x32_bf16 v[58:61], v[150:153], v[166:169], v[58:61]
	v_mfma_f32_16x16x32_bf16 v[54:57], v[158:161], v[166:169], v[54:57]
	v_mfma_f32_16x16x32_bf16 v[42:45], v[150:153], v[174:177], v[42:45]
	v_mfma_f32_16x16x32_bf16 v[38:41], v[158:161], v[174:177], v[38:41]
	v_mfma_f32_16x16x32_bf16 v[26:29], v[150:153], v[182:185], v[26:29]
	v_mfma_f32_16x16x32_bf16 v[22:25], v[158:161], v[182:185], v[22:25]
	v_mfma_f32_16x16x32_bf16 v[8:11], v[150:153], v[190:193], v[10:13]
	v_mfma_f32_16x16x32_bf16 v[4:7], v[158:161], v[190:193], v[4:7]
	v_mfma_f32_16x16x32_bf16 v[66:69], v[138:141], v[170:173], v[66:69]
	v_mfma_f32_16x16x32_bf16 v[62:65], v[146:149], v[170:173], v[62:65]
	v_mfma_f32_16x16x32_bf16 v[50:53], v[138:141], v[178:181], v[50:53]
	v_mfma_f32_16x16x32_bf16 v[46:49], v[146:149], v[178:181], v[46:49]
	v_mfma_f32_16x16x32_bf16 v[34:37], v[138:141], v[186:189], v[34:37]
	v_mfma_f32_16x16x32_bf16 v[30:33], v[146:149], v[186:189], v[30:33]
	v_mfma_f32_16x16x32_bf16 v[18:21], v[138:141], v[194:197], v[18:21]
	v_mfma_f32_16x16x32_bf16 v[14:17], v[146:149], v[194:197], v[14:17]
	v_mfma_f32_16x16x32_bf16 v[58:61], v[154:157], v[170:173], v[58:61]
	v_mfma_f32_16x16x32_bf16 v[54:57], v[162:165], v[170:173], v[54:57]
	v_mfma_f32_16x16x32_bf16 v[42:45], v[154:157], v[178:181], v[42:45]
	v_mfma_f32_16x16x32_bf16 v[38:41], v[162:165], v[178:181], v[38:41]
	v_mfma_f32_16x16x32_bf16 v[26:29], v[154:157], v[186:189], v[26:29]
	v_mfma_f32_16x16x32_bf16 v[22:25], v[162:165], v[186:189], v[22:25]
	v_mfma_f32_16x16x32_bf16 v[10:13], v[154:157], v[194:197], v[8:11]
	v_mfma_f32_16x16x32_bf16 v[6:9], v[162:165], v[194:197], v[4:7]
	s_setprio 0
	s_barrier
	s_add_i32 s91, s91, 2
	s_addk_i32 s90, 0x100
	s_cmp_ge_i32 s91, s3
	s_cbranch_scc1 .LBB0_1193

.LBB0_1290:
	ds_read_b128 v[106:109], v224
	ds_read_b128 v[118:121], v224 offset:1024
	ds_read_b128 v[130:133], v224 offset:2048
	ds_read_b128 v[138:141], v224 offset:3072
	ds_read_b128 v[146:149], v225
	ds_read_b128 v[150:153], v225 offset:1024
	ds_read_b128 v[154:157], v225 offset:2048
	ds_read_b128 v[158:161], v225 offset:3072
	s_add_i32 s18, s72, 0xffe80080
	s_cmp_eq_u32 s56, s74
	s_cselect_b32 s75, s6, s18
	s_cselect_b32 s77, s7, s73
	s_or_b32 s76, s75, 0x80
	s_add_i32 s18, s72, 0xfff80000
	s_mov_b32 m0, s57
	ds_read_b128 v[162:165], v226
	ds_read_b128 v[166:169], v226 offset:1024
	ds_read_b128 v[170:173], v226 offset:2048
	ds_read_b128 v[174:177], v226 offset:3072
	ds_read_b128 v[178:181], v226 offset:4096
	ds_read_b128 v[182:185], v226 offset:5120
	ds_read_b128 v[190:193], v226 offset:6144
	ds_read_b128 v[194:197], v226 offset:7168
	buffer_load_dwordx4 v222, s[12:15], s18 offen lds
	s_mov_b32 m0, s60
	s_nop 0
	buffer_load_dwordx4 v222, s[12:15], s72 offen lds
	s_waitcnt vmcnt(8) lgkmcnt(0)
	s_setprio 1
	v_mfma_f32_16x16x32_bf16 v[142:145], v[106:109], v[162:165], v[142:145]
	s_barrier
	v_mfma_f32_16x16x32_bf16 v[142:145], v[118:121], v[166:169], v[142:145]
	v_mfma_f32_16x16x32_bf16 v[134:137], v[130:133], v[162:165], v[134:137]
	v_mfma_f32_16x16x32_bf16 v[134:137], v[138:141], v[166:169], v[134:137]
	v_mfma_f32_16x16x32_bf16 v[126:129], v[146:149], v[162:165], v[126:129]
	v_mfma_f32_16x16x32_bf16 v[126:129], v[150:153], v[166:169], v[126:129]
	v_mfma_f32_16x16x32_bf16 v[122:125], v[154:157], v[162:165], v[122:125]
	v_mfma_f32_16x16x32_bf16 v[122:125], v[158:161], v[166:169], v[122:125]
	v_mfma_f32_16x16x32_bf16 v[98:101], v[154:157], v[170:173], v[98:101]
	v_mfma_f32_16x16x32_bf16 v[98:101], v[158:161], v[174:177], v[98:101]
	v_mfma_f32_16x16x32_bf16 v[102:105], v[146:149], v[170:173], v[102:105]
	v_mfma_f32_16x16x32_bf16 v[102:105], v[150:153], v[174:177], v[102:105]
	v_mfma_f32_16x16x32_bf16 v[110:113], v[130:133], v[170:173], v[110:113]
	v_mfma_f32_16x16x32_bf16 v[110:113], v[138:141], v[174:177], v[110:113]
	v_mfma_f32_16x16x32_bf16 v[114:117], v[106:109], v[170:173], v[114:117]
	v_mfma_f32_16x16x32_bf16 v[114:117], v[118:121], v[174:177], v[114:117]
	v_mfma_f32_16x16x32_bf16 v[94:97], v[106:109], v[178:181], v[94:97]
	v_mfma_f32_16x16x32_bf16 v[94:97], v[118:121], v[182:185], v[94:97]
	v_mfma_f32_16x16x32_bf16 v[90:93], v[130:133], v[178:181], v[90:93]
	v_mfma_f32_16x16x32_bf16 v[90:93], v[138:141], v[182:185], v[90:93]
	v_mfma_f32_16x16x32_bf16 v[86:89], v[146:149], v[178:181], v[86:89]
	v_mfma_f32_16x16x32_bf16 v[86:89], v[150:153], v[182:185], v[86:89]
	v_mfma_f32_16x16x32_bf16 v[82:85], v[154:157], v[178:181], v[82:85]
	v_mfma_f32_16x16x32_bf16 v[82:85], v[158:161], v[182:185], v[82:85]
	v_mfma_f32_16x16x32_bf16 v[66:69], v[154:157], v[190:193], v[66:69]
	v_mfma_f32_16x16x32_bf16 v[66:69], v[158:161], v[194:197], v[66:69]
	v_mfma_f32_16x16x32_bf16 v[70:73], v[146:149], v[190:193], v[70:73]
	v_mfma_f32_16x16x32_bf16 v[70:73], v[150:153], v[194:197], v[70:73]
	v_mfma_f32_16x16x32_bf16 v[74:77], v[130:133], v[190:193], v[74:77]
	v_mfma_f32_16x16x32_bf16 v[74:77], v[138:141], v[194:197], v[74:77]
	v_mfma_f32_16x16x32_bf16 v[78:81], v[106:109], v[190:193], v[78:81]
	v_mfma_f32_16x16x32_bf16 v[78:81], v[118:121], v[194:197], v[78:81]
	s_setprio 0
	s_barrier
	ds_read_b128 v[162:165], v226 offset:16384
	ds_read_b128 v[166:169], v226 offset:17408
	ds_read_b128 v[170:173], v226 offset:18432
	ds_read_b128 v[174:177], v226 offset:19456
	ds_read_b128 v[178:181], v226 offset:20480
	ds_read_b128 v[182:185], v226 offset:21504
	ds_read_b128 v[190:193], v226 offset:22528
	ds_read_b128 v[194:197], v226 offset:23552
	s_mov_b32 m0, s27
	s_mov_b32 s18, s14
	s_mov_b32 s19, s15
	buffer_load_dwordx4 v223, s[16:19], s77 offen lds
	s_mov_b32 m0, s30
	s_add_i32 s78, s77, 0x80000
	buffer_load_dwordx4 v223, s[16:19], s78 offen lds
	s_mov_b32 m0, s31
	s_add_i32 s78, s77, 0x100000
	buffer_load_dwordx4 v223, s[16:19], s78 offen lds
	s_mov_b32 m0, s41
	s_add_i32 s78, s77, 0x180000
	buffer_load_dwordx4 v223, s[16:19], s78 offen lds
	s_mov_b32 m0, s25
	s_add_i32 s78, s75, 0x80000
	buffer_load_dwordx4 v222, s[12:15], s75 offen lds
	s_mov_b32 m0, s42
	s_nop 0
	buffer_load_dwordx4 v222, s[12:15], s78 offen lds
	s_waitcnt vmcnt(8) lgkmcnt(0)
	s_setprio 1
	v_mfma_f32_16x16x32_bf16 v[62:65], v[106:109], v[162:165], v[62:65]
	s_barrier
	v_mfma_f32_16x16x32_bf16 v[62:65], v[118:121], v[166:169], v[62:65]
	v_mfma_f32_16x16x32_bf16 v[58:61], v[130:133], v[162:165], v[58:61]
	v_mfma_f32_16x16x32_bf16 v[58:61], v[138:141], v[166:169], v[58:61]
	v_mfma_f32_16x16x32_bf16 v[54:57], v[146:149], v[162:165], v[54:57]
	v_mfma_f32_16x16x32_bf16 v[54:57], v[150:153], v[166:169], v[54:57]
	v_mfma_f32_16x16x32_bf16 v[50:53], v[154:157], v[162:165], v[50:53]
	v_mfma_f32_16x16x32_bf16 v[50:53], v[158:161], v[166:169], v[50:53]
	v_mfma_f32_16x16x32_bf16 v[34:37], v[154:157], v[170:173], v[34:37]
	v_mfma_f32_16x16x32_bf16 v[34:37], v[158:161], v[174:177], v[34:37]
	v_mfma_f32_16x16x32_bf16 v[38:41], v[146:149], v[170:173], v[38:41]
	v_mfma_f32_16x16x32_bf16 v[38:41], v[150:153], v[174:177], v[38:41]
	v_mfma_f32_16x16x32_bf16 v[42:45], v[130:133], v[170:173], v[42:45]
	v_mfma_f32_16x16x32_bf16 v[42:45], v[138:141], v[174:177], v[42:45]
	v_mfma_f32_16x16x32_bf16 v[46:49], v[106:109], v[170:173], v[46:49]
	v_mfma_f32_16x16x32_bf16 v[46:49], v[118:121], v[174:177], v[46:49]
	v_mfma_f32_16x16x32_bf16 v[30:33], v[106:109], v[178:181], v[30:33]
	v_mfma_f32_16x16x32_bf16 v[30:33], v[118:121], v[182:185], v[30:33]
	v_mfma_f32_16x16x32_bf16 v[26:29], v[130:133], v[178:181], v[26:29]
	v_mfma_f32_16x16x32_bf16 v[26:29], v[138:141], v[182:185], v[26:29]
	v_mfma_f32_16x16x32_bf16 v[22:25], v[146:149], v[178:181], v[22:25]
	v_mfma_f32_16x16x32_bf16 v[22:25], v[150:153], v[182:185], v[22:25]
	v_mfma_f32_16x16x32_bf16 v[18:21], v[154:157], v[178:181], v[18:21]
	v_mfma_f32_16x16x32_bf16 v[18:21], v[158:161], v[182:185], v[18:21]
	v_mfma_f32_16x16x32_bf16 v[2:5], v[154:157], v[190:193], v[2:5]
	v_mfma_f32_16x16x32_bf16 v[2:5], v[158:161], v[194:197], v[2:5]
	v_mfma_f32_16x16x32_bf16 v[6:9], v[146:149], v[190:193], v[6:9]
	v_mfma_f32_16x16x32_bf16 v[6:9], v[150:153], v[194:197], v[6:9]
	v_mfma_f32_16x16x32_bf16 v[10:13], v[130:133], v[190:193], v[10:13]
	v_mfma_f32_16x16x32_bf16 v[10:13], v[138:141], v[194:197], v[10:13]
	v_mfma_f32_16x16x32_bf16 v[14:17], v[106:109], v[190:193], v[14:17]
	v_mfma_f32_16x16x32_bf16 v[14:17], v[118:121], v[194:197], v[14:17]
	s_setprio 0
	s_barrier
	ds_read_b128 v[106:109], v227
	ds_read_b128 v[118:121], v227 offset:1024
	ds_read_b128 v[130:133], v227 offset:2048
	ds_read_b128 v[138:141], v227 offset:3072
	ds_read_b128 v[146:149], v228
	ds_read_b128 v[150:153], v228 offset:1024
	ds_read_b128 v[154:157], v228 offset:2048
	ds_read_b128 v[158:161], v228 offset:3072
	s_mov_b32 m0, s43
	s_add_i32 s78, s75, 0x100000
	ds_read_b128 v[162:165], v226 offset:32768
	ds_read_b128 v[166:169], v226 offset:33792
	ds_read_b128 v[170:173], v226 offset:34816
	ds_read_b128 v[174:177], v226 offset:35840
	ds_read_b128 v[178:181], v226 offset:36864
	ds_read_b128 v[182:185], v226 offset:37888
	ds_read_b128 v[190:193], v226 offset:38912
	ds_read_b128 v[194:197], v226 offset:39936
	buffer_load_dwordx4 v222, s[12:15], s78 offen lds
	s_mov_b32 m0, s44
	s_add_i32 s78, s75, 0x180000
	buffer_load_dwordx4 v222, s[12:15], s78 offen lds
	s_waitcnt vmcnt(8) lgkmcnt(0)
	s_setprio 1
	v_mfma_f32_16x16x32_bf16 v[142:145], v[106:109], v[162:165], v[142:145]
	s_barrier
	v_mfma_f32_16x16x32_bf16 v[142:145], v[118:121], v[166:169], v[142:145]
	v_mfma_f32_16x16x32_bf16 v[134:137], v[130:133], v[162:165], v[134:137]
	v_mfma_f32_16x16x32_bf16 v[134:137], v[138:141], v[166:169], v[134:137]
	v_mfma_f32_16x16x32_bf16 v[126:129], v[146:149], v[162:165], v[126:129]
	v_mfma_f32_16x16x32_bf16 v[126:129], v[150:153], v[166:169], v[126:129]
	v_mfma_f32_16x16x32_bf16 v[122:125], v[154:157], v[162:165], v[122:125]
	v_mfma_f32_16x16x32_bf16 v[122:125], v[158:161], v[166:169], v[122:125]
	v_mfma_f32_16x16x32_bf16 v[98:101], v[154:157], v[170:173], v[98:101]
	v_mfma_f32_16x16x32_bf16 v[98:101], v[158:161], v[174:177], v[98:101]
	v_mfma_f32_16x16x32_bf16 v[102:105], v[146:149], v[170:173], v[102:105]
	v_mfma_f32_16x16x32_bf16 v[102:105], v[150:153], v[174:177], v[102:105]
	v_mfma_f32_16x16x32_bf16 v[110:113], v[130:133], v[170:173], v[110:113]
	v_mfma_f32_16x16x32_bf16 v[110:113], v[138:141], v[174:177], v[110:113]
	v_mfma_f32_16x16x32_bf16 v[114:117], v[106:109], v[170:173], v[114:117]
	v_mfma_f32_16x16x32_bf16 v[114:117], v[118:121], v[174:177], v[114:117]
	v_mfma_f32_16x16x32_bf16 v[94:97], v[106:109], v[178:181], v[94:97]
	v_mfma_f32_16x16x32_bf16 v[94:97], v[118:121], v[182:185], v[94:97]
	v_mfma_f32_16x16x32_bf16 v[90:93], v[130:133], v[178:181], v[90:93]
	v_mfma_f32_16x16x32_bf16 v[90:93], v[138:141], v[182:185], v[90:93]
	v_mfma_f32_16x16x32_bf16 v[86:89], v[146:149], v[178:181], v[86:89]
	v_mfma_f32_16x16x32_bf16 v[86:89], v[150:153], v[182:185], v[86:89]
	v_mfma_f32_16x16x32_bf16 v[82:85], v[154:157], v[178:181], v[82:85]
	v_mfma_f32_16x16x32_bf16 v[82:85], v[158:161], v[182:185], v[82:85]
	v_mfma_f32_16x16x32_bf16 v[66:69], v[154:157], v[190:193], v[66:69]
	v_mfma_f32_16x16x32_bf16 v[66:69], v[158:161], v[194:197], v[66:69]
	v_mfma_f32_16x16x32_bf16 v[70:73], v[146:149], v[190:193], v[70:73]
	v_mfma_f32_16x16x32_bf16 v[70:73], v[150:153], v[194:197], v[70:73]
	v_mfma_f32_16x16x32_bf16 v[74:77], v[130:133], v[190:193], v[74:77]
	v_mfma_f32_16x16x32_bf16 v[74:77], v[138:141], v[194:197], v[74:77]
	v_mfma_f32_16x16x32_bf16 v[78:81], v[106:109], v[190:193], v[78:81]
	v_mfma_f32_16x16x32_bf16 v[78:81], v[118:121], v[194:197], v[78:81]
	s_setprio 0
	s_barrier
	ds_read_b128 v[162:165], v226 offset:49152
	ds_read_b128 v[166:169], v226 offset:50176
	ds_read_b128 v[170:173], v226 offset:51200
	ds_read_b128 v[174:177], v226 offset:52224
	ds_read_b128 v[178:181], v226 offset:53248
	ds_read_b128 v[182:185], v226 offset:54272
	ds_read_b128 v[190:193], v226 offset:55296
	ds_read_b128 v[194:197], v226 offset:56320
	s_mov_b32 m0, s48
	s_or_b32 s78, s77, 0x80
	buffer_load_dwordx4 v223, s[16:19], s78 offen lds
	s_add_i32 s78, s77, 0x80080
	s_mov_b32 m0, s49
	s_add_i32 s75, s75, 0x80080
	buffer_load_dwordx4 v223, s[16:19], s78 offen lds
	s_add_i32 s78, s77, 0x100080
	s_mov_b32 m0, s52
	s_add_i32 s77, s77, 0x180080
	buffer_load_dwordx4 v223, s[16:19], s78 offen lds
	s_mov_b32 m0, s53
	s_nop 0
	buffer_load_dwordx4 v223, s[16:19], s77 offen lds
	s_mov_b32 m0, s50
	s_nop 0
	buffer_load_dwordx4 v222, s[12:15], s76 offen lds
	s_mov_b32 m0, s51
	s_nop 0
	buffer_load_dwordx4 v222, s[12:15], s75 offen lds
	s_waitcnt vmcnt(8) lgkmcnt(0)
	s_setprio 1
	v_mfma_f32_16x16x32_bf16 v[62:65], v[106:109], v[162:165], v[62:65]
	s_barrier
	v_mfma_f32_16x16x32_bf16 v[62:65], v[118:121], v[166:169], v[62:65]
	v_mfma_f32_16x16x32_bf16 v[58:61], v[130:133], v[162:165], v[58:61]
	v_mfma_f32_16x16x32_bf16 v[58:61], v[138:141], v[166:169], v[58:61]
	v_mfma_f32_16x16x32_bf16 v[54:57], v[146:149], v[162:165], v[54:57]
	v_mfma_f32_16x16x32_bf16 v[54:57], v[150:153], v[166:169], v[54:57]
	v_mfma_f32_16x16x32_bf16 v[50:53], v[154:157], v[162:165], v[50:53]
	v_mfma_f32_16x16x32_bf16 v[50:53], v[158:161], v[166:169], v[50:53]
	v_mfma_f32_16x16x32_bf16 v[34:37], v[154:157], v[170:173], v[34:37]
	v_mfma_f32_16x16x32_bf16 v[34:37], v[158:161], v[174:177], v[34:37]
	v_mfma_f32_16x16x32_bf16 v[38:41], v[146:149], v[170:173], v[38:41]
	v_mfma_f32_16x16x32_bf16 v[38:41], v[150:153], v[174:177], v[38:41]
	v_mfma_f32_16x16x32_bf16 v[42:45], v[130:133], v[170:173], v[42:45]
	v_mfma_f32_16x16x32_bf16 v[42:45], v[138:141], v[174:177], v[42:45]
	v_mfma_f32_16x16x32_bf16 v[46:49], v[106:109], v[170:173], v[46:49]
	v_mfma_f32_16x16x32_bf16 v[46:49], v[118:121], v[174:177], v[46:49]
	v_mfma_f32_16x16x32_bf16 v[30:33], v[106:109], v[178:181], v[30:33]
	v_mfma_f32_16x16x32_bf16 v[30:33], v[118:121], v[182:185], v[30:33]
	v_mfma_f32_16x16x32_bf16 v[26:29], v[130:133], v[178:181], v[26:29]
	v_mfma_f32_16x16x32_bf16 v[26:29], v[138:141], v[182:185], v[26:29]
	v_mfma_f32_16x16x32_bf16 v[22:25], v[146:149], v[178:181], v[22:25]
	v_mfma_f32_16x16x32_bf16 v[22:25], v[150:153], v[182:185], v[22:25]
	v_mfma_f32_16x16x32_bf16 v[18:21], v[154:157], v[178:181], v[18:21]
	v_mfma_f32_16x16x32_bf16 v[18:21], v[158:161], v[182:185], v[18:21]
	v_mfma_f32_16x16x32_bf16 v[2:5], v[154:157], v[190:193], v[2:5]
	v_mfma_f32_16x16x32_bf16 v[2:5], v[158:161], v[194:197], v[2:5]
	v_mfma_f32_16x16x32_bf16 v[6:9], v[146:149], v[190:193], v[6:9]
	v_mfma_f32_16x16x32_bf16 v[6:9], v[150:153], v[194:197], v[6:9]
	v_mfma_f32_16x16x32_bf16 v[10:13], v[130:133], v[190:193], v[10:13]
	v_mfma_f32_16x16x32_bf16 v[10:13], v[138:141], v[194:197], v[10:13]
	v_mfma_f32_16x16x32_bf16 v[14:17], v[106:109], v[190:193], v[14:17]
	v_mfma_f32_16x16x32_bf16 v[14:17], v[118:121], v[194:197], v[14:17]
	s_setprio 0
	s_barrier
	s_add_i32 s74, s74, 2
	s_addk_i32 s72, 0x100
	s_addk_i32 s73, 0x100
	s_cmp_ge_i32 s74, s3
	s_cbranch_scc0 .LBB0_1290
	s_and_b64 vcc, exec, s[38:39]
	s_cbranch_vccz .LBB0_1293

.LBB0_1382:
	ds_read_b128 v[144:147], v138
	ds_read_b128 v[148:151], v138 offset:1024
	ds_read_b128 v[152:155], v138 offset:2048
	ds_read_b128 v[156:159], v138 offset:3072
	ds_read_b128 v[160:163], v139
	ds_read_b128 v[164:167], v139 offset:1024
	ds_read_b128 v[168:171], v139 offset:2048
	ds_read_b128 v[172:175], v139 offset:3072
	s_add_i32 s14, s74, 0xffe80080
	s_cmp_eq_u32 s61, s76
	s_cselect_b32 s77, s72, s14
	s_cselect_b32 s79, s73, s75
	s_or_b32 s78, s77, 0x80
	s_add_i32 s14, s74, 0xfff80000
	s_mov_b32 m0, s62
	ds_read_b128 v[176:179], v140
	ds_read_b128 v[180:183], v140 offset:1024
	ds_read_b128 v[184:187], v140 offset:2048
	ds_read_b128 v[188:191], v140 offset:3072
	ds_read_b128 v[192:195], v140 offset:4096
	ds_read_b128 v[196:199], v140 offset:5120
	ds_read_b128 v[200:203], v140 offset:6144
	ds_read_b128 v[204:207], v140 offset:7168
	buffer_load_dwordx4 v136, s[16:19], s14 offen lds
	s_mov_b32 m0, s63
	s_nop 0
	buffer_load_dwordx4 v136, s[16:19], s74 offen lds
	s_waitcnt vmcnt(8) lgkmcnt(0)
	s_setprio 1
	v_mfma_f32_16x16x32_bf16 v[118:121], v[144:147], v[176:179], v[118:121]
	s_barrier
	v_mfma_f32_16x16x32_bf16 v[118:121], v[148:151], v[180:183], v[118:121]
	v_mfma_f32_16x16x32_bf16 v[114:117], v[152:155], v[176:179], v[114:117]
	v_mfma_f32_16x16x32_bf16 v[114:117], v[156:159], v[180:183], v[114:117]
	v_mfma_f32_16x16x32_bf16 v[126:129], v[160:163], v[176:179], v[126:129]
	v_mfma_f32_16x16x32_bf16 v[126:129], v[164:167], v[180:183], v[126:129]
	v_mfma_f32_16x16x32_bf16 v[122:125], v[168:171], v[176:179], v[122:125]
	v_mfma_f32_16x16x32_bf16 v[122:125], v[172:175], v[180:183], v[122:125]
	v_mfma_f32_16x16x32_bf16 v[98:101], v[168:171], v[184:187], v[98:101]
	v_mfma_f32_16x16x32_bf16 v[98:101], v[172:175], v[188:191], v[98:101]
	v_mfma_f32_16x16x32_bf16 v[106:109], v[160:163], v[184:187], v[106:109]
	v_mfma_f32_16x16x32_bf16 v[106:109], v[164:167], v[188:191], v[106:109]
	v_mfma_f32_16x16x32_bf16 v[102:105], v[152:155], v[184:187], v[102:105]
	v_mfma_f32_16x16x32_bf16 v[102:105], v[156:159], v[188:191], v[102:105]
	v_mfma_f32_16x16x32_bf16 v[110:113], v[144:147], v[184:187], v[110:113]
	v_mfma_f32_16x16x32_bf16 v[110:113], v[148:151], v[188:191], v[110:113]
	v_mfma_f32_16x16x32_bf16 v[94:97], v[144:147], v[192:195], v[94:97]
	v_mfma_f32_16x16x32_bf16 v[94:97], v[148:151], v[196:199], v[94:97]
	v_mfma_f32_16x16x32_bf16 v[86:89], v[152:155], v[192:195], v[86:89]
	v_mfma_f32_16x16x32_bf16 v[86:89], v[156:159], v[196:199], v[86:89]
	v_mfma_f32_16x16x32_bf16 v[90:93], v[160:163], v[192:195], v[90:93]
	v_mfma_f32_16x16x32_bf16 v[90:93], v[164:167], v[196:199], v[90:93]
	v_mfma_f32_16x16x32_bf16 v[82:85], v[168:171], v[192:195], v[82:85]
	v_mfma_f32_16x16x32_bf16 v[82:85], v[172:175], v[196:199], v[82:85]
	v_mfma_f32_16x16x32_bf16 v[70:73], v[168:171], v[200:203], v[70:73]
	v_mfma_f32_16x16x32_bf16 v[70:73], v[172:175], v[204:207], v[70:73]
	v_mfma_f32_16x16x32_bf16 v[74:77], v[160:163], v[200:203], v[74:77]
	v_mfma_f32_16x16x32_bf16 v[74:77], v[164:167], v[204:207], v[74:77]
	v_mfma_f32_16x16x32_bf16 v[66:69], v[152:155], v[200:203], v[66:69]
	v_mfma_f32_16x16x32_bf16 v[66:69], v[156:159], v[204:207], v[66:69]
	v_mfma_f32_16x16x32_bf16 v[78:81], v[144:147], v[200:203], v[78:81]
	v_mfma_f32_16x16x32_bf16 v[78:81], v[148:151], v[204:207], v[78:81]
	s_setprio 0
	s_barrier
	ds_read_b128 v[176:179], v140 offset:16384
	ds_read_b128 v[180:183], v140 offset:17408
	ds_read_b128 v[184:187], v140 offset:18432
	ds_read_b128 v[188:191], v140 offset:19456
	ds_read_b128 v[192:195], v140 offset:20480
	ds_read_b128 v[196:199], v140 offset:21504
	ds_read_b128 v[200:203], v140 offset:22528
	ds_read_b128 v[204:207], v140 offset:23552
	s_mov_b32 m0, s45
	s_mov_b32 s14, s18
	s_mov_b32 s15, s19
	buffer_load_dwordx4 v137, s[12:15], s79 offen lds
	s_mov_b32 m0, s46
	s_add_i32 s80, s79, 0x80000
	buffer_load_dwordx4 v137, s[12:15], s80 offen lds
	s_mov_b32 m0, s47
	s_add_i32 s80, s79, 0x100000
	buffer_load_dwordx4 v137, s[12:15], s80 offen lds
	s_mov_b32 m0, s48
	s_add_i32 s80, s79, 0x180000
	buffer_load_dwordx4 v137, s[12:15], s80 offen lds
	s_mov_b32 m0, s44
	s_add_i32 s80, s77, 0x80000
	buffer_load_dwordx4 v136, s[16:19], s77 offen lds
	s_mov_b32 m0, s49
	s_nop 0
	buffer_load_dwordx4 v136, s[16:19], s80 offen lds
	s_waitcnt vmcnt(8) lgkmcnt(0)
	s_setprio 1
	v_mfma_f32_16x16x32_bf16 v[62:65], v[144:147], v[176:179], v[62:65]
	s_barrier
	v_mfma_f32_16x16x32_bf16 v[62:65], v[148:151], v[180:183], v[62:65]
	v_mfma_f32_16x16x32_bf16 v[54:57], v[152:155], v[176:179], v[54:57]
	v_mfma_f32_16x16x32_bf16 v[54:57], v[156:159], v[180:183], v[54:57]
	v_mfma_f32_16x16x32_bf16 v[58:61], v[160:163], v[176:179], v[58:61]
	v_mfma_f32_16x16x32_bf16 v[58:61], v[164:167], v[180:183], v[58:61]
	v_mfma_f32_16x16x32_bf16 v[50:53], v[168:171], v[176:179], v[50:53]
	v_mfma_f32_16x16x32_bf16 v[50:53], v[172:175], v[180:183], v[50:53]
	v_mfma_f32_16x16x32_bf16 v[34:37], v[168:171], v[184:187], v[34:37]
	v_mfma_f32_16x16x32_bf16 v[34:37], v[172:175], v[188:191], v[34:37]
	v_mfma_f32_16x16x32_bf16 v[42:45], v[160:163], v[184:187], v[42:45]
	v_mfma_f32_16x16x32_bf16 v[42:45], v[164:167], v[188:191], v[42:45]
	v_mfma_f32_16x16x32_bf16 v[38:41], v[152:155], v[184:187], v[38:41]
	v_mfma_f32_16x16x32_bf16 v[38:41], v[156:159], v[188:191], v[38:41]
	v_mfma_f32_16x16x32_bf16 v[46:49], v[144:147], v[184:187], v[46:49]
	v_mfma_f32_16x16x32_bf16 v[46:49], v[148:151], v[188:191], v[46:49]
	v_mfma_f32_16x16x32_bf16 v[30:33], v[144:147], v[192:195], v[30:33]
	v_mfma_f32_16x16x32_bf16 v[30:33], v[148:151], v[196:199], v[30:33]
	v_mfma_f32_16x16x32_bf16 v[22:25], v[152:155], v[192:195], v[22:25]
	v_mfma_f32_16x16x32_bf16 v[22:25], v[156:159], v[196:199], v[22:25]
	v_mfma_f32_16x16x32_bf16 v[26:29], v[160:163], v[192:195], v[26:29]
	v_mfma_f32_16x16x32_bf16 v[26:29], v[164:167], v[196:199], v[26:29]
	v_mfma_f32_16x16x32_bf16 v[18:21], v[168:171], v[192:195], v[18:21]
	v_mfma_f32_16x16x32_bf16 v[18:21], v[172:175], v[196:199], v[18:21]
	v_mfma_f32_16x16x32_bf16 v[2:5], v[168:171], v[200:203], v[2:5]
	v_mfma_f32_16x16x32_bf16 v[2:5], v[172:175], v[204:207], v[2:5]
	v_mfma_f32_16x16x32_bf16 v[10:13], v[160:163], v[200:203], v[10:13]
	v_mfma_f32_16x16x32_bf16 v[10:13], v[164:167], v[204:207], v[10:13]
	v_mfma_f32_16x16x32_bf16 v[6:9], v[152:155], v[200:203], v[6:9]
	v_mfma_f32_16x16x32_bf16 v[6:9], v[156:159], v[204:207], v[6:9]
	v_mfma_f32_16x16x32_bf16 v[14:17], v[144:147], v[200:203], v[14:17]
	v_mfma_f32_16x16x32_bf16 v[14:17], v[148:151], v[204:207], v[14:17]
	s_setprio 0
	s_barrier
	ds_read_b128 v[144:147], v141
	ds_read_b128 v[148:151], v141 offset:1024
	ds_read_b128 v[152:155], v141 offset:2048
	ds_read_b128 v[156:159], v141 offset:3072
	ds_read_b128 v[160:163], v142
	ds_read_b128 v[164:167], v142 offset:1024
	ds_read_b128 v[168:171], v142 offset:2048
	ds_read_b128 v[172:175], v142 offset:3072
	s_mov_b32 m0, s50
	s_add_i32 s80, s77, 0x100000
	ds_read_b128 v[176:179], v140 offset:32768
	ds_read_b128 v[180:183], v140 offset:33792
	ds_read_b128 v[184:187], v140 offset:34816
	ds_read_b128 v[188:191], v140 offset:35840
	ds_read_b128 v[192:195], v140 offset:36864
	ds_read_b128 v[196:199], v140 offset:37888
	ds_read_b128 v[200:203], v140 offset:38912
	ds_read_b128 v[204:207], v140 offset:39936
	buffer_load_dwordx4 v136, s[16:19], s80 offen lds
	s_mov_b32 m0, s51
	s_add_i32 s80, s77, 0x180000
	buffer_load_dwordx4 v136, s[16:19], s80 offen lds
	s_waitcnt vmcnt(8) lgkmcnt(0)
	s_setprio 1
	v_mfma_f32_16x16x32_bf16 v[118:121], v[144:147], v[176:179], v[118:121]
	s_barrier
	v_mfma_f32_16x16x32_bf16 v[118:121], v[148:151], v[180:183], v[118:121]
	v_mfma_f32_16x16x32_bf16 v[114:117], v[152:155], v[176:179], v[114:117]
	v_mfma_f32_16x16x32_bf16 v[114:117], v[156:159], v[180:183], v[114:117]
	v_mfma_f32_16x16x32_bf16 v[126:129], v[160:163], v[176:179], v[126:129]
	v_mfma_f32_16x16x32_bf16 v[126:129], v[164:167], v[180:183], v[126:129]
	v_mfma_f32_16x16x32_bf16 v[122:125], v[168:171], v[176:179], v[122:125]
	v_mfma_f32_16x16x32_bf16 v[122:125], v[172:175], v[180:183], v[122:125]
	v_mfma_f32_16x16x32_bf16 v[98:101], v[168:171], v[184:187], v[98:101]
	v_mfma_f32_16x16x32_bf16 v[98:101], v[172:175], v[188:191], v[98:101]
	v_mfma_f32_16x16x32_bf16 v[106:109], v[160:163], v[184:187], v[106:109]
	v_mfma_f32_16x16x32_bf16 v[106:109], v[164:167], v[188:191], v[106:109]
	v_mfma_f32_16x16x32_bf16 v[102:105], v[152:155], v[184:187], v[102:105]
	v_mfma_f32_16x16x32_bf16 v[102:105], v[156:159], v[188:191], v[102:105]
	v_mfma_f32_16x16x32_bf16 v[110:113], v[144:147], v[184:187], v[110:113]
	v_mfma_f32_16x16x32_bf16 v[110:113], v[148:151], v[188:191], v[110:113]
	v_mfma_f32_16x16x32_bf16 v[94:97], v[144:147], v[192:195], v[94:97]
	v_mfma_f32_16x16x32_bf16 v[94:97], v[148:151], v[196:199], v[94:97]
	v_mfma_f32_16x16x32_bf16 v[86:89], v[152:155], v[192:195], v[86:89]
	v_mfma_f32_16x16x32_bf16 v[86:89], v[156:159], v[196:199], v[86:89]
	v_mfma_f32_16x16x32_bf16 v[90:93], v[160:163], v[192:195], v[90:93]
	v_mfma_f32_16x16x32_bf16 v[90:93], v[164:167], v[196:199], v[90:93]
	v_mfma_f32_16x16x32_bf16 v[82:85], v[168:171], v[192:195], v[82:85]
	v_mfma_f32_16x16x32_bf16 v[82:85], v[172:175], v[196:199], v[82:85]
	v_mfma_f32_16x16x32_bf16 v[70:73], v[168:171], v[200:203], v[70:73]
	v_mfma_f32_16x16x32_bf16 v[70:73], v[172:175], v[204:207], v[70:73]
	v_mfma_f32_16x16x32_bf16 v[74:77], v[160:163], v[200:203], v[74:77]
	v_mfma_f32_16x16x32_bf16 v[74:77], v[164:167], v[204:207], v[74:77]
	v_mfma_f32_16x16x32_bf16 v[66:69], v[152:155], v[200:203], v[66:69]
	v_mfma_f32_16x16x32_bf16 v[66:69], v[156:159], v[204:207], v[66:69]
	v_mfma_f32_16x16x32_bf16 v[78:81], v[144:147], v[200:203], v[78:81]
	v_mfma_f32_16x16x32_bf16 v[78:81], v[148:151], v[204:207], v[78:81]
	s_setprio 0
	s_barrier
	ds_read_b128 v[176:179], v140 offset:49152
	ds_read_b128 v[180:183], v140 offset:50176
	ds_read_b128 v[184:187], v140 offset:51200
	ds_read_b128 v[188:191], v140 offset:52224
	ds_read_b128 v[192:195], v140 offset:53248
	ds_read_b128 v[196:199], v140 offset:54272
	ds_read_b128 v[200:203], v140 offset:55296
	ds_read_b128 v[204:207], v140 offset:56320
	s_mov_b32 m0, s53
	s_or_b32 s80, s79, 0x80
	buffer_load_dwordx4 v137, s[12:15], s80 offen lds
	s_add_i32 s80, s79, 0x80080
	s_mov_b32 m0, s54
	s_add_i32 s77, s77, 0x80080
	buffer_load_dwordx4 v137, s[12:15], s80 offen lds
	s_add_i32 s80, s79, 0x100080
	s_mov_b32 m0, s57
	s_add_i32 s79, s79, 0x180080
	buffer_load_dwordx4 v137, s[12:15], s80 offen lds
	s_mov_b32 m0, s58
	s_nop 0
	buffer_load_dwordx4 v137, s[12:15], s79 offen lds
	s_mov_b32 m0, s55
	s_nop 0
	buffer_load_dwordx4 v136, s[16:19], s78 offen lds
	s_mov_b32 m0, s56
	s_nop 0
	buffer_load_dwordx4 v136, s[16:19], s77 offen lds
	s_waitcnt vmcnt(8) lgkmcnt(0)
	s_setprio 1
	v_mfma_f32_16x16x32_bf16 v[62:65], v[144:147], v[176:179], v[62:65]
	s_barrier
	v_mfma_f32_16x16x32_bf16 v[62:65], v[148:151], v[180:183], v[62:65]
	v_mfma_f32_16x16x32_bf16 v[54:57], v[152:155], v[176:179], v[54:57]
	v_mfma_f32_16x16x32_bf16 v[54:57], v[156:159], v[180:183], v[54:57]
	v_mfma_f32_16x16x32_bf16 v[58:61], v[160:163], v[176:179], v[58:61]
	v_mfma_f32_16x16x32_bf16 v[58:61], v[164:167], v[180:183], v[58:61]
	v_mfma_f32_16x16x32_bf16 v[50:53], v[168:171], v[176:179], v[50:53]
	v_mfma_f32_16x16x32_bf16 v[50:53], v[172:175], v[180:183], v[50:53]
	v_mfma_f32_16x16x32_bf16 v[34:37], v[168:171], v[184:187], v[34:37]
	v_mfma_f32_16x16x32_bf16 v[34:37], v[172:175], v[188:191], v[34:37]
	v_mfma_f32_16x16x32_bf16 v[42:45], v[160:163], v[184:187], v[42:45]
	v_mfma_f32_16x16x32_bf16 v[42:45], v[164:167], v[188:191], v[42:45]
	v_mfma_f32_16x16x32_bf16 v[38:41], v[152:155], v[184:187], v[38:41]
	v_mfma_f32_16x16x32_bf16 v[38:41], v[156:159], v[188:191], v[38:41]
	v_mfma_f32_16x16x32_bf16 v[46:49], v[144:147], v[184:187], v[46:49]
	v_mfma_f32_16x16x32_bf16 v[46:49], v[148:151], v[188:191], v[46:49]
	v_mfma_f32_16x16x32_bf16 v[30:33], v[144:147], v[192:195], v[30:33]
	v_mfma_f32_16x16x32_bf16 v[30:33], v[148:151], v[196:199], v[30:33]
	v_mfma_f32_16x16x32_bf16 v[22:25], v[152:155], v[192:195], v[22:25]
	v_mfma_f32_16x16x32_bf16 v[22:25], v[156:159], v[196:199], v[22:25]
	v_mfma_f32_16x16x32_bf16 v[26:29], v[160:163], v[192:195], v[26:29]
	v_mfma_f32_16x16x32_bf16 v[26:29], v[164:167], v[196:199], v[26:29]
	v_mfma_f32_16x16x32_bf16 v[18:21], v[168:171], v[192:195], v[18:21]
	v_mfma_f32_16x16x32_bf16 v[18:21], v[172:175], v[196:199], v[18:21]
	v_mfma_f32_16x16x32_bf16 v[2:5], v[168:171], v[200:203], v[2:5]
	v_mfma_f32_16x16x32_bf16 v[2:5], v[172:175], v[204:207], v[2:5]
	v_mfma_f32_16x16x32_bf16 v[10:13], v[160:163], v[200:203], v[10:13]
	v_mfma_f32_16x16x32_bf16 v[10:13], v[164:167], v[204:207], v[10:13]
	v_mfma_f32_16x16x32_bf16 v[6:9], v[152:155], v[200:203], v[6:9]
	v_mfma_f32_16x16x32_bf16 v[6:9], v[156:159], v[204:207], v[6:9]
	v_mfma_f32_16x16x32_bf16 v[14:17], v[144:147], v[200:203], v[14:17]
	v_mfma_f32_16x16x32_bf16 v[14:17], v[148:151], v[204:207], v[14:17]
	s_setprio 0
	s_barrier
	s_add_i32 s76, s76, 2
	s_addk_i32 s74, 0x100
	s_addk_i32 s75, 0x100
	s_cmp_ge_i32 s76, s27
	s_cbranch_scc0 .LBB0_1382
	s_and_b64 vcc, exec, s[42:43]
	s_cbranch_vccz .LBB0_1385

.LBB0_1402:
	ds_read_b128 v[146:149], v138
	ds_read_b128 v[150:153], v138 offset:1024
	ds_read_b128 v[154:157], v138 offset:2048
	ds_read_b128 v[158:161], v138 offset:3072
	ds_read_b128 v[162:165], v139
	ds_read_b128 v[166:169], v139 offset:1024
	ds_read_b128 v[170:173], v139 offset:2048
	ds_read_b128 v[174:177], v139 offset:3072
	s_add_i32 s22, s75, 0xffe80080
	s_cmp_eq_u32 s62, s77
	s_cselect_b32 s78, s73, s22
	s_cselect_b32 s80, s74, s76
	s_or_b32 s79, s78, 0x80
	s_add_i32 s22, s75, 0xfff80000
	s_mov_b32 m0, s63
	ds_read_b128 v[178:181], v140
	ds_read_b128 v[182:185], v140 offset:1024
	ds_read_b128 v[186:189], v140 offset:2048
	ds_read_b128 v[190:193], v140 offset:3072
	ds_read_b128 v[194:197], v140 offset:4096
	ds_read_b128 v[198:201], v140 offset:5120
	ds_read_b128 v[202:205], v140 offset:6144
	ds_read_b128 v[206:209], v140 offset:7168
	buffer_load_dwordx4 v136, s[16:19], s22 offen lds
	s_mov_b32 m0, s64
	s_nop 0
	buffer_load_dwordx4 v136, s[16:19], s75 offen lds
	s_waitcnt vmcnt(8) lgkmcnt(0)
	s_setprio 1
	v_mfma_f32_16x16x32_bf16 v[118:121], v[146:149], v[178:181], v[118:121]
	s_barrier
	v_mfma_f32_16x16x32_bf16 v[118:121], v[150:153], v[182:185], v[118:121]
	v_mfma_f32_16x16x32_bf16 v[114:117], v[154:157], v[178:181], v[114:117]
	v_mfma_f32_16x16x32_bf16 v[114:117], v[158:161], v[182:185], v[114:117]
	v_mfma_f32_16x16x32_bf16 v[126:129], v[162:165], v[178:181], v[126:129]
	v_mfma_f32_16x16x32_bf16 v[126:129], v[166:169], v[182:185], v[126:129]
	v_mfma_f32_16x16x32_bf16 v[122:125], v[170:173], v[178:181], v[122:125]
	v_mfma_f32_16x16x32_bf16 v[122:125], v[174:177], v[182:185], v[122:125]
	v_mfma_f32_16x16x32_bf16 v[98:101], v[170:173], v[186:189], v[98:101]
	v_mfma_f32_16x16x32_bf16 v[98:101], v[174:177], v[190:193], v[98:101]
	v_mfma_f32_16x16x32_bf16 v[106:109], v[162:165], v[186:189], v[106:109]
	v_mfma_f32_16x16x32_bf16 v[106:109], v[166:169], v[190:193], v[106:109]
	v_mfma_f32_16x16x32_bf16 v[102:105], v[154:157], v[186:189], v[102:105]
	v_mfma_f32_16x16x32_bf16 v[102:105], v[158:161], v[190:193], v[102:105]
	v_mfma_f32_16x16x32_bf16 v[110:113], v[146:149], v[186:189], v[110:113]
	v_mfma_f32_16x16x32_bf16 v[110:113], v[150:153], v[190:193], v[110:113]
	v_mfma_f32_16x16x32_bf16 v[94:97], v[146:149], v[194:197], v[94:97]
	v_mfma_f32_16x16x32_bf16 v[94:97], v[150:153], v[198:201], v[94:97]
	v_mfma_f32_16x16x32_bf16 v[86:89], v[154:157], v[194:197], v[86:89]
	v_mfma_f32_16x16x32_bf16 v[86:89], v[158:161], v[198:201], v[86:89]
	v_mfma_f32_16x16x32_bf16 v[90:93], v[162:165], v[194:197], v[90:93]
	v_mfma_f32_16x16x32_bf16 v[90:93], v[166:169], v[198:201], v[90:93]
	v_mfma_f32_16x16x32_bf16 v[82:85], v[170:173], v[194:197], v[82:85]
	v_mfma_f32_16x16x32_bf16 v[82:85], v[174:177], v[198:201], v[82:85]
	v_mfma_f32_16x16x32_bf16 v[70:73], v[170:173], v[202:205], v[70:73]
	v_mfma_f32_16x16x32_bf16 v[70:73], v[174:177], v[206:209], v[70:73]
	v_mfma_f32_16x16x32_bf16 v[74:77], v[162:165], v[202:205], v[74:77]
	v_mfma_f32_16x16x32_bf16 v[74:77], v[166:169], v[206:209], v[74:77]
	v_mfma_f32_16x16x32_bf16 v[66:69], v[154:157], v[202:205], v[66:69]
	v_mfma_f32_16x16x32_bf16 v[66:69], v[158:161], v[206:209], v[66:69]
	v_mfma_f32_16x16x32_bf16 v[78:81], v[146:149], v[202:205], v[78:81]
	v_mfma_f32_16x16x32_bf16 v[78:81], v[150:153], v[206:209], v[78:81]
	s_setprio 0
	s_barrier
	ds_read_b128 v[178:181], v140 offset:16384
	ds_read_b128 v[182:185], v140 offset:17408
	ds_read_b128 v[186:189], v140 offset:18432
	ds_read_b128 v[190:193], v140 offset:19456
	ds_read_b128 v[194:197], v140 offset:20480
	ds_read_b128 v[198:201], v140 offset:21504
	ds_read_b128 v[202:205], v140 offset:22528
	ds_read_b128 v[206:209], v140 offset:23552
	s_mov_b32 m0, s31
	s_mov_b32 s22, s18
	s_mov_b32 s23, s19
	buffer_load_dwordx4 v137, s[20:23], s80 offen lds
	s_mov_b32 m0, s48
	s_add_i32 s81, s80, 0x80000
	buffer_load_dwordx4 v137, s[20:23], s81 offen lds
	s_mov_b32 m0, s49
	s_add_i32 s81, s80, 0x100000
	buffer_load_dwordx4 v137, s[20:23], s81 offen lds
	s_mov_b32 m0, s50
	s_add_i32 s81, s80, 0x180000
	buffer_load_dwordx4 v137, s[20:23], s81 offen lds
	s_mov_b32 m0, s30
	s_add_i32 s81, s78, 0x80000
	buffer_load_dwordx4 v136, s[16:19], s78 offen lds
	s_mov_b32 m0, s51
	s_nop 0
	buffer_load_dwordx4 v136, s[16:19], s81 offen lds
	s_waitcnt vmcnt(8) lgkmcnt(0)
	s_setprio 1
	v_mfma_f32_16x16x32_bf16 v[62:65], v[146:149], v[178:181], v[62:65]
	s_barrier
	v_mfma_f32_16x16x32_bf16 v[62:65], v[150:153], v[182:185], v[62:65]
	v_mfma_f32_16x16x32_bf16 v[54:57], v[154:157], v[178:181], v[54:57]
	v_mfma_f32_16x16x32_bf16 v[54:57], v[158:161], v[182:185], v[54:57]
	v_mfma_f32_16x16x32_bf16 v[58:61], v[162:165], v[178:181], v[58:61]
	v_mfma_f32_16x16x32_bf16 v[58:61], v[166:169], v[182:185], v[58:61]
	v_mfma_f32_16x16x32_bf16 v[50:53], v[170:173], v[178:181], v[50:53]
	v_mfma_f32_16x16x32_bf16 v[50:53], v[174:177], v[182:185], v[50:53]
	v_mfma_f32_16x16x32_bf16 v[34:37], v[170:173], v[186:189], v[34:37]
	v_mfma_f32_16x16x32_bf16 v[34:37], v[174:177], v[190:193], v[34:37]
	v_mfma_f32_16x16x32_bf16 v[42:45], v[162:165], v[186:189], v[42:45]
	v_mfma_f32_16x16x32_bf16 v[42:45], v[166:169], v[190:193], v[42:45]
	v_mfma_f32_16x16x32_bf16 v[38:41], v[154:157], v[186:189], v[38:41]
	v_mfma_f32_16x16x32_bf16 v[38:41], v[158:161], v[190:193], v[38:41]
	v_mfma_f32_16x16x32_bf16 v[46:49], v[146:149], v[186:189], v[46:49]
	v_mfma_f32_16x16x32_bf16 v[46:49], v[150:153], v[190:193], v[46:49]
	v_mfma_f32_16x16x32_bf16 v[30:33], v[146:149], v[194:197], v[30:33]
	v_mfma_f32_16x16x32_bf16 v[30:33], v[150:153], v[198:201], v[30:33]
	v_mfma_f32_16x16x32_bf16 v[22:25], v[154:157], v[194:197], v[22:25]
	v_mfma_f32_16x16x32_bf16 v[22:25], v[158:161], v[198:201], v[22:25]
	v_mfma_f32_16x16x32_bf16 v[26:29], v[162:165], v[194:197], v[26:29]
	v_mfma_f32_16x16x32_bf16 v[26:29], v[166:169], v[198:201], v[26:29]
	v_mfma_f32_16x16x32_bf16 v[18:21], v[170:173], v[194:197], v[18:21]
	v_mfma_f32_16x16x32_bf16 v[18:21], v[174:177], v[198:201], v[18:21]
	v_mfma_f32_16x16x32_bf16 v[2:5], v[170:173], v[202:205], v[2:5]
	v_mfma_f32_16x16x32_bf16 v[2:5], v[174:177], v[206:209], v[2:5]
	v_mfma_f32_16x16x32_bf16 v[10:13], v[162:165], v[202:205], v[10:13]
	v_mfma_f32_16x16x32_bf16 v[10:13], v[166:169], v[206:209], v[10:13]
	v_mfma_f32_16x16x32_bf16 v[6:9], v[154:157], v[202:205], v[6:9]
	v_mfma_f32_16x16x32_bf16 v[6:9], v[158:161], v[206:209], v[6:9]
	v_mfma_f32_16x16x32_bf16 v[14:17], v[146:149], v[202:205], v[14:17]
	v_mfma_f32_16x16x32_bf16 v[14:17], v[150:153], v[206:209], v[14:17]
	s_setprio 0
	s_barrier
	ds_read_b128 v[146:149], v141
	ds_read_b128 v[150:153], v141 offset:1024
	ds_read_b128 v[154:157], v141 offset:2048
	ds_read_b128 v[158:161], v141 offset:3072
	ds_read_b128 v[162:165], v142
	ds_read_b128 v[166:169], v142 offset:1024
	ds_read_b128 v[170:173], v142 offset:2048
	ds_read_b128 v[174:177], v142 offset:3072
	s_mov_b32 m0, s52
	s_add_i32 s81, s78, 0x100000
	ds_read_b128 v[178:181], v140 offset:32768
	ds_read_b128 v[182:185], v140 offset:33792
	ds_read_b128 v[186:189], v140 offset:34816
	ds_read_b128 v[190:193], v140 offset:35840
	ds_read_b128 v[194:197], v140 offset:36864
	ds_read_b128 v[198:201], v140 offset:37888
	ds_read_b128 v[202:205], v140 offset:38912
	ds_read_b128 v[206:209], v140 offset:39936
	buffer_load_dwordx4 v136, s[16:19], s81 offen lds
	s_mov_b32 m0, s53
	s_add_i32 s81, s78, 0x180000
	buffer_load_dwordx4 v136, s[16:19], s81 offen lds
	s_waitcnt vmcnt(8) lgkmcnt(0)
	s_setprio 1
	v_mfma_f32_16x16x32_bf16 v[118:121], v[146:149], v[178:181], v[118:121]
	s_barrier
	v_mfma_f32_16x16x32_bf16 v[118:121], v[150:153], v[182:185], v[118:121]
	v_mfma_f32_16x16x32_bf16 v[114:117], v[154:157], v[178:181], v[114:117]
	v_mfma_f32_16x16x32_bf16 v[114:117], v[158:161], v[182:185], v[114:117]
	v_mfma_f32_16x16x32_bf16 v[126:129], v[162:165], v[178:181], v[126:129]
	v_mfma_f32_16x16x32_bf16 v[126:129], v[166:169], v[182:185], v[126:129]
	v_mfma_f32_16x16x32_bf16 v[122:125], v[170:173], v[178:181], v[122:125]
	v_mfma_f32_16x16x32_bf16 v[122:125], v[174:177], v[182:185], v[122:125]
	v_mfma_f32_16x16x32_bf16 v[98:101], v[170:173], v[186:189], v[98:101]
	v_mfma_f32_16x16x32_bf16 v[98:101], v[174:177], v[190:193], v[98:101]
	v_mfma_f32_16x16x32_bf16 v[106:109], v[162:165], v[186:189], v[106:109]
	v_mfma_f32_16x16x32_bf16 v[106:109], v[166:169], v[190:193], v[106:109]
	v_mfma_f32_16x16x32_bf16 v[102:105], v[154:157], v[186:189], v[102:105]
	v_mfma_f32_16x16x32_bf16 v[102:105], v[158:161], v[190:193], v[102:105]
	v_mfma_f32_16x16x32_bf16 v[110:113], v[146:149], v[186:189], v[110:113]
	v_mfma_f32_16x16x32_bf16 v[110:113], v[150:153], v[190:193], v[110:113]
	v_mfma_f32_16x16x32_bf16 v[94:97], v[146:149], v[194:197], v[94:97]
	v_mfma_f32_16x16x32_bf16 v[94:97], v[150:153], v[198:201], v[94:97]
	v_mfma_f32_16x16x32_bf16 v[86:89], v[154:157], v[194:197], v[86:89]
	v_mfma_f32_16x16x32_bf16 v[86:89], v[158:161], v[198:201], v[86:89]
	v_mfma_f32_16x16x32_bf16 v[90:93], v[162:165], v[194:197], v[90:93]
	v_mfma_f32_16x16x32_bf16 v[90:93], v[166:169], v[198:201], v[90:93]
	v_mfma_f32_16x16x32_bf16 v[82:85], v[170:173], v[194:197], v[82:85]
	v_mfma_f32_16x16x32_bf16 v[82:85], v[174:177], v[198:201], v[82:85]
	v_mfma_f32_16x16x32_bf16 v[70:73], v[170:173], v[202:205], v[70:73]
	v_mfma_f32_16x16x32_bf16 v[70:73], v[174:177], v[206:209], v[70:73]
	v_mfma_f32_16x16x32_bf16 v[74:77], v[162:165], v[202:205], v[74:77]
	v_mfma_f32_16x16x32_bf16 v[74:77], v[166:169], v[206:209], v[74:77]
	v_mfma_f32_16x16x32_bf16 v[66:69], v[154:157], v[202:205], v[66:69]
	v_mfma_f32_16x16x32_bf16 v[66:69], v[158:161], v[206:209], v[66:69]
	v_mfma_f32_16x16x32_bf16 v[78:81], v[146:149], v[202:205], v[78:81]
	v_mfma_f32_16x16x32_bf16 v[78:81], v[150:153], v[206:209], v[78:81]
	s_setprio 0
	s_barrier
	ds_read_b128 v[178:181], v140 offset:49152
	ds_read_b128 v[182:185], v140 offset:50176
	ds_read_b128 v[186:189], v140 offset:51200
	ds_read_b128 v[190:193], v140 offset:52224
	ds_read_b128 v[194:197], v140 offset:53248
	ds_read_b128 v[198:201], v140 offset:54272
	ds_read_b128 v[202:205], v140 offset:55296
	ds_read_b128 v[206:209], v140 offset:56320
	s_mov_b32 m0, s54
	s_or_b32 s81, s80, 0x80
	buffer_load_dwordx4 v137, s[20:23], s81 offen lds
	s_add_i32 s81, s80, 0x80080
	s_mov_b32 m0, s55
	s_add_i32 s78, s78, 0x80080
	buffer_load_dwordx4 v137, s[20:23], s81 offen lds
	s_add_i32 s81, s80, 0x100080
	s_mov_b32 m0, s58
	s_add_i32 s80, s80, 0x180080
	buffer_load_dwordx4 v137, s[20:23], s81 offen lds
	s_mov_b32 m0, s59
	s_nop 0
	buffer_load_dwordx4 v137, s[20:23], s80 offen lds
	s_mov_b32 m0, s56
	s_nop 0
	buffer_load_dwordx4 v136, s[16:19], s79 offen lds
	s_mov_b32 m0, s57
	s_nop 0
	buffer_load_dwordx4 v136, s[16:19], s78 offen lds
	s_waitcnt vmcnt(8) lgkmcnt(0)
	s_setprio 1
	v_mfma_f32_16x16x32_bf16 v[62:65], v[146:149], v[178:181], v[62:65]
	s_barrier
	v_mfma_f32_16x16x32_bf16 v[62:65], v[150:153], v[182:185], v[62:65]
	v_mfma_f32_16x16x32_bf16 v[54:57], v[154:157], v[178:181], v[54:57]
	v_mfma_f32_16x16x32_bf16 v[54:57], v[158:161], v[182:185], v[54:57]
	v_mfma_f32_16x16x32_bf16 v[58:61], v[162:165], v[178:181], v[58:61]
	v_mfma_f32_16x16x32_bf16 v[58:61], v[166:169], v[182:185], v[58:61]
	v_mfma_f32_16x16x32_bf16 v[50:53], v[170:173], v[178:181], v[50:53]
	v_mfma_f32_16x16x32_bf16 v[50:53], v[174:177], v[182:185], v[50:53]
	v_mfma_f32_16x16x32_bf16 v[34:37], v[170:173], v[186:189], v[34:37]
	v_mfma_f32_16x16x32_bf16 v[34:37], v[174:177], v[190:193], v[34:37]
	v_mfma_f32_16x16x32_bf16 v[42:45], v[162:165], v[186:189], v[42:45]
	v_mfma_f32_16x16x32_bf16 v[42:45], v[166:169], v[190:193], v[42:45]
	v_mfma_f32_16x16x32_bf16 v[38:41], v[154:157], v[186:189], v[38:41]
	v_mfma_f32_16x16x32_bf16 v[38:41], v[158:161], v[190:193], v[38:41]
	v_mfma_f32_16x16x32_bf16 v[46:49], v[146:149], v[186:189], v[46:49]
	v_mfma_f32_16x16x32_bf16 v[46:49], v[150:153], v[190:193], v[46:49]
	v_mfma_f32_16x16x32_bf16 v[30:33], v[146:149], v[194:197], v[30:33]
	v_mfma_f32_16x16x32_bf16 v[30:33], v[150:153], v[198:201], v[30:33]
	v_mfma_f32_16x16x32_bf16 v[22:25], v[154:157], v[194:197], v[22:25]
	v_mfma_f32_16x16x32_bf16 v[22:25], v[158:161], v[198:201], v[22:25]
	v_mfma_f32_16x16x32_bf16 v[26:29], v[162:165], v[194:197], v[26:29]
	v_mfma_f32_16x16x32_bf16 v[26:29], v[166:169], v[198:201], v[26:29]
	v_mfma_f32_16x16x32_bf16 v[18:21], v[170:173], v[194:197], v[18:21]
	v_mfma_f32_16x16x32_bf16 v[18:21], v[174:177], v[198:201], v[18:21]
	v_mfma_f32_16x16x32_bf16 v[2:5], v[170:173], v[202:205], v[2:5]
	v_mfma_f32_16x16x32_bf16 v[2:5], v[174:177], v[206:209], v[2:5]
	v_mfma_f32_16x16x32_bf16 v[10:13], v[162:165], v[202:205], v[10:13]
	v_mfma_f32_16x16x32_bf16 v[10:13], v[166:169], v[206:209], v[10:13]
	v_mfma_f32_16x16x32_bf16 v[6:9], v[154:157], v[202:205], v[6:9]
	v_mfma_f32_16x16x32_bf16 v[6:9], v[158:161], v[206:209], v[6:9]
	v_mfma_f32_16x16x32_bf16 v[14:17], v[146:149], v[202:205], v[14:17]
	v_mfma_f32_16x16x32_bf16 v[14:17], v[150:153], v[206:209], v[14:17]
	s_setprio 0
	s_barrier
	s_add_i32 s77, s77, 2
	s_addk_i32 s75, 0x100
	s_addk_i32 s76, 0x100
	s_cmp_ge_i32 s77, s13
	s_cbranch_scc0 .LBB0_1402
	s_and_b64 vcc, exec, s[46:47]
	s_cbranch_vccz .LBB0_1405

.LBB0_1519:
	ds_read_b128 v[134:137], v208
	ds_read_b128 v[138:141], v208 offset:1024
	ds_read_b128 v[142:145], v208 offset:2048
	ds_read_b128 v[146:149], v208 offset:3072
	ds_read_b128 v[150:153], v209
	ds_read_b128 v[154:157], v209 offset:1024
	ds_read_b128 v[158:161], v209 offset:2048
	ds_read_b128 v[162:165], v209 offset:3072
	s_add_i32 s18, s80, 0xffbf8080
	s_cmp_eq_u32 s65, s82
	s_cselect_b32 s83, s6, s18
	s_cselect_b32 s85, s7, s81
	s_or_b32 s84, s83, 0x80
	s_add_i32 s18, s80, 0xffea8000
	s_mov_b32 m0, s66
	ds_read_b128 v[166:169], v210
	ds_read_b128 v[170:173], v210 offset:1024
	ds_read_b128 v[174:177], v210 offset:2048
	ds_read_b128 v[178:181], v210 offset:3072
	ds_read_b128 v[182:185], v210 offset:4096
	ds_read_b128 v[186:189], v210 offset:5120
	ds_read_b128 v[190:193], v210 offset:6144
	ds_read_b128 v[194:197], v210 offset:7168
	buffer_load_dwordx4 v206, s[12:15], s18 offen lds
	s_mov_b32 m0, s69
	s_nop 0
	buffer_load_dwordx4 v206, s[12:15], s80 offen lds
	s_waitcnt vmcnt(8) lgkmcnt(0)
	s_setprio 1
	v_mfma_f32_16x16x32_bf16 v[126:129], v[134:137], v[166:169], v[126:129]
	s_barrier
	v_mfma_f32_16x16x32_bf16 v[126:129], v[138:141], v[170:173], v[126:129]
	v_mfma_f32_16x16x32_bf16 v[122:125], v[142:145], v[166:169], v[122:125]
	v_mfma_f32_16x16x32_bf16 v[122:125], v[146:149], v[170:173], v[122:125]
	v_mfma_f32_16x16x32_bf16 v[110:113], v[150:153], v[166:169], v[110:113]
	v_mfma_f32_16x16x32_bf16 v[110:113], v[154:157], v[170:173], v[110:113]
	v_mfma_f32_16x16x32_bf16 v[102:105], v[158:161], v[166:169], v[102:105]
	v_mfma_f32_16x16x32_bf16 v[102:105], v[162:165], v[170:173], v[102:105]
	v_mfma_f32_16x16x32_bf16 v[86:89], v[158:161], v[174:177], v[86:89]
	v_mfma_f32_16x16x32_bf16 v[86:89], v[162:165], v[178:181], v[86:89]
	v_mfma_f32_16x16x32_bf16 v[94:97], v[150:153], v[174:177], v[94:97]
	v_mfma_f32_16x16x32_bf16 v[94:97], v[154:157], v[178:181], v[94:97]
	v_mfma_f32_16x16x32_bf16 v[114:117], v[142:145], v[174:177], v[114:117]
	v_mfma_f32_16x16x32_bf16 v[114:117], v[146:149], v[178:181], v[114:117]
	v_mfma_f32_16x16x32_bf16 v[118:121], v[134:137], v[174:177], v[118:121]
	v_mfma_f32_16x16x32_bf16 v[118:121], v[138:141], v[178:181], v[118:121]
	v_mfma_f32_16x16x32_bf16 v[106:109], v[134:137], v[182:185], v[106:109]
	v_mfma_f32_16x16x32_bf16 v[106:109], v[138:141], v[186:189], v[106:109]
	v_mfma_f32_16x16x32_bf16 v[98:101], v[142:145], v[182:185], v[98:101]
	v_mfma_f32_16x16x32_bf16 v[98:101], v[146:149], v[186:189], v[98:101]
	v_mfma_f32_16x16x32_bf16 v[78:81], v[150:153], v[182:185], v[78:81]
	v_mfma_f32_16x16x32_bf16 v[78:81], v[154:157], v[186:189], v[78:81]
	v_mfma_f32_16x16x32_bf16 v[74:77], v[158:161], v[182:185], v[74:77]
	v_mfma_f32_16x16x32_bf16 v[74:77], v[162:165], v[186:189], v[74:77]
	v_mfma_f32_16x16x32_bf16 v[66:69], v[158:161], v[190:193], v[66:69]
	v_mfma_f32_16x16x32_bf16 v[66:69], v[162:165], v[194:197], v[66:69]
	v_mfma_f32_16x16x32_bf16 v[70:73], v[150:153], v[190:193], v[70:73]
	v_mfma_f32_16x16x32_bf16 v[70:73], v[154:157], v[194:197], v[70:73]
	v_mfma_f32_16x16x32_bf16 v[82:85], v[142:145], v[190:193], v[82:85]
	v_mfma_f32_16x16x32_bf16 v[82:85], v[146:149], v[194:197], v[82:85]
	v_mfma_f32_16x16x32_bf16 v[90:93], v[134:137], v[190:193], v[90:93]
	v_mfma_f32_16x16x32_bf16 v[90:93], v[138:141], v[194:197], v[90:93]
	s_setprio 0
	s_barrier
	ds_read_b128 v[166:169], v210 offset:16384
	ds_read_b128 v[170:173], v210 offset:17408
	ds_read_b128 v[174:177], v210 offset:18432
	ds_read_b128 v[178:181], v210 offset:19456
	ds_read_b128 v[182:185], v210 offset:20480
	ds_read_b128 v[186:189], v210 offset:21504
	ds_read_b128 v[190:193], v210 offset:22528
	ds_read_b128 v[194:197], v210 offset:23552
	s_mov_b32 m0, s27
	s_mov_b32 s18, s14
	s_mov_b32 s19, s15
	buffer_load_dwordx4 v207, s[16:19], s85 offen lds
	s_mov_b32 m0, s30
	s_add_i32 s86, s85, 0x158000
	buffer_load_dwordx4 v207, s[16:19], s86 offen lds
	s_mov_b32 m0, s31
	s_add_i32 s86, s85, 0x2b0000
	buffer_load_dwordx4 v207, s[16:19], s86 offen lds
	s_mov_b32 m0, s50
	s_add_i32 s86, s85, 0x408000
	buffer_load_dwordx4 v207, s[16:19], s86 offen lds
	s_mov_b32 m0, s25
	s_add_i32 s86, s83, 0x158000
	buffer_load_dwordx4 v206, s[12:15], s83 offen lds
	s_mov_b32 m0, s51
	s_nop 0
	buffer_load_dwordx4 v206, s[12:15], s86 offen lds
	s_waitcnt vmcnt(8) lgkmcnt(0)
	s_setprio 1
	v_mfma_f32_16x16x32_bf16 v[62:65], v[134:137], v[166:169], v[62:65]
	s_barrier
	v_mfma_f32_16x16x32_bf16 v[62:65], v[138:141], v[170:173], v[62:65]
	v_mfma_f32_16x16x32_bf16 v[58:61], v[142:145], v[166:169], v[58:61]
	v_mfma_f32_16x16x32_bf16 v[58:61], v[146:149], v[170:173], v[58:61]
	v_mfma_f32_16x16x32_bf16 v[46:49], v[150:153], v[166:169], v[46:49]
	v_mfma_f32_16x16x32_bf16 v[46:49], v[154:157], v[170:173], v[46:49]
	v_mfma_f32_16x16x32_bf16 v[38:41], v[158:161], v[166:169], v[38:41]
	v_mfma_f32_16x16x32_bf16 v[38:41], v[162:165], v[170:173], v[38:41]
	v_mfma_f32_16x16x32_bf16 v[22:25], v[158:161], v[174:177], v[22:25]
	v_mfma_f32_16x16x32_bf16 v[22:25], v[162:165], v[178:181], v[22:25]
	v_mfma_f32_16x16x32_bf16 v[30:33], v[150:153], v[174:177], v[30:33]
	v_mfma_f32_16x16x32_bf16 v[30:33], v[154:157], v[178:181], v[30:33]
	v_mfma_f32_16x16x32_bf16 v[50:53], v[142:145], v[174:177], v[50:53]
	v_mfma_f32_16x16x32_bf16 v[50:53], v[146:149], v[178:181], v[50:53]
	v_mfma_f32_16x16x32_bf16 v[54:57], v[134:137], v[174:177], v[54:57]
	v_mfma_f32_16x16x32_bf16 v[54:57], v[138:141], v[178:181], v[54:57]
	v_mfma_f32_16x16x32_bf16 v[42:45], v[134:137], v[182:185], v[42:45]
	v_mfma_f32_16x16x32_bf16 v[42:45], v[138:141], v[186:189], v[42:45]
	v_mfma_f32_16x16x32_bf16 v[34:37], v[142:145], v[182:185], v[34:37]
	v_mfma_f32_16x16x32_bf16 v[34:37], v[146:149], v[186:189], v[34:37]
	v_mfma_f32_16x16x32_bf16 v[14:17], v[150:153], v[182:185], v[14:17]
	v_mfma_f32_16x16x32_bf16 v[14:17], v[154:157], v[186:189], v[14:17]
	v_mfma_f32_16x16x32_bf16 v[10:13], v[158:161], v[182:185], v[10:13]
	v_mfma_f32_16x16x32_bf16 v[10:13], v[162:165], v[186:189], v[10:13]
	v_mfma_f32_16x16x32_bf16 v[2:5], v[158:161], v[190:193], v[2:5]
	v_mfma_f32_16x16x32_bf16 v[2:5], v[162:165], v[194:197], v[2:5]
	v_mfma_f32_16x16x32_bf16 v[6:9], v[150:153], v[190:193], v[6:9]
	v_mfma_f32_16x16x32_bf16 v[6:9], v[154:157], v[194:197], v[6:9]
	v_mfma_f32_16x16x32_bf16 v[18:21], v[142:145], v[190:193], v[18:21]
	v_mfma_f32_16x16x32_bf16 v[18:21], v[146:149], v[194:197], v[18:21]
	v_mfma_f32_16x16x32_bf16 v[26:29], v[134:137], v[190:193], v[26:29]
	v_mfma_f32_16x16x32_bf16 v[26:29], v[138:141], v[194:197], v[26:29]
	s_setprio 0
	s_barrier
	ds_read_b128 v[134:137], v211
	ds_read_b128 v[138:141], v211 offset:1024
	ds_read_b128 v[142:145], v211 offset:2048
	ds_read_b128 v[146:149], v211 offset:3072
	ds_read_b128 v[150:153], v212
	ds_read_b128 v[154:157], v212 offset:1024
	ds_read_b128 v[158:161], v212 offset:2048
	ds_read_b128 v[162:165], v212 offset:3072
	s_mov_b32 m0, s52
	s_add_i32 s86, s83, 0x2b0000
	ds_read_b128 v[166:169], v210 offset:32768
	ds_read_b128 v[170:173], v210 offset:33792
	ds_read_b128 v[174:177], v210 offset:34816
	ds_read_b128 v[178:181], v210 offset:35840
	ds_read_b128 v[182:185], v210 offset:36864
	ds_read_b128 v[186:189], v210 offset:37888
	ds_read_b128 v[190:193], v210 offset:38912
	ds_read_b128 v[194:197], v210 offset:39936
	buffer_load_dwordx4 v206, s[12:15], s86 offen lds
	s_mov_b32 m0, s53
	s_add_i32 s86, s83, 0x408000
	buffer_load_dwordx4 v206, s[12:15], s86 offen lds
	s_waitcnt vmcnt(8) lgkmcnt(0)
	s_setprio 1
	v_mfma_f32_16x16x32_bf16 v[126:129], v[134:137], v[166:169], v[126:129]
	s_barrier
	v_mfma_f32_16x16x32_bf16 v[126:129], v[138:141], v[170:173], v[126:129]
	v_mfma_f32_16x16x32_bf16 v[122:125], v[142:145], v[166:169], v[122:125]
	v_mfma_f32_16x16x32_bf16 v[122:125], v[146:149], v[170:173], v[122:125]
	v_mfma_f32_16x16x32_bf16 v[110:113], v[150:153], v[166:169], v[110:113]
	v_mfma_f32_16x16x32_bf16 v[110:113], v[154:157], v[170:173], v[110:113]
	v_mfma_f32_16x16x32_bf16 v[102:105], v[158:161], v[166:169], v[102:105]
	v_mfma_f32_16x16x32_bf16 v[102:105], v[162:165], v[170:173], v[102:105]
	v_mfma_f32_16x16x32_bf16 v[86:89], v[158:161], v[174:177], v[86:89]
	v_mfma_f32_16x16x32_bf16 v[86:89], v[162:165], v[178:181], v[86:89]
	v_mfma_f32_16x16x32_bf16 v[94:97], v[150:153], v[174:177], v[94:97]
	v_mfma_f32_16x16x32_bf16 v[94:97], v[154:157], v[178:181], v[94:97]
	v_mfma_f32_16x16x32_bf16 v[114:117], v[142:145], v[174:177], v[114:117]
	v_mfma_f32_16x16x32_bf16 v[114:117], v[146:149], v[178:181], v[114:117]
	v_mfma_f32_16x16x32_bf16 v[118:121], v[134:137], v[174:177], v[118:121]
	v_mfma_f32_16x16x32_bf16 v[118:121], v[138:141], v[178:181], v[118:121]
	v_mfma_f32_16x16x32_bf16 v[106:109], v[134:137], v[182:185], v[106:109]
	v_mfma_f32_16x16x32_bf16 v[106:109], v[138:141], v[186:189], v[106:109]
	v_mfma_f32_16x16x32_bf16 v[98:101], v[142:145], v[182:185], v[98:101]
	v_mfma_f32_16x16x32_bf16 v[98:101], v[146:149], v[186:189], v[98:101]
	v_mfma_f32_16x16x32_bf16 v[78:81], v[150:153], v[182:185], v[78:81]
	v_mfma_f32_16x16x32_bf16 v[78:81], v[154:157], v[186:189], v[78:81]
	v_mfma_f32_16x16x32_bf16 v[74:77], v[158:161], v[182:185], v[74:77]
	v_mfma_f32_16x16x32_bf16 v[74:77], v[162:165], v[186:189], v[74:77]
	v_mfma_f32_16x16x32_bf16 v[66:69], v[158:161], v[190:193], v[66:69]
	v_mfma_f32_16x16x32_bf16 v[66:69], v[162:165], v[194:197], v[66:69]
	v_mfma_f32_16x16x32_bf16 v[70:73], v[150:153], v[190:193], v[70:73]
	v_mfma_f32_16x16x32_bf16 v[70:73], v[154:157], v[194:197], v[70:73]
	v_mfma_f32_16x16x32_bf16 v[82:85], v[142:145], v[190:193], v[82:85]
	v_mfma_f32_16x16x32_bf16 v[82:85], v[146:149], v[194:197], v[82:85]
	v_mfma_f32_16x16x32_bf16 v[90:93], v[134:137], v[190:193], v[90:93]
	v_mfma_f32_16x16x32_bf16 v[90:93], v[138:141], v[194:197], v[90:93]
	s_setprio 0
	s_barrier
	ds_read_b128 v[166:169], v210 offset:49152
	ds_read_b128 v[170:173], v210 offset:50176
	ds_read_b128 v[174:177], v210 offset:51200
	ds_read_b128 v[178:181], v210 offset:52224
	ds_read_b128 v[182:185], v210 offset:53248
	ds_read_b128 v[186:189], v210 offset:54272
	ds_read_b128 v[190:193], v210 offset:55296
	ds_read_b128 v[194:197], v210 offset:56320
	s_mov_b32 m0, s57
	s_or_b32 s86, s85, 0x80
	buffer_load_dwordx4 v207, s[16:19], s86 offen lds
	s_add_i32 s86, s85, 0x158080
	s_mov_b32 m0, s58
	s_add_i32 s83, s83, 0x158080
	buffer_load_dwordx4 v207, s[16:19], s86 offen lds
	s_add_i32 s86, s85, 0x2b0080
	s_mov_b32 m0, s61
	s_add_i32 s85, s85, 0x408080
	buffer_load_dwordx4 v207, s[16:19], s86 offen lds
	s_mov_b32 m0, s62
	s_nop 0
	buffer_load_dwordx4 v207, s[16:19], s85 offen lds
	s_mov_b32 m0, s59
	s_nop 0
	buffer_load_dwordx4 v206, s[12:15], s84 offen lds
	s_mov_b32 m0, s60
	s_nop 0
	buffer_load_dwordx4 v206, s[12:15], s83 offen lds
	s_waitcnt vmcnt(8) lgkmcnt(0)
	s_setprio 1
	v_mfma_f32_16x16x32_bf16 v[62:65], v[134:137], v[166:169], v[62:65]
	s_barrier
	v_mfma_f32_16x16x32_bf16 v[62:65], v[138:141], v[170:173], v[62:65]
	v_mfma_f32_16x16x32_bf16 v[58:61], v[142:145], v[166:169], v[58:61]
	v_mfma_f32_16x16x32_bf16 v[58:61], v[146:149], v[170:173], v[58:61]
	v_mfma_f32_16x16x32_bf16 v[46:49], v[150:153], v[166:169], v[46:49]
	v_mfma_f32_16x16x32_bf16 v[46:49], v[154:157], v[170:173], v[46:49]
	v_mfma_f32_16x16x32_bf16 v[38:41], v[158:161], v[166:169], v[38:41]
	v_mfma_f32_16x16x32_bf16 v[38:41], v[162:165], v[170:173], v[38:41]
	v_mfma_f32_16x16x32_bf16 v[22:25], v[158:161], v[174:177], v[22:25]
	v_mfma_f32_16x16x32_bf16 v[22:25], v[162:165], v[178:181], v[22:25]
	v_mfma_f32_16x16x32_bf16 v[30:33], v[150:153], v[174:177], v[30:33]
	v_mfma_f32_16x16x32_bf16 v[30:33], v[154:157], v[178:181], v[30:33]
	v_mfma_f32_16x16x32_bf16 v[50:53], v[142:145], v[174:177], v[50:53]
	v_mfma_f32_16x16x32_bf16 v[50:53], v[146:149], v[178:181], v[50:53]
	v_mfma_f32_16x16x32_bf16 v[54:57], v[134:137], v[174:177], v[54:57]
	v_mfma_f32_16x16x32_bf16 v[54:57], v[138:141], v[178:181], v[54:57]
	v_mfma_f32_16x16x32_bf16 v[42:45], v[134:137], v[182:185], v[42:45]
	v_mfma_f32_16x16x32_bf16 v[42:45], v[138:141], v[186:189], v[42:45]
	v_mfma_f32_16x16x32_bf16 v[34:37], v[142:145], v[182:185], v[34:37]
	v_mfma_f32_16x16x32_bf16 v[34:37], v[146:149], v[186:189], v[34:37]
	v_mfma_f32_16x16x32_bf16 v[14:17], v[150:153], v[182:185], v[14:17]
	v_mfma_f32_16x16x32_bf16 v[14:17], v[154:157], v[186:189], v[14:17]
	v_mfma_f32_16x16x32_bf16 v[10:13], v[158:161], v[182:185], v[10:13]
	v_mfma_f32_16x16x32_bf16 v[10:13], v[162:165], v[186:189], v[10:13]
	v_mfma_f32_16x16x32_bf16 v[2:5], v[158:161], v[190:193], v[2:5]
	v_mfma_f32_16x16x32_bf16 v[2:5], v[162:165], v[194:197], v[2:5]
	v_mfma_f32_16x16x32_bf16 v[6:9], v[150:153], v[190:193], v[6:9]
	v_mfma_f32_16x16x32_bf16 v[6:9], v[154:157], v[194:197], v[6:9]
	v_mfma_f32_16x16x32_bf16 v[18:21], v[142:145], v[190:193], v[18:21]
	v_mfma_f32_16x16x32_bf16 v[18:21], v[146:149], v[194:197], v[18:21]
	v_mfma_f32_16x16x32_bf16 v[26:29], v[134:137], v[190:193], v[26:29]
	v_mfma_f32_16x16x32_bf16 v[26:29], v[138:141], v[194:197], v[26:29]
	s_setprio 0
	s_barrier
	s_add_i32 s82, s82, 2
	s_addk_i32 s80, 0x100
	s_addk_i32 s81, 0x100
	s_cmp_ge_i32 s82, s3
	s_cbranch_scc0 .LBB0_1519
	v_pk_mul_f32 v[182:183], v[128:129], 0.5 op_sel_hi:[1,0]
	v_pk_mul_f32 v[184:185], v[126:127], 0.5 op_sel_hi:[1,0]
	v_pk_mul_f32 v[186:187], v[124:125], 0.5 op_sel_hi:[1,0]
	v_pk_mul_f32 v[188:189], v[122:123], 0.5 op_sel_hi:[1,0]
	v_pk_mul_f32 v[196:197], v[112:113], 0.5 op_sel_hi:[1,0]
	v_pk_mul_f32 v[194:195], v[110:111], 0.5 op_sel_hi:[1,0]
	v_pk_mul_f32 v[192:193], v[104:105], 0.5 op_sel_hi:[1,0]
	v_pk_mul_f32 v[190:191], v[102:103], 0.5 op_sel_hi:[1,0]
	v_pk_mul_f32 v[180:181], v[120:121], 0.5 op_sel_hi:[1,0]
	v_pk_mul_f32 v[178:179], v[118:119], 0.5 op_sel_hi:[1,0]
	v_pk_mul_f32 v[176:177], v[116:117], 0.5 op_sel_hi:[1,0]
	v_pk_mul_f32 v[174:175], v[114:115], 0.5 op_sel_hi:[1,0]
	v_pk_mul_f32 v[170:171], v[96:97], 0.5 op_sel_hi:[1,0]
	v_pk_mul_f32 v[168:169], v[94:95], 0.5 op_sel_hi:[1,0]
	v_pk_mul_f32 v[166:167], v[88:89], 0.5 op_sel_hi:[1,0]
	v_pk_mul_f32 v[164:165], v[86:87], 0.5 op_sel_hi:[1,0]
	v_pk_mul_f32 v[162:163], v[108:109], 0.5 op_sel_hi:[1,0]
	v_pk_mul_f32 v[160:161], v[106:107], 0.5 op_sel_hi:[1,0]
	v_pk_mul_f32 v[158:159], v[100:101], 0.5 op_sel_hi:[1,0]
	v_pk_mul_f32 v[156:157], v[98:99], 0.5 op_sel_hi:[1,0]
	v_pk_mul_f32 v[154:155], v[80:81], 0.5 op_sel_hi:[1,0]
	v_pk_mul_f32 v[152:153], v[78:79], 0.5 op_sel_hi:[1,0]
	v_pk_mul_f32 v[150:151], v[76:77], 0.5 op_sel_hi:[1,0]
	v_pk_mul_f32 v[148:149], v[74:75], 0.5 op_sel_hi:[1,0]
	v_pk_mul_f32 v[144:145], v[92:93], 0.5 op_sel_hi:[1,0]
	v_pk_mul_f32 v[142:143], v[90:91], 0.5 op_sel_hi:[1,0]
	v_pk_mul_f32 v[140:141], v[84:85], 0.5 op_sel_hi:[1,0]
	v_pk_mul_f32 v[138:139], v[82:83], 0.5 op_sel_hi:[1,0]
	v_pk_mul_f32 v[136:137], v[72:73], 0.5 op_sel_hi:[1,0]
	v_pk_mul_f32 v[134:135], v[70:71], 0.5 op_sel_hi:[1,0]
	v_pk_mul_f32 v[128:129], v[68:69], 0.5 op_sel_hi:[1,0]
	v_pk_mul_f32 v[126:127], v[66:67], 0.5 op_sel_hi:[1,0]
	v_pk_mul_f32 v[122:123], v[64:65], 0.5 op_sel_hi:[1,0]
	v_pk_mul_f32 v[120:121], v[62:63], 0.5 op_sel_hi:[1,0]
	v_pk_mul_f32 v[118:119], v[60:61], 0.5 op_sel_hi:[1,0]
	v_pk_mul_f32 v[116:117], v[58:59], 0.5 op_sel_hi:[1,0]
	v_pk_mul_f32 v[112:113], v[48:49], 0.5 op_sel_hi:[1,0]
	v_pk_mul_f32 v[110:111], v[46:47], 0.5 op_sel_hi:[1,0]
	v_pk_mul_f32 v[108:109], v[40:41], 0.5 op_sel_hi:[1,0]
	v_pk_mul_f32 v[106:107], v[38:39], 0.5 op_sel_hi:[1,0]
	v_pk_mul_f32 v[104:105], v[56:57], 0.5 op_sel_hi:[1,0]
	v_pk_mul_f32 v[102:103], v[54:55], 0.5 op_sel_hi:[1,0]
	v_pk_mul_f32 v[100:101], v[52:53], 0.5 op_sel_hi:[1,0]
	v_pk_mul_f32 v[98:99], v[50:51], 0.5 op_sel_hi:[1,0]
	v_pk_mul_f32 v[96:97], v[32:33], 0.5 op_sel_hi:[1,0]
	v_pk_mul_f32 v[94:95], v[30:31], 0.5 op_sel_hi:[1,0]
	v_pk_mul_f32 v[92:93], v[24:25], 0.5 op_sel_hi:[1,0]
	v_pk_mul_f32 v[90:91], v[22:23], 0.5 op_sel_hi:[1,0]
	v_pk_mul_f32 v[88:89], v[44:45], 0.5 op_sel_hi:[1,0]
	v_pk_mul_f32 v[86:87], v[42:43], 0.5 op_sel_hi:[1,0]
	v_pk_mul_f32 v[84:85], v[36:37], 0.5 op_sel_hi:[1,0]
	v_pk_mul_f32 v[82:83], v[34:35], 0.5 op_sel_hi:[1,0]
	v_pk_mul_f32 v[80:81], v[16:17], 0.5 op_sel_hi:[1,0]
	v_pk_mul_f32 v[78:79], v[14:15], 0.5 op_sel_hi:[1,0]
	v_pk_mul_f32 v[76:77], v[12:13], 0.5 op_sel_hi:[1,0]
	v_pk_mul_f32 v[74:75], v[10:11], 0.5 op_sel_hi:[1,0]
	v_pk_mul_f32 v[72:73], v[28:29], 0.5 op_sel_hi:[1,0]
	v_pk_mul_f32 v[70:71], v[26:27], 0.5 op_sel_hi:[1,0]
	v_pk_mul_f32 v[68:69], v[20:21], 0.5 op_sel_hi:[1,0]
	v_pk_mul_f32 v[66:67], v[18:19], 0.5 op_sel_hi:[1,0]
	v_pk_mul_f32 v[64:65], v[8:9], 0.5 op_sel_hi:[1,0]
	v_pk_mul_f32 v[62:63], v[6:7], 0.5 op_sel_hi:[1,0]
	v_pk_mul_f32 v[60:61], v[4:5], 0.5 op_sel_hi:[1,0]
	v_pk_mul_f32 v[58:59], v[2:3], 0.5 op_sel_hi:[1,0]
	s_and_b64 vcc, exec, s[40:41]
	s_cbranch_vccz .LBB0_1522
